# speedup vs baseline: 1.0819x; 1.0619x over previous
; #define LDA8(dst, b, h)                                                                                               \
;   _Pragma("unroll") for (int m = 0; m < 4; ++m) _Pragma("unroll") for (int k = 0; k < 2; ++k)                         \
;     dst[m][k] = *(const bf16x8*)(SA8(b, h) + la + m * 2048 + k * 1024)
; #define LDB8(dst, b, h)                                                                                               \
;   _Pragma("unroll") for (int n = 0; n < 2; ++n) _Pragma("unroll") for (int k = 0; k < 2; ++k)                         \
;     dst[n][k] = *(const bf16x8*)(SB8(b, h) + lb + n * 2048 + k * 1024)
; #define WAITL8(n) asm volatile("s_waitcnt lgkmcnt(" #n ")" ::: "memory")
; #define BAR8 __builtin_amdgcn_s_barrier()
; #define SCHED8 __builtin_amdgcn_sched_barrier(0)
; template <class Epi>
; DEV void gemm_tile8(char* shm, const u16* __restrict__ A, const u16* __restrict__ Bt, int K, int brow, int bcol, Epi& epi) {
;     ...
; #pragma unroll 1
;   for (int t = 0; t < nt - 2; t += 2) {
;     LDB8(B0, 0, 0); SCHED8; LDA8(At, 0, 0); STAGE8(SA8(1, 1), A, brow + HALF, t + 1);
;     WAITL8(8); BAR8; WAITL8(0); MMA8(0, 0, At, B0); BAR8; SCHED8;
;     LDB8(B1, 0, 1); STAGE8(SB8(0, 0), Bt, bcol, t + 2);
;     BAR8; WAITL8(0); MMA8(0, 1, At, B1); BAR8;
;     LDA8(At, 0, 1); STAGE8(SA8(0, 0), A, brow, t + 2);
;     BAR8; WAITL8(0); MMA8(1, 0, At, B0); BAR8; SCHED8;
.LBB0_389:
	v_or_b32_e32 v134, 0x10000, v133
	v_add_u32_e32 v136, 0x10800, v133
	v_add_u32_e32 v135, 0x10400, v133
	ds_read_b128 v[144:147], v134
	ds_read_b128 v[148:151], v135
	v_add_u32_e32 v137, 0x10c00, v133
	ds_read_b128 v[152:155], v136
	ds_read_b128 v[156:159], v137
	v_lshl_add_u64 v[228:229], s[10:11], 0, v[130:131]
	s_add_i32 s95, s7, 0xc000
	v_lshl_add_u64 v[138:139], v[228:229], 0, vcc
	s_mov_b32 m0, s95
	s_add_i32 s27, s7, 0xe000
	ds_read_b128 v[160:163], v132
	ds_read_b128 v[164:167], v132 offset:1024
	ds_read_b128 v[168:171], v132 offset:2048
	ds_read_b128 v[172:175], v132 offset:3072
	ds_read_b128 v[176:179], v132 offset:4096
	ds_read_b128 v[180:183], v132 offset:5120
	ds_read_b128 v[184:187], v132 offset:6144
	ds_read_b128 v[188:191], v132 offset:7168
	global_load_lds_dwordx4 v[138:139], off
	v_lshl_add_u64 v[138:139], v[228:229], 0, s[14:15]
	s_mov_b32 m0, s27
	s_nop 0
	global_load_lds_dwordx4 v[138:139], off
	s_waitcnt lgkmcnt(8)
	s_barrier
	s_waitcnt lgkmcnt(0)
	s_setprio 1
	s_waitcnt lgkmcnt(0)
	v_mfma_f32_16x16x32_bf16 v[124:127], v[144:147], v[160:163], v[124:127]
	v_mfma_f32_16x16x32_bf16 v[120:123], v[152:155], v[160:163], v[120:123]
	v_mfma_f32_16x16x32_bf16 v[116:119], v[144:147], v[168:171], v[116:119]
	v_mfma_f32_16x16x32_bf16 v[112:115], v[152:155], v[168:171], v[112:115]
	v_mfma_f32_16x16x32_bf16 v[108:111], v[144:147], v[176:179], v[108:111]
	v_mfma_f32_16x16x32_bf16 v[104:107], v[152:155], v[176:179], v[104:107]
	v_mfma_f32_16x16x32_bf16 v[100:103], v[144:147], v[184:187], v[100:103]
	v_mfma_f32_16x16x32_bf16 v[96:99], v[152:155], v[184:187], v[96:99]
	v_mfma_f32_16x16x32_bf16 v[124:127], v[148:151], v[164:167], v[124:127]
	v_mfma_f32_16x16x32_bf16 v[120:123], v[156:159], v[164:167], v[120:123]
	v_mfma_f32_16x16x32_bf16 v[116:119], v[148:151], v[172:175], v[116:119]
	v_mfma_f32_16x16x32_bf16 v[112:115], v[156:159], v[172:175], v[112:115]
	v_mfma_f32_16x16x32_bf16 v[108:111], v[148:151], v[180:183], v[108:111]
	v_mfma_f32_16x16x32_bf16 v[104:107], v[156:159], v[180:183], v[104:107]
	v_mfma_f32_16x16x32_bf16 v[100:103], v[148:151], v[188:191], v[100:103]
	v_mfma_f32_16x16x32_bf16 v[96:99], v[156:159], v[188:191], v[96:99]
	s_setprio 0
	s_barrier
	v_lshl_add_u64 v[230:231], s[24:25], 0, v[130:131]
	s_mov_b64 s[96:97], 0x1f80100
	s_mov_b32 m0, s55
	v_or_b32_e32 v138, 0x14000, v133
	v_add_u32_e32 v140, 0x14800, v133
	v_lshl_add_u64 v[220:221], v[230:231], 0, s[96:97]
	s_mov_b64 s[96:97], 0x1fa0100
	v_add_u32_e32 v139, 0x14400, v133
	ds_read_b128 v[204:207], v138
	ds_read_b128 v[208:211], v139
	v_add_u32_e32 v142, 0x14c00, v133
	ds_read_b128 v[212:215], v140
	ds_read_b128 v[216:219], v142
	global_load_lds_dwordx4 v[220:221], off
	v_lshl_add_u64 v[220:221], v[230:231], 0, s[96:97]
	s_mov_b32 m0, s70
	s_nop 0
	global_load_lds_dwordx4 v[220:221], off
	s_barrier
	s_waitcnt lgkmcnt(0)
	s_setprio 1
	s_waitcnt lgkmcnt(0)
	v_mfma_f32_16x16x32_bf16 v[92:95], v[204:207], v[160:163], v[92:95]
	v_mfma_f32_16x16x32_bf16 v[88:91], v[212:215], v[160:163], v[88:91]
	v_mfma_f32_16x16x32_bf16 v[84:87], v[204:207], v[168:171], v[84:87]
	v_mfma_f32_16x16x32_bf16 v[80:83], v[212:215], v[168:171], v[80:83]
	v_mfma_f32_16x16x32_bf16 v[76:79], v[204:207], v[176:179], v[76:79]
	v_mfma_f32_16x16x32_bf16 v[72:75], v[212:215], v[176:179], v[72:75]
	v_mfma_f32_16x16x32_bf16 v[68:71], v[204:207], v[184:187], v[68:71]
	v_mfma_f32_16x16x32_bf16 v[64:67], v[212:215], v[184:187], v[64:67]
	v_mfma_f32_16x16x32_bf16 v[92:95], v[208:211], v[164:167], v[92:95]
	v_mfma_f32_16x16x32_bf16 v[88:91], v[216:219], v[164:167], v[88:91]
	v_mfma_f32_16x16x32_bf16 v[84:87], v[208:211], v[172:175], v[84:87]
	v_mfma_f32_16x16x32_bf16 v[80:83], v[216:219], v[172:175], v[80:83]
	v_mfma_f32_16x16x32_bf16 v[76:79], v[208:211], v[180:183], v[76:79]
	v_mfma_f32_16x16x32_bf16 v[72:75], v[216:219], v[180:183], v[72:75]
	v_mfma_f32_16x16x32_bf16 v[68:71], v[208:211], v[188:191], v[68:71]
	v_mfma_f32_16x16x32_bf16 v[64:67], v[216:219], v[188:191], v[64:67]
	s_setprio 0
	s_mov_b32 m0, s7
	v_lshl_add_u64 v[220:221], v[228:229], 0, s[2:3]
	s_barrier
	ds_read_b128 v[160:163], v132 offset:16384
	ds_read_b128 v[164:167], v132 offset:17408
	ds_read_b128 v[168:171], v132 offset:18432
	ds_read_b128 v[172:175], v132 offset:19456
	ds_read_b128 v[176:179], v132 offset:20480
	ds_read_b128 v[180:183], v132 offset:21504
	ds_read_b128 v[184:187], v132 offset:22528
	ds_read_b128 v[188:191], v132 offset:23552
	global_load_lds_dwordx4 v[220:221], off
	v_lshl_add_u64 v[220:221], v[228:229], 0, s[74:75]
	s_mov_b32 m0, s71
	s_nop 0
	global_load_lds_dwordx4 v[220:221], off
	s_barrier
	s_waitcnt lgkmcnt(0)
	s_setprio 1
	s_waitcnt lgkmcnt(0)
	v_mfma_f32_16x16x32_bf16 v[60:63], v[144:147], v[160:163], v[60:63]
	v_mfma_f32_16x16x32_bf16 v[56:59], v[152:155], v[160:163], v[56:59]
	v_mfma_f32_16x16x32_bf16 v[52:55], v[144:147], v[168:171], v[52:55]
	v_mfma_f32_16x16x32_bf16 v[48:51], v[152:155], v[168:171], v[48:51]
	v_mfma_f32_16x16x32_bf16 v[44:47], v[144:147], v[176:179], v[44:47]
	v_mfma_f32_16x16x32_bf16 v[40:43], v[152:155], v[176:179], v[40:43]
	v_mfma_f32_16x16x32_bf16 v[36:39], v[144:147], v[184:187], v[36:39]
	v_mfma_f32_16x16x32_bf16 v[32:35], v[152:155], v[184:187], v[32:35]
	v_mfma_f32_16x16x32_bf16 v[60:63], v[148:151], v[164:167], v[60:63]
	v_mfma_f32_16x16x32_bf16 v[56:59], v[156:159], v[164:167], v[56:59]
	v_mfma_f32_16x16x32_bf16 v[52:55], v[148:151], v[172:175], v[52:55]
	v_mfma_f32_16x16x32_bf16 v[48:51], v[156:159], v[172:175], v[48:51]
	v_mfma_f32_16x16x32_bf16 v[44:47], v[148:151], v[180:183], v[44:47]
	v_mfma_f32_16x16x32_bf16 v[40:43], v[156:159], v[180:183], v[40:43]
	v_mfma_f32_16x16x32_bf16 v[36:39], v[148:151], v[188:191], v[36:39]
	v_mfma_f32_16x16x32_bf16 v[32:35], v[156:159], v[188:191], v[32:35]
	s_setprio 0
	s_barrier
; #define LDA8(dst, b, h)                                                                                               \
;   _Pragma("unroll") for (int m = 0; m < 4; ++m) _Pragma("unroll") for (int k = 0; k < 2; ++k)                         \
;     dst[m][k] = *(const bf16x8*)(SA8(b, h) + la + m * 2048 + k * 1024)
; #define LDB8(dst, b, h)                                                                                               \
;   _Pragma("unroll") for (int n = 0; n < 2; ++n) _Pragma("unroll") for (int k = 0; k < 2; ++k)                         \
;     dst[n][k] = *(const bf16x8*)(SB8(b, h) + lb + n * 2048 + k * 1024)
; #define WAITV8(n) asm volatile("s_waitcnt vmcnt(" #n ")" ::: "memory")
; #define WAITL8(n) asm volatile("s_waitcnt lgkmcnt(" #n ")" ::: "memory")
; #define BAR8 __builtin_amdgcn_s_barrier()
; #define SCHED8 __builtin_amdgcn_sched_barrier(0)
; template <class Epi>
; DEV void gemm_tile8(char* shm, const u16* __restrict__ A, const u16* __restrict__ Bt, int K, int brow, int bcol, Epi& epi) {
;     ...
;     STAGE8(SB8(0, 1), Bt, bcol + HALF, t + 2);
;     WAITV8(6); BAR8; MMA8(1, 1, At, B1); BAR8;
;     LDB8(B0, 1, 0); SCHED8; LDA8(At, 1, 0); STAGE8(SA8(0, 1), A, brow + HALF, t + 2);
;     WAITL8(8); BAR8; WAITL8(0); MMA8(0, 0, At, B0); BAR8; SCHED8;
;     LDB8(B1, 1, 1); STAGE8(SB8(1, 0), Bt, bcol, t + 3);
	s_mov_b64 s[96:97], 0x1fc0100
	s_mov_b32 m0, s72
	v_lshl_add_u64 v[144:145], v[230:231], 0, s[96:97]
	s_mov_b64 s[96:97], 0x1fe0100
	global_load_lds_dwordx4 v[144:145], off
	v_lshl_add_u64 v[144:145], v[230:231], 0, s[96:97]
	s_mov_b32 m0, s73
	s_nop 0
	global_load_lds_dwordx4 v[144:145], off
	s_waitcnt vmcnt(6)
	s_barrier
	s_setprio 1
	v_mfma_f32_16x16x32_bf16 v[28:31], v[204:207], v[160:163], v[28:31]
	v_mfma_f32_16x16x32_bf16 v[24:27], v[212:215], v[160:163], v[24:27]
	v_mfma_f32_16x16x32_bf16 v[20:23], v[204:207], v[168:171], v[20:23]
	v_mfma_f32_16x16x32_bf16 v[16:19], v[212:215], v[168:171], v[16:19]
	v_mfma_f32_16x16x32_bf16 v[12:15], v[204:207], v[176:179], v[12:15]
	v_mfma_f32_16x16x32_bf16 v[8:11], v[212:215], v[176:179], v[8:11]
	v_mfma_f32_16x16x32_bf16 v[4:7], v[204:207], v[184:187], v[4:7]
	v_mfma_f32_16x16x32_bf16 v[0:3], v[212:215], v[184:187], v[0:3]
	v_mfma_f32_16x16x32_bf16 v[28:31], v[208:211], v[164:167], v[28:31]
	v_mfma_f32_16x16x32_bf16 v[24:27], v[216:219], v[164:167], v[24:27]
	v_mfma_f32_16x16x32_bf16 v[20:23], v[208:211], v[172:175], v[20:23]
	v_mfma_f32_16x16x32_bf16 v[16:19], v[216:219], v[172:175], v[16:19]
	v_mfma_f32_16x16x32_bf16 v[12:15], v[208:211], v[180:183], v[12:15]
	v_mfma_f32_16x16x32_bf16 v[8:11], v[216:219], v[180:183], v[8:11]
	v_mfma_f32_16x16x32_bf16 v[4:7], v[208:211], v[188:191], v[4:7]
	v_mfma_f32_16x16x32_bf16 v[0:3], v[216:219], v[188:191], v[0:3]
	s_setprio 0
	v_or_b32_e32 v143, 0x18000, v133
	v_add_u32_e32 v145, 0x18800, v133
	s_barrier
	v_add_u32_e32 v144, 0x18400, v133
	ds_read_b128 v[152:155], v143
	ds_read_b128 v[156:159], v144
	v_add_u32_e32 v146, 0x18c00, v133
	ds_read_b128 v[160:163], v145
	ds_read_b128 v[164:167], v146
	s_mov_b32 m0, s81
	v_lshl_add_u64 v[148:149], v[228:229], 0, s[18:19]
	ds_read_b128 v[168:171], v132 offset:32768
	ds_read_b128 v[172:175], v132 offset:33792
	ds_read_b128 v[176:179], v132 offset:34816
	ds_read_b128 v[180:183], v132 offset:35840
	ds_read_b128 v[184:187], v132 offset:36864
	ds_read_b128 v[188:191], v132 offset:37888
	ds_read_b128 v[204:207], v132 offset:38912
	ds_read_b128 v[208:211], v132 offset:39936
	global_load_lds_dwordx4 v[148:149], off
	v_lshl_add_u64 v[148:149], v[228:229], 0, s[22:23]
	s_mov_b32 m0, s84
	s_nop 0
	global_load_lds_dwordx4 v[148:149], off
	s_waitcnt lgkmcnt(8)
	s_barrier
	s_waitcnt lgkmcnt(0)
	s_setprio 1
	s_waitcnt lgkmcnt(0)
	v_mfma_f32_16x16x32_bf16 v[124:127], v[152:155], v[168:171], v[124:127]
	v_mfma_f32_16x16x32_bf16 v[120:123], v[160:163], v[168:171], v[120:123]
	v_mfma_f32_16x16x32_bf16 v[116:119], v[152:155], v[176:179], v[116:119]
	v_mfma_f32_16x16x32_bf16 v[112:115], v[160:163], v[176:179], v[112:115]
	v_mfma_f32_16x16x32_bf16 v[108:111], v[152:155], v[184:187], v[108:111]
	v_mfma_f32_16x16x32_bf16 v[104:107], v[160:163], v[184:187], v[104:107]
	v_mfma_f32_16x16x32_bf16 v[100:103], v[152:155], v[204:207], v[100:103]
	v_mfma_f32_16x16x32_bf16 v[96:99], v[160:163], v[204:207], v[96:99]
	v_mfma_f32_16x16x32_bf16 v[124:127], v[156:159], v[172:175], v[124:127]
	v_mfma_f32_16x16x32_bf16 v[120:123], v[164:167], v[172:175], v[120:123]
	v_mfma_f32_16x16x32_bf16 v[116:119], v[156:159], v[180:183], v[116:119]
	v_mfma_f32_16x16x32_bf16 v[112:115], v[164:167], v[180:183], v[112:115]
	v_mfma_f32_16x16x32_bf16 v[108:111], v[156:159], v[188:191], v[108:111]
	v_mfma_f32_16x16x32_bf16 v[104:107], v[164:167], v[188:191], v[104:107]
	v_mfma_f32_16x16x32_bf16 v[100:103], v[156:159], v[208:211], v[100:103]
	v_mfma_f32_16x16x32_bf16 v[96:99], v[164:167], v[208:211], v[96:99]
	s_setprio 0
	s_barrier
	s_mov_b64 s[96:97], 0x1f80180
	s_mov_b32 m0, s85
	v_or_b32_e32 v147, 0x1c000, v133
	v_add_u32_e32 v149, 0x1c800, v133
	v_lshl_add_u64 v[232:233], v[230:231], 0, s[96:97]
	s_mov_b64 s[96:97], 0x1fa0180
	v_add_u32_e32 v148, 0x1c400, v133
	ds_read_b128 v[212:215], v147
	ds_read_b128 v[216:219], v148
	v_add_u32_e32 v150, 0x1cc00, v133
	ds_read_b128 v[220:223], v149
	ds_read_b128 v[224:227], v150
	global_load_lds_dwordx4 v[232:233], off
	v_lshl_add_u64 v[232:233], v[230:231], 0, s[96:97]
	s_mov_b32 m0, s90
	s_nop 0
	global_load_lds_dwordx4 v[232:233], off
	s_barrier
	s_waitcnt lgkmcnt(0)
	s_setprio 1
	s_waitcnt lgkmcnt(0)
	v_mfma_f32_16x16x32_bf16 v[92:95], v[212:215], v[168:171], v[92:95]
	v_mfma_f32_16x16x32_bf16 v[88:91], v[220:223], v[168:171], v[88:91]
	v_mfma_f32_16x16x32_bf16 v[84:87], v[212:215], v[176:179], v[84:87]
	v_mfma_f32_16x16x32_bf16 v[80:83], v[220:223], v[176:179], v[80:83]
	v_mfma_f32_16x16x32_bf16 v[76:79], v[212:215], v[184:187], v[76:79]
	v_mfma_f32_16x16x32_bf16 v[72:75], v[220:223], v[184:187], v[72:75]
	v_mfma_f32_16x16x32_bf16 v[68:71], v[212:215], v[204:207], v[68:71]
	v_mfma_f32_16x16x32_bf16 v[64:67], v[220:223], v[204:207], v[64:67]
	v_mfma_f32_16x16x32_bf16 v[92:95], v[216:219], v[172:175], v[92:95]
	v_mfma_f32_16x16x32_bf16 v[88:91], v[224:227], v[172:175], v[88:91]
	v_mfma_f32_16x16x32_bf16 v[84:87], v[216:219], v[180:183], v[84:87]
	v_mfma_f32_16x16x32_bf16 v[80:83], v[224:227], v[180:183], v[80:83]
	v_mfma_f32_16x16x32_bf16 v[76:79], v[216:219], v[188:191], v[76:79]
	v_mfma_f32_16x16x32_bf16 v[72:75], v[224:227], v[188:191], v[72:75]
	v_mfma_f32_16x16x32_bf16 v[68:71], v[216:219], v[208:211], v[68:71]
	v_mfma_f32_16x16x32_bf16 v[64:67], v[224:227], v[208:211], v[64:67]
	s_setprio 0
	s_mov_b32 m0, s91
	v_lshl_add_u64 v[232:233], v[228:229], 0, s[64:65]
	s_barrier
; #define LDA8(dst, b, h)                                                                                               \
;   _Pragma("unroll") for (int m = 0; m < 4; ++m) _Pragma("unroll") for (int k = 0; k < 2; ++k)                         \
;     dst[m][k] = *(const bf16x8*)(SA8(b, h) + la + m * 2048 + k * 1024)
; #define LDB8(dst, b, h)                                                                                               \
;   _Pragma("unroll") for (int n = 0; n < 2; ++n) _Pragma("unroll") for (int k = 0; k < 2; ++k)                         \
;     dst[n][k] = *(const bf16x8*)(SB8(b, h) + lb + n * 2048 + k * 1024)
; #define WAITV8(n) asm volatile("s_waitcnt vmcnt(" #n ")" ::: "memory")
; #define WAITL8(n) asm volatile("s_waitcnt lgkmcnt(" #n ")" ::: "memory")
; #define BAR8 __builtin_amdgcn_s_barrier()
; #define SCHED8 __builtin_amdgcn_sched_barrier(0)
; template <class Epi>
; DEV void gemm_tile8(char* shm, const u16* __restrict__ A, const u16* __restrict__ Bt, int K, int brow, int bcol, Epi& epi) {
;     ...
;     BAR8; WAITL8(0); MMA8(0, 1, At, B1); BAR8;
;     LDA8(At, 1, 1); STAGE8(SA8(1, 0), A, brow, t + 3);
;     BAR8; WAITL8(0); MMA8(1, 0, At, B0); BAR8; SCHED8;
;     STAGE8(SB8(1, 1), Bt, bcol + HALF, t + 3);
;     WAITV8(6); BAR8; MMA8(1, 1, At, B1); BAR8;
;   }
;   { LDB8(B0, 0, 0); LDA8(At, 0, 0); STAGE8(SA8(1, 1), A, brow + HALF, nt - 1);
;     BAR8; WAITL8(0); MMA8(0, 0, At, B0); BAR8;
	ds_read_b128 v[168:171], v132 offset:49152
	ds_read_b128 v[172:175], v132 offset:50176
	ds_read_b128 v[176:179], v132 offset:51200
	ds_read_b128 v[180:183], v132 offset:52224
	ds_read_b128 v[184:187], v132 offset:53248
	ds_read_b128 v[188:191], v132 offset:54272
	ds_read_b128 v[204:207], v132 offset:55296
	ds_read_b128 v[208:211], v132 offset:56320
	global_load_lds_dwordx4 v[232:233], off
	v_lshl_add_u64 v[228:229], v[228:229], 0, s[82:83]
	s_mov_b32 m0, s92
	s_nop 0
	global_load_lds_dwordx4 v[228:229], off
	s_barrier
	s_waitcnt lgkmcnt(0)
	s_setprio 1
	s_waitcnt lgkmcnt(0)
	v_mfma_f32_16x16x32_bf16 v[60:63], v[152:155], v[168:171], v[60:63]
	v_mfma_f32_16x16x32_bf16 v[56:59], v[160:163], v[168:171], v[56:59]
	v_mfma_f32_16x16x32_bf16 v[52:55], v[152:155], v[176:179], v[52:55]
	v_mfma_f32_16x16x32_bf16 v[48:51], v[160:163], v[176:179], v[48:51]
	v_mfma_f32_16x16x32_bf16 v[44:47], v[152:155], v[184:187], v[44:47]
	v_mfma_f32_16x16x32_bf16 v[40:43], v[160:163], v[184:187], v[40:43]
	v_mfma_f32_16x16x32_bf16 v[36:39], v[152:155], v[204:207], v[36:39]
	v_mfma_f32_16x16x32_bf16 v[32:35], v[160:163], v[204:207], v[32:35]
	v_mfma_f32_16x16x32_bf16 v[60:63], v[156:159], v[172:175], v[60:63]
	v_mfma_f32_16x16x32_bf16 v[56:59], v[164:167], v[172:175], v[56:59]
	v_mfma_f32_16x16x32_bf16 v[52:55], v[156:159], v[180:183], v[52:55]
	v_mfma_f32_16x16x32_bf16 v[48:51], v[164:167], v[180:183], v[48:51]
	v_mfma_f32_16x16x32_bf16 v[44:47], v[156:159], v[188:191], v[44:47]
	v_mfma_f32_16x16x32_bf16 v[40:43], v[164:167], v[188:191], v[40:43]
	v_mfma_f32_16x16x32_bf16 v[36:39], v[156:159], v[208:211], v[36:39]
	v_mfma_f32_16x16x32_bf16 v[32:35], v[164:167], v[208:211], v[32:35]
	s_setprio 0
	s_barrier
	s_mov_b64 s[96:97], 0x1fc0180
	s_mov_b32 m0, s93
	v_lshl_add_u64 v[152:153], v[230:231], 0, s[96:97]
	s_mov_b64 s[96:97], 0x1fe0180
	global_load_lds_dwordx4 v[152:153], off
	v_lshl_add_u64 v[152:153], v[230:231], 0, s[96:97]
	s_mov_b32 m0, s94
	s_nop 0
	global_load_lds_dwordx4 v[152:153], off
	s_waitcnt vmcnt(6)
	s_barrier
	s_setprio 1
	v_mfma_f32_16x16x32_bf16 v[28:31], v[212:215], v[168:171], v[28:31]
	v_mfma_f32_16x16x32_bf16 v[24:27], v[220:223], v[168:171], v[24:27]
	v_mfma_f32_16x16x32_bf16 v[20:23], v[212:215], v[176:179], v[20:23]
	v_mfma_f32_16x16x32_bf16 v[16:19], v[220:223], v[176:179], v[16:19]
	v_mfma_f32_16x16x32_bf16 v[12:15], v[212:215], v[184:187], v[12:15]
	v_mfma_f32_16x16x32_bf16 v[8:11], v[220:223], v[184:187], v[8:11]
	v_mfma_f32_16x16x32_bf16 v[4:7], v[212:215], v[204:207], v[4:7]
	v_mfma_f32_16x16x32_bf16 v[0:3], v[220:223], v[204:207], v[0:3]
	v_mfma_f32_16x16x32_bf16 v[28:31], v[216:219], v[172:175], v[28:31]
	v_mfma_f32_16x16x32_bf16 v[24:27], v[224:227], v[172:175], v[24:27]
	v_mfma_f32_16x16x32_bf16 v[20:23], v[216:219], v[180:183], v[20:23]
	v_mfma_f32_16x16x32_bf16 v[16:19], v[224:227], v[180:183], v[16:19]
	v_mfma_f32_16x16x32_bf16 v[12:15], v[216:219], v[188:191], v[12:15]
	v_mfma_f32_16x16x32_bf16 v[8:11], v[224:227], v[188:191], v[8:11]
	v_mfma_f32_16x16x32_bf16 v[4:7], v[216:219], v[208:211], v[4:7]
	v_mfma_f32_16x16x32_bf16 v[0:3], v[224:227], v[208:211], v[0:3]
	s_setprio 0
	s_add_i32 s26, s26, 2
	s_add_u32 s10, s10, 0x100
	s_addc_u32 s11, s11, 0
	s_add_u32 s24, s24, 0x100
	s_addc_u32 s25, s25, 0
	s_cmp_lt_u32 s26, 12
	s_barrier
	s_cbranch_scc1 .LBB0_389
	s_mov_b64 s[10:11], 0x780
	s_mov_b32 m0, s95
	v_lshl_add_u64 v[130:131], v[128:129], 0, s[10:11]
	s_mov_b64 s[10:11], 0x20780
	s_waitcnt vmcnt(0)
	ds_read_b128 v[152:155], v134
	ds_read_b128 v[156:159], v135
	ds_read_b128 v[160:163], v136
	ds_read_b128 v[134:137], v137
	ds_read_b128 v[164:167], v132
	ds_read_b128 v[168:171], v132 offset:1024
	ds_read_b128 v[172:175], v132 offset:2048
	ds_read_b128 v[176:179], v132 offset:3072
	ds_read_b128 v[180:183], v132 offset:4096
	ds_read_b128 v[184:187], v132 offset:5120
	ds_read_b128 v[188:191], v132 offset:6144
	ds_read_b128 v[204:207], v132 offset:7168
	global_load_lds_dwordx4 v[130:131], off
	v_lshl_add_u64 v[128:129], v[128:129], 0, s[10:11]
	s_mov_b32 m0, s27
	s_nop 0
	global_load_lds_dwordx4 v[128:129], off
	s_barrier
	s_waitcnt lgkmcnt(0)
	s_setprio 1
	s_waitcnt lgkmcnt(0)
	v_mfma_f32_16x16x32_bf16 v[124:127], v[152:155], v[164:167], v[124:127]
	v_mfma_f32_16x16x32_bf16 v[120:123], v[160:163], v[164:167], v[120:123]
	v_mfma_f32_16x16x32_bf16 v[116:119], v[152:155], v[172:175], v[116:119]
	v_mfma_f32_16x16x32_bf16 v[112:115], v[160:163], v[172:175], v[112:115]
	v_mfma_f32_16x16x32_bf16 v[108:111], v[152:155], v[180:183], v[108:111]
	v_mfma_f32_16x16x32_bf16 v[104:107], v[160:163], v[180:183], v[104:107]
	v_mfma_f32_16x16x32_bf16 v[100:103], v[152:155], v[188:191], v[100:103]
	v_mfma_f32_16x16x32_bf16 v[96:99], v[160:163], v[188:191], v[96:99]
	v_mfma_f32_16x16x32_bf16 v[124:127], v[156:159], v[168:171], v[124:127]
	v_mfma_f32_16x16x32_bf16 v[120:123], v[134:137], v[168:171], v[120:123]
	v_mfma_f32_16x16x32_bf16 v[116:119], v[156:159], v[176:179], v[116:119]
	v_mfma_f32_16x16x32_bf16 v[112:115], v[134:137], v[176:179], v[112:115]
	v_mfma_f32_16x16x32_bf16 v[108:111], v[156:159], v[184:187], v[108:111]
	v_mfma_f32_16x16x32_bf16 v[104:107], v[134:137], v[184:187], v[104:107]
	v_mfma_f32_16x16x32_bf16 v[100:103], v[156:159], v[204:207], v[100:103]
	v_mfma_f32_16x16x32_bf16 v[96:99], v[134:137], v[204:207], v[96:99]
	s_setprio 0
	s_barrier
	s_waitcnt vmcnt(0)
	ds_read_b128 v[128:131], v138
	ds_read_b128 v[208:211], v139
	ds_read_b128 v[212:215], v140
	ds_read_b128 v[216:219], v142
	s_barrier
; #define LDA8(dst, b, h)                                                                                               \
;   _Pragma("unroll") for (int m = 0; m < 4; ++m) _Pragma("unroll") for (int k = 0; k < 2; ++k)                         \
;     dst[m][k] = *(const bf16x8*)(SA8(b, h) + la + m * 2048 + k * 1024)
; #define LDB8(dst, b, h)                                                                                               \
;   _Pragma("unroll") for (int n = 0; n < 2; ++n) _Pragma("unroll") for (int k = 0; k < 2; ++k)                         \
;     dst[n][k] = *(const bf16x8*)(SB8(b, h) + lb + n * 2048 + k * 1024)
; #define WAITV8(n) asm volatile("s_waitcnt vmcnt(" #n ")" ::: "memory")
; #define WAITL8(n) asm volatile("s_waitcnt lgkmcnt(" #n ")" ::: "memory")
; #define BAR8 __builtin_amdgcn_s_barrier()
; template <class Epi>
; DEV void gemm_tile8(char* shm, const u16* __restrict__ A, const u16* __restrict__ Bt, int K, int brow, int bcol, Epi& epi) {
;     ...
;     BAR8; WAITL8(0); MMA8(0, 0, At, B0); BAR8;
;     LDB8(B1, 0, 1); BAR8; WAITL8(0); MMA8(0, 1, At, B1); BAR8;
;     LDA8(At, 0, 1); WAITV8(4); BAR8; WAITL8(0); MMA8(1, 0, At, B0); MMA8(1, 1, At, B1); BAR8; }
;   { LDB8(B0, 1, 0); LDA8(At, 1, 0); WAITV8(2); BAR8; WAITL8(0); MMA8(0, 0, At, B0); BAR8;
;     LDB8(B1, 1, 1); WAITV8(0); BAR8; WAITL8(0); MMA8(0, 1, At, B1); BAR8;
	s_waitcnt lgkmcnt(0)
	s_setprio 1
	s_waitcnt lgkmcnt(3)
	v_mfma_f32_16x16x32_bf16 v[92:95], v[128:131], v[164:167], v[92:95]
	s_waitcnt lgkmcnt(1)
	v_mfma_f32_16x16x32_bf16 v[88:91], v[212:215], v[164:167], v[88:91]
	v_mfma_f32_16x16x32_bf16 v[84:87], v[128:131], v[172:175], v[84:87]
	v_mfma_f32_16x16x32_bf16 v[80:83], v[212:215], v[172:175], v[80:83]
	v_mfma_f32_16x16x32_bf16 v[76:79], v[128:131], v[180:183], v[76:79]
	v_mfma_f32_16x16x32_bf16 v[72:75], v[212:215], v[180:183], v[72:75]
	v_mfma_f32_16x16x32_bf16 v[68:71], v[128:131], v[188:191], v[68:71]
	v_mfma_f32_16x16x32_bf16 v[64:67], v[212:215], v[188:191], v[64:67]
	v_mfma_f32_16x16x32_bf16 v[220:223], v[208:211], v[168:171], v[92:95]
	s_waitcnt lgkmcnt(0)
	v_mfma_f32_16x16x32_bf16 v[164:167], v[216:219], v[168:171], v[88:91]
	v_mfma_f32_16x16x32_bf16 v[168:171], v[208:211], v[176:179], v[84:87]
	v_mfma_f32_16x16x32_bf16 v[172:175], v[216:219], v[176:179], v[80:83]
	v_mfma_f32_16x16x32_bf16 v[176:179], v[208:211], v[184:187], v[76:79]
	v_mfma_f32_16x16x32_bf16 v[180:183], v[216:219], v[184:187], v[72:75]
	v_mfma_f32_16x16x32_bf16 v[184:187], v[208:211], v[204:207], v[68:71]
	v_mfma_f32_16x16x32_bf16 v[188:191], v[216:219], v[204:207], v[64:67]
	s_setprio 0
	s_barrier
	s_nop 0
	ds_read_b128 v[64:67], v132 offset:16384
	ds_read_b128 v[68:71], v132 offset:17408
	ds_read_b128 v[72:75], v132 offset:18432
	ds_read_b128 v[76:79], v132 offset:19456
	ds_read_b128 v[80:83], v132 offset:20480
	ds_read_b128 v[84:87], v132 offset:21504
	ds_read_b128 v[88:91], v132 offset:22528
	ds_read_b128 v[92:95], v132 offset:23552
	s_waitcnt vmcnt(4)
	s_barrier
	s_waitcnt lgkmcnt(0)
	s_setprio 1
	s_waitcnt lgkmcnt(7)
	v_mfma_f32_16x16x32_bf16 v[60:63], v[152:155], v[64:67], v[60:63]
	v_mfma_f32_16x16x32_bf16 v[56:59], v[160:163], v[64:67], v[56:59]
	s_waitcnt lgkmcnt(5)
	v_mfma_f32_16x16x32_bf16 v[52:55], v[152:155], v[72:75], v[52:55]
	v_mfma_f32_16x16x32_bf16 v[48:51], v[160:163], v[72:75], v[48:51]
	s_waitcnt lgkmcnt(3)
	v_mfma_f32_16x16x32_bf16 v[44:47], v[152:155], v[80:83], v[44:47]
	v_mfma_f32_16x16x32_bf16 v[40:43], v[160:163], v[80:83], v[40:43]
	s_waitcnt lgkmcnt(1)
	v_mfma_f32_16x16x32_bf16 v[36:39], v[152:155], v[88:91], v[36:39]
	v_mfma_f32_16x16x32_bf16 v[32:35], v[160:163], v[88:91], v[32:35]
	v_mfma_f32_16x16x32_bf16 v[60:63], v[156:159], v[68:71], v[60:63]
	v_mfma_f32_16x16x32_bf16 v[56:59], v[134:137], v[68:71], v[56:59]
	v_mfma_f32_16x16x32_bf16 v[52:55], v[156:159], v[76:79], v[52:55]
	v_mfma_f32_16x16x32_bf16 v[48:51], v[134:137], v[76:79], v[48:51]
	v_mfma_f32_16x16x32_bf16 v[44:47], v[156:159], v[84:87], v[44:47]
	v_mfma_f32_16x16x32_bf16 v[40:43], v[134:137], v[84:87], v[40:43]
	s_waitcnt lgkmcnt(0)
	v_mfma_f32_16x16x32_bf16 v[36:39], v[156:159], v[92:95], v[36:39]
	v_mfma_f32_16x16x32_bf16 v[32:35], v[134:137], v[92:95], v[32:35]
	s_setprio 0
	s_setprio 1
	v_mfma_f32_16x16x32_bf16 v[28:31], v[128:131], v[64:67], v[28:31]
	v_mfma_f32_16x16x32_bf16 v[24:27], v[212:215], v[64:67], v[24:27]
	v_mfma_f32_16x16x32_bf16 v[20:23], v[128:131], v[72:75], v[20:23]
	v_mfma_f32_16x16x32_bf16 v[16:19], v[212:215], v[72:75], v[16:19]
	v_mfma_f32_16x16x32_bf16 v[12:15], v[128:131], v[80:83], v[12:15]
	v_mfma_f32_16x16x32_bf16 v[8:11], v[212:215], v[80:83], v[8:11]
	v_mfma_f32_16x16x32_bf16 v[4:7], v[128:131], v[88:91], v[4:7]
	v_mfma_f32_16x16x32_bf16 v[0:3], v[212:215], v[88:91], v[0:3]
	v_mfma_f32_16x16x32_bf16 v[134:137], v[208:211], v[68:71], v[28:31]
	v_mfma_f32_16x16x32_bf16 v[152:155], v[216:219], v[68:71], v[24:27]
	v_mfma_f32_16x16x32_bf16 v[156:159], v[208:211], v[76:79], v[20:23]
	v_mfma_f32_16x16x32_bf16 v[160:163], v[216:219], v[76:79], v[16:19]
	v_mfma_f32_16x16x32_bf16 v[204:207], v[208:211], v[84:87], v[12:15]
	v_mfma_f32_16x16x32_bf16 v[224:227], v[216:219], v[84:87], v[8:11]
	v_mfma_f32_16x16x32_bf16 v[128:131], v[208:211], v[92:95], v[4:7]
	v_mfma_f32_16x16x32_bf16 v[208:211], v[216:219], v[92:95], v[0:3]
	s_setprio 0
	s_barrier
	ds_read_b128 v[24:27], v143
	ds_read_b128 v[28:31], v144
	ds_read_b128 v[142:145], v145
	ds_read_b128 v[212:215], v146
	ds_read_b128 v[0:3], v132 offset:32768
	ds_read_b128 v[4:7], v132 offset:33792
	ds_read_b128 v[8:11], v132 offset:34816
	ds_read_b128 v[12:15], v132 offset:35840
	ds_read_b128 v[16:19], v132 offset:36864
	ds_read_b128 v[20:23], v132 offset:37888
	ds_read_b128 v[216:219], v132 offset:38912
	ds_read_b128 v[228:231], v132 offset:39936
	s_waitcnt vmcnt(2)
	s_barrier
; #define LDA8(dst, b, h)                                                                                               \
;   _Pragma("unroll") for (int m = 0; m < 4; ++m) _Pragma("unroll") for (int k = 0; k < 2; ++k)                         \
;     dst[m][k] = *(const bf16x8*)(SA8(b, h) + la + m * 2048 + k * 1024)
; #define LDB8(dst, b, h)                                                                                               \
;   _Pragma("unroll") for (int n = 0; n < 2; ++n) _Pragma("unroll") for (int k = 0; k < 2; ++k)                         \
;     dst[n][k] = *(const bf16x8*)(SB8(b, h) + lb + n * 2048 + k * 1024)
; #define WAITV8(n) asm volatile("s_waitcnt vmcnt(" #n ")" ::: "memory")
; #define WAITL8(n) asm volatile("s_waitcnt lgkmcnt(" #n ")" ::: "memory")
; #define BAR8 __builtin_amdgcn_s_barrier()
; template <class Epi>
; DEV void gemm_tile8(char* shm, const u16* __restrict__ A, const u16* __restrict__ Bt, int K, int brow, int bcol, Epi& epi) {
;     ...
;   { LDB8(B0, 1, 0); LDA8(At, 1, 0); WAITV8(2); BAR8; WAITL8(0); MMA8(0, 0, At, B0); BAR8;
;     LDB8(B1, 1, 1); WAITV8(0); BAR8; WAITL8(0); MMA8(0, 1, At, B1); BAR8;
;     LDA8(At, 1, 1); BAR8; WAITL8(0); MMA8(1, 0, At, B0); MMA8(1, 1, At, B1); BAR8; }
;   if (wrs == 0) BAR8;
	s_waitcnt lgkmcnt(0)
	s_setprio 1
	s_waitcnt lgkmcnt(7)
	v_mfma_f32_16x16x32_bf16 v[64:67], v[24:27], v[0:3], v[124:127]
	s_waitcnt lgkmcnt(6)
	v_mfma_f32_16x16x32_bf16 v[72:75], v[28:31], v[4:7], v[64:67]
	v_mfma_f32_16x16x32_bf16 v[64:67], v[142:145], v[0:3], v[120:123]
	s_waitcnt lgkmcnt(5)
	v_mfma_f32_16x16x32_bf16 v[68:71], v[24:27], v[8:11], v[116:119]
	v_mfma_f32_16x16x32_bf16 v[76:79], v[142:145], v[8:11], v[112:115]
	s_waitcnt lgkmcnt(3)
	v_mfma_f32_16x16x32_bf16 v[80:83], v[24:27], v[16:19], v[108:111]
	v_mfma_f32_16x16x32_bf16 v[84:87], v[142:145], v[16:19], v[104:107]
	s_waitcnt lgkmcnt(1)
	v_mfma_f32_16x16x32_bf16 v[88:91], v[24:27], v[216:219], v[100:103]
	v_mfma_f32_16x16x32_bf16 v[92:95], v[142:145], v[216:219], v[96:99]
	v_mfma_f32_16x16x32_bf16 v[64:67], v[212:215], v[4:7], v[64:67]
	v_mfma_f32_16x16x32_bf16 v[68:71], v[28:31], v[12:15], v[68:71]
	v_mfma_f32_16x16x32_bf16 v[76:79], v[212:215], v[12:15], v[76:79]
	v_mfma_f32_16x16x32_bf16 v[80:83], v[28:31], v[20:23], v[80:83]
	v_mfma_f32_16x16x32_bf16 v[84:87], v[212:215], v[20:23], v[84:87]
	s_waitcnt lgkmcnt(0)
	v_mfma_f32_16x16x32_bf16 v[88:91], v[28:31], v[228:231], v[88:91]
	v_mfma_f32_16x16x32_bf16 v[92:95], v[212:215], v[228:231], v[92:95]
	s_setprio 0
	s_barrier
	ds_read_b128 v[232:235], v147
	ds_read_b128 v[236:239], v148
	ds_read_b128 v[146:149], v149
	ds_read_b128 v[240:243], v150
	s_waitcnt vmcnt(0)
	s_barrier
	s_waitcnt lgkmcnt(0)
	s_setprio 1
	s_waitcnt lgkmcnt(3)
	v_mfma_f32_16x16x32_bf16 v[96:99], v[232:235], v[0:3], v[220:223]
	s_waitcnt lgkmcnt(1)
	v_mfma_f32_16x16x32_bf16 v[0:3], v[146:149], v[0:3], v[164:167]
	v_mfma_f32_16x16x32_bf16 v[104:107], v[236:239], v[4:7], v[96:99]
	s_waitcnt lgkmcnt(0)
	v_mfma_f32_16x16x32_bf16 v[96:99], v[240:243], v[4:7], v[0:3]
	v_mfma_f32_16x16x32_bf16 v[0:3], v[232:235], v[8:11], v[168:171]
	v_mfma_f32_16x16x32_bf16 v[100:103], v[236:239], v[12:15], v[0:3]
	v_mfma_f32_16x16x32_bf16 v[0:3], v[146:149], v[8:11], v[172:175]
	v_mfma_f32_16x16x32_bf16 v[108:111], v[240:243], v[12:15], v[0:3]
	v_mfma_f32_16x16x32_bf16 v[0:3], v[232:235], v[16:19], v[176:179]
	v_mfma_f32_16x16x32_bf16 v[112:115], v[236:239], v[20:23], v[0:3]
	v_mfma_f32_16x16x32_bf16 v[0:3], v[146:149], v[16:19], v[180:183]
	v_mfma_f32_16x16x32_bf16 v[116:119], v[240:243], v[20:23], v[0:3]
	v_mfma_f32_16x16x32_bf16 v[0:3], v[232:235], v[216:219], v[184:187]
	v_mfma_f32_16x16x32_bf16 v[120:123], v[236:239], v[228:231], v[0:3]
	v_mfma_f32_16x16x32_bf16 v[0:3], v[146:149], v[216:219], v[188:191]
	v_mfma_f32_16x16x32_bf16 v[124:127], v[240:243], v[228:231], v[0:3]
	s_setprio 0
	s_barrier
	ds_read_b128 v[164:167], v132 offset:49152
	ds_read_b128 v[168:171], v132 offset:50176
	ds_read_b128 v[172:175], v132 offset:51200
	ds_read_b128 v[176:179], v132 offset:52224
	ds_read_b128 v[180:183], v132 offset:53248
	ds_read_b128 v[184:187], v132 offset:54272
	ds_read_b128 v[188:191], v132 offset:55296
	ds_read_b128 v[216:219], v132 offset:56320
	s_barrier
	s_waitcnt lgkmcnt(0)
	s_setprio 1
	s_waitcnt lgkmcnt(7)
	v_mfma_f32_16x16x32_bf16 v[0:3], v[24:27], v[164:167], v[60:63]
	s_waitcnt lgkmcnt(5)
	v_mfma_f32_16x16x32_bf16 v[8:11], v[24:27], v[172:175], v[52:55]
	s_waitcnt lgkmcnt(3)
	v_mfma_f32_16x16x32_bf16 v[16:19], v[24:27], v[180:183], v[44:47]
	s_waitcnt lgkmcnt(1)
	v_mfma_f32_16x16x32_bf16 v[24:27], v[24:27], v[188:191], v[36:39]
	v_mfma_f32_16x16x32_bf16 v[0:3], v[28:31], v[168:171], v[0:3]
	v_mfma_f32_16x16x32_bf16 v[4:7], v[142:145], v[164:167], v[56:59]
	v_mfma_f32_16x16x32_bf16 v[8:11], v[28:31], v[176:179], v[8:11]
	v_mfma_f32_16x16x32_bf16 v[12:15], v[142:145], v[172:175], v[48:51]
	v_mfma_f32_16x16x32_bf16 v[16:19], v[28:31], v[184:187], v[16:19]
	v_mfma_f32_16x16x32_bf16 v[20:23], v[142:145], v[180:183], v[40:43]
	s_waitcnt lgkmcnt(0)
	v_mfma_f32_16x16x32_bf16 v[24:27], v[28:31], v[216:219], v[24:27]
	v_mfma_f32_16x16x32_bf16 v[28:31], v[142:145], v[188:191], v[32:35]
	v_mfma_f32_16x16x32_bf16 v[4:7], v[212:215], v[168:171], v[4:7]
	v_mfma_f32_16x16x32_bf16 v[12:15], v[212:215], v[176:179], v[12:15]
	v_mfma_f32_16x16x32_bf16 v[20:23], v[212:215], v[184:187], v[20:23]
	v_mfma_f32_16x16x32_bf16 v[28:31], v[212:215], v[216:219], v[28:31]
	s_setprio 0
	s_setprio 1
	v_mfma_f32_16x16x32_bf16 v[32:35], v[232:235], v[164:167], v[134:137]
	v_mfma_f32_16x16x32_bf16 v[36:39], v[146:149], v[164:167], v[152:155]
	v_mfma_f32_16x16x32_bf16 v[40:43], v[232:235], v[172:175], v[156:159]
	v_mfma_f32_16x16x32_bf16 v[44:47], v[146:149], v[172:175], v[160:163]
	v_mfma_f32_16x16x32_bf16 v[48:51], v[232:235], v[180:183], v[204:207]
	v_mfma_f32_16x16x32_bf16 v[52:55], v[146:149], v[180:183], v[224:227]
	v_mfma_f32_16x16x32_bf16 v[56:59], v[232:235], v[188:191], v[128:131]
	v_mfma_f32_16x16x32_bf16 v[60:63], v[146:149], v[188:191], v[208:211]
	v_mfma_f32_16x16x32_bf16 v[32:35], v[236:239], v[168:171], v[32:35]
	v_mfma_f32_16x16x32_bf16 v[36:39], v[240:243], v[168:171], v[36:39]
	v_mfma_f32_16x16x32_bf16 v[40:43], v[236:239], v[176:179], v[40:43]
	v_mfma_f32_16x16x32_bf16 v[44:47], v[240:243], v[176:179], v[44:47]
	v_mfma_f32_16x16x32_bf16 v[48:51], v[236:239], v[184:187], v[48:51]
	v_mfma_f32_16x16x32_bf16 v[52:55], v[240:243], v[184:187], v[52:55]
	v_mfma_f32_16x16x32_bf16 v[56:59], v[236:239], v[216:219], v[56:59]
	v_mfma_f32_16x16x32_bf16 v[60:63], v[240:243], v[216:219], v[60:63]
	s_setprio 0
	s_cmp_lg_u32 s54, 0
	s_barrier
	s_cbranch_scc1 .LBB0_392
	s_barrier

; #define LDA8(dst, b, h)                                                                                               \
;   _Pragma("unroll") for (int m = 0; m < 4; ++m) _Pragma("unroll") for (int k = 0; k < 2; ++k)                         \
;     dst[m][k] = *(const bf16x8*)(SA8(b, h) + la + m * 2048 + k * 1024)
; #define LDB8(dst, b, h)                                                                                               \
;   _Pragma("unroll") for (int n = 0; n < 2; ++n) _Pragma("unroll") for (int k = 0; k < 2; ++k)                         \
;     dst[n][k] = *(const bf16x8*)(SB8(b, h) + lb + n * 2048 + k * 1024)
; #define WAITL8(n) asm volatile("s_waitcnt lgkmcnt(" #n ")" ::: "memory")
; #define BAR8 __builtin_amdgcn_s_barrier()
; #define SCHED8 __builtin_amdgcn_sched_barrier(0)
; template <class Epi>
; DEV void gemm_tile8(char* shm, const u16* __restrict__ A, const u16* __restrict__ Bt, int K, int brow, int bcol, Epi& epi) {
;     ...
; #pragma unroll 1
;   for (int t = 0; t < nt - 2; t += 2) {
;     LDB8(B0, 0, 0); SCHED8; LDA8(At, 0, 0); STAGE8(SA8(1, 1), A, brow + HALF, t + 1);
;     WAITL8(8); BAR8; WAITL8(0); MMA8(0, 0, At, B0); BAR8; SCHED8;
;     LDB8(B1, 0, 1); STAGE8(SB8(0, 0), Bt, bcol, t + 2);
;     BAR8; WAITL8(0); MMA8(0, 1, At, B1); BAR8;
;     LDA8(At, 0, 1); STAGE8(SA8(0, 0), A, brow, t + 2);
;     BAR8; WAITL8(0); MMA8(1, 0, At, B0); BAR8; SCHED8;
.LBB0_424:
	v_or_b32_e32 v134, 0x10000, v133
	v_add_u32_e32 v136, 0x10800, v133
	v_add_u32_e32 v135, 0x10400, v133
	ds_read_b128 v[144:147], v134
	ds_read_b128 v[148:151], v135
	v_add_u32_e32 v137, 0x10c00, v133
	ds_read_b128 v[152:155], v136
	ds_read_b128 v[156:159], v137
	v_lshl_add_u64 v[228:229], s[22:23], 0, v[130:131]
	s_mov_b64 s[96:97], 0x112b0080
	v_lshl_add_u64 v[138:139], v[228:229], 0, s[96:97]
	s_add_i32 s97, s54, 0xc000
	s_mov_b32 m0, s97
	s_mov_b64 vcc, 0x11308080
	s_add_i32 s96, s54, 0xe000
	ds_read_b128 v[160:163], v132
	ds_read_b128 v[164:167], v132 offset:1024
	ds_read_b128 v[168:171], v132 offset:2048
	ds_read_b128 v[172:175], v132 offset:3072
	ds_read_b128 v[176:179], v132 offset:4096
	ds_read_b128 v[180:183], v132 offset:5120
	ds_read_b128 v[184:187], v132 offset:6144
	ds_read_b128 v[188:191], v132 offset:7168
	global_load_lds_dwordx4 v[138:139], off
	v_lshl_add_u64 v[138:139], v[228:229], 0, vcc
	s_mov_b32 m0, s96
	s_nop 0
	global_load_lds_dwordx4 v[138:139], off
	s_waitcnt lgkmcnt(8)
	s_barrier
	s_waitcnt lgkmcnt(0)
	s_setprio 1
	s_waitcnt lgkmcnt(0)
	v_mfma_f32_16x16x32_bf16 v[124:127], v[144:147], v[160:163], v[124:127]
	v_mfma_f32_16x16x32_bf16 v[120:123], v[152:155], v[160:163], v[120:123]
	v_mfma_f32_16x16x32_bf16 v[116:119], v[144:147], v[168:171], v[116:119]
	v_mfma_f32_16x16x32_bf16 v[112:115], v[152:155], v[168:171], v[112:115]
	v_mfma_f32_16x16x32_bf16 v[108:111], v[144:147], v[176:179], v[108:111]
	v_mfma_f32_16x16x32_bf16 v[104:107], v[152:155], v[176:179], v[104:107]
	v_mfma_f32_16x16x32_bf16 v[100:103], v[144:147], v[184:187], v[100:103]
	v_mfma_f32_16x16x32_bf16 v[96:99], v[152:155], v[184:187], v[96:99]
	v_mfma_f32_16x16x32_bf16 v[124:127], v[148:151], v[164:167], v[124:127]
	v_mfma_f32_16x16x32_bf16 v[120:123], v[156:159], v[164:167], v[120:123]
	v_mfma_f32_16x16x32_bf16 v[116:119], v[148:151], v[172:175], v[116:119]
	v_mfma_f32_16x16x32_bf16 v[112:115], v[156:159], v[172:175], v[112:115]
	v_mfma_f32_16x16x32_bf16 v[108:111], v[148:151], v[180:183], v[108:111]
	v_mfma_f32_16x16x32_bf16 v[104:107], v[156:159], v[180:183], v[104:107]
	v_mfma_f32_16x16x32_bf16 v[100:103], v[148:151], v[188:191], v[100:103]
	v_mfma_f32_16x16x32_bf16 v[96:99], v[156:159], v[188:191], v[96:99]
	s_setprio 0
	s_barrier
	v_lshl_add_u64 v[230:231], s[20:21], 0, v[130:131]
	s_mov_b64 vcc, 0x1a00100
	s_mov_b32 m0, s55
	v_or_b32_e32 v138, 0x14000, v133
	v_add_u32_e32 v140, 0x14800, v133
	v_lshl_add_u64 v[220:221], v[230:231], 0, vcc
	s_mov_b64 vcc, 0x1a58100
	v_add_u32_e32 v139, 0x14400, v133
	ds_read_b128 v[204:207], v138
	ds_read_b128 v[208:211], v139
	v_add_u32_e32 v142, 0x14c00, v133
	ds_read_b128 v[212:215], v140
	ds_read_b128 v[216:219], v142
	global_load_lds_dwordx4 v[220:221], off
	v_lshl_add_u64 v[220:221], v[230:231], 0, vcc
	s_mov_b32 m0, s70
	s_nop 0
	global_load_lds_dwordx4 v[220:221], off
	s_barrier
	s_waitcnt lgkmcnt(0)
	s_setprio 1
	s_waitcnt lgkmcnt(0)
	v_mfma_f32_16x16x32_bf16 v[92:95], v[204:207], v[160:163], v[92:95]
	v_mfma_f32_16x16x32_bf16 v[88:91], v[212:215], v[160:163], v[88:91]
	v_mfma_f32_16x16x32_bf16 v[84:87], v[204:207], v[168:171], v[84:87]
	v_mfma_f32_16x16x32_bf16 v[80:83], v[212:215], v[168:171], v[80:83]
	v_mfma_f32_16x16x32_bf16 v[76:79], v[204:207], v[176:179], v[76:79]
	v_mfma_f32_16x16x32_bf16 v[72:75], v[212:215], v[176:179], v[72:75]
	v_mfma_f32_16x16x32_bf16 v[68:71], v[204:207], v[184:187], v[68:71]
	v_mfma_f32_16x16x32_bf16 v[64:67], v[212:215], v[184:187], v[64:67]
	v_mfma_f32_16x16x32_bf16 v[92:95], v[208:211], v[164:167], v[92:95]
	v_mfma_f32_16x16x32_bf16 v[88:91], v[216:219], v[164:167], v[88:91]
	v_mfma_f32_16x16x32_bf16 v[84:87], v[208:211], v[172:175], v[84:87]
	v_mfma_f32_16x16x32_bf16 v[80:83], v[216:219], v[172:175], v[80:83]
	v_mfma_f32_16x16x32_bf16 v[76:79], v[208:211], v[180:183], v[76:79]
	v_mfma_f32_16x16x32_bf16 v[72:75], v[216:219], v[180:183], v[72:75]
	v_mfma_f32_16x16x32_bf16 v[68:71], v[208:211], v[188:191], v[68:71]
	v_mfma_f32_16x16x32_bf16 v[64:67], v[216:219], v[188:191], v[64:67]
	s_setprio 0
	s_mov_b64 vcc, 0x11200100
	s_mov_b32 m0, s54
	v_lshl_add_u64 v[220:221], v[228:229], 0, vcc
	s_mov_b64 vcc, 0x11258100
	s_barrier
	ds_read_b128 v[160:163], v132 offset:16384
	ds_read_b128 v[164:167], v132 offset:17408
	ds_read_b128 v[168:171], v132 offset:18432
	ds_read_b128 v[172:175], v132 offset:19456
	ds_read_b128 v[176:179], v132 offset:20480
	ds_read_b128 v[180:183], v132 offset:21504
	ds_read_b128 v[184:187], v132 offset:22528
	ds_read_b128 v[188:191], v132 offset:23552
	global_load_lds_dwordx4 v[220:221], off
	v_lshl_add_u64 v[220:221], v[228:229], 0, vcc
	s_mov_b32 m0, s71
	s_nop 0
	global_load_lds_dwordx4 v[220:221], off
	s_barrier
	s_waitcnt lgkmcnt(0)
	s_setprio 1
	s_waitcnt lgkmcnt(0)
	v_mfma_f32_16x16x32_bf16 v[60:63], v[144:147], v[160:163], v[60:63]
	v_mfma_f32_16x16x32_bf16 v[56:59], v[152:155], v[160:163], v[56:59]
	v_mfma_f32_16x16x32_bf16 v[52:55], v[144:147], v[168:171], v[52:55]
	v_mfma_f32_16x16x32_bf16 v[48:51], v[152:155], v[168:171], v[48:51]
	v_mfma_f32_16x16x32_bf16 v[44:47], v[144:147], v[176:179], v[44:47]
	v_mfma_f32_16x16x32_bf16 v[40:43], v[152:155], v[176:179], v[40:43]
	v_mfma_f32_16x16x32_bf16 v[36:39], v[144:147], v[184:187], v[36:39]
	v_mfma_f32_16x16x32_bf16 v[32:35], v[152:155], v[184:187], v[32:35]
	v_mfma_f32_16x16x32_bf16 v[60:63], v[148:151], v[164:167], v[60:63]
	v_mfma_f32_16x16x32_bf16 v[56:59], v[156:159], v[164:167], v[56:59]
	v_mfma_f32_16x16x32_bf16 v[52:55], v[148:151], v[172:175], v[52:55]
	v_mfma_f32_16x16x32_bf16 v[48:51], v[156:159], v[172:175], v[48:51]
	v_mfma_f32_16x16x32_bf16 v[44:47], v[148:151], v[180:183], v[44:47]
	v_mfma_f32_16x16x32_bf16 v[40:43], v[156:159], v[180:183], v[40:43]
	v_mfma_f32_16x16x32_bf16 v[36:39], v[148:151], v[188:191], v[36:39]
	v_mfma_f32_16x16x32_bf16 v[32:35], v[156:159], v[188:191], v[32:35]
	s_setprio 0
	s_barrier
; #define LDA8(dst, b, h)                                                                                               \
;   _Pragma("unroll") for (int m = 0; m < 4; ++m) _Pragma("unroll") for (int k = 0; k < 2; ++k)                         \
;     dst[m][k] = *(const bf16x8*)(SA8(b, h) + la + m * 2048 + k * 1024)
; #define LDB8(dst, b, h)                                                                                               \
;   _Pragma("unroll") for (int n = 0; n < 2; ++n) _Pragma("unroll") for (int k = 0; k < 2; ++k)                         \
;     dst[n][k] = *(const bf16x8*)(SB8(b, h) + lb + n * 2048 + k * 1024)
; #define WAITV8(n) asm volatile("s_waitcnt vmcnt(" #n ")" ::: "memory")
; #define WAITL8(n) asm volatile("s_waitcnt lgkmcnt(" #n ")" ::: "memory")
; #define BAR8 __builtin_amdgcn_s_barrier()
; #define SCHED8 __builtin_amdgcn_sched_barrier(0)
; template <class Epi>
; DEV void gemm_tile8(char* shm, const u16* __restrict__ A, const u16* __restrict__ Bt, int K, int brow, int bcol, Epi& epi) {
;     ...
;     STAGE8(SB8(0, 1), Bt, bcol + HALF, t + 2);
;     WAITV8(6); BAR8; MMA8(1, 1, At, B1); BAR8;
;     LDB8(B0, 1, 0); SCHED8; LDA8(At, 1, 0); STAGE8(SA8(0, 1), A, brow + HALF, t + 2);
;     WAITL8(8); BAR8; WAITL8(0); MMA8(0, 0, At, B0); BAR8; SCHED8;
;     LDB8(B1, 1, 1); STAGE8(SB8(1, 0), Bt, bcol, t + 3);
	s_mov_b64 vcc, 0x1ab0100
	s_mov_b32 m0, s72
	v_lshl_add_u64 v[144:145], v[230:231], 0, vcc
	s_mov_b64 vcc, 0x1b08100
	global_load_lds_dwordx4 v[144:145], off
	v_lshl_add_u64 v[144:145], v[230:231], 0, vcc
	s_mov_b32 m0, s73
	s_nop 0
	global_load_lds_dwordx4 v[144:145], off
	s_waitcnt vmcnt(6)
	s_barrier
	s_setprio 1
	v_mfma_f32_16x16x32_bf16 v[28:31], v[204:207], v[160:163], v[28:31]
	v_mfma_f32_16x16x32_bf16 v[24:27], v[212:215], v[160:163], v[24:27]
	v_mfma_f32_16x16x32_bf16 v[20:23], v[204:207], v[168:171], v[20:23]
	v_mfma_f32_16x16x32_bf16 v[16:19], v[212:215], v[168:171], v[16:19]
	v_mfma_f32_16x16x32_bf16 v[12:15], v[204:207], v[176:179], v[12:15]
	v_mfma_f32_16x16x32_bf16 v[8:11], v[212:215], v[176:179], v[8:11]
	v_mfma_f32_16x16x32_bf16 v[4:7], v[204:207], v[184:187], v[4:7]
	v_mfma_f32_16x16x32_bf16 v[0:3], v[212:215], v[184:187], v[0:3]
	v_mfma_f32_16x16x32_bf16 v[28:31], v[208:211], v[164:167], v[28:31]
	v_mfma_f32_16x16x32_bf16 v[24:27], v[216:219], v[164:167], v[24:27]
	v_mfma_f32_16x16x32_bf16 v[20:23], v[208:211], v[172:175], v[20:23]
	v_mfma_f32_16x16x32_bf16 v[16:19], v[216:219], v[172:175], v[16:19]
	v_mfma_f32_16x16x32_bf16 v[12:15], v[208:211], v[180:183], v[12:15]
	v_mfma_f32_16x16x32_bf16 v[8:11], v[216:219], v[180:183], v[8:11]
	v_mfma_f32_16x16x32_bf16 v[4:7], v[208:211], v[188:191], v[4:7]
	v_mfma_f32_16x16x32_bf16 v[0:3], v[216:219], v[188:191], v[0:3]
	s_setprio 0
	v_or_b32_e32 v143, 0x18000, v133
	v_add_u32_e32 v145, 0x18800, v133
	s_barrier
	v_add_u32_e32 v144, 0x18400, v133
	ds_read_b128 v[152:155], v143
	ds_read_b128 v[156:159], v144
	v_add_u32_e32 v146, 0x18c00, v133
	ds_read_b128 v[160:163], v145
	ds_read_b128 v[164:167], v146
	s_mov_b64 vcc, 0x112b0100
	s_mov_b32 m0, s81
	v_lshl_add_u64 v[148:149], v[228:229], 0, vcc
	s_mov_b64 vcc, 0x11308100
	ds_read_b128 v[168:171], v132 offset:32768
	ds_read_b128 v[172:175], v132 offset:33792
	ds_read_b128 v[176:179], v132 offset:34816
	ds_read_b128 v[180:183], v132 offset:35840
	ds_read_b128 v[184:187], v132 offset:36864
	ds_read_b128 v[188:191], v132 offset:37888
	ds_read_b128 v[204:207], v132 offset:38912
	ds_read_b128 v[208:211], v132 offset:39936
	global_load_lds_dwordx4 v[148:149], off
	v_lshl_add_u64 v[148:149], v[228:229], 0, vcc
	s_mov_b32 m0, s84
	s_nop 0
	global_load_lds_dwordx4 v[148:149], off
	s_waitcnt lgkmcnt(8)
	s_barrier
	s_waitcnt lgkmcnt(0)
	s_setprio 1
	s_waitcnt lgkmcnt(0)
	v_mfma_f32_16x16x32_bf16 v[124:127], v[152:155], v[168:171], v[124:127]
	v_mfma_f32_16x16x32_bf16 v[120:123], v[160:163], v[168:171], v[120:123]
	v_mfma_f32_16x16x32_bf16 v[116:119], v[152:155], v[176:179], v[116:119]
	v_mfma_f32_16x16x32_bf16 v[112:115], v[160:163], v[176:179], v[112:115]
	v_mfma_f32_16x16x32_bf16 v[108:111], v[152:155], v[184:187], v[108:111]
	v_mfma_f32_16x16x32_bf16 v[104:107], v[160:163], v[184:187], v[104:107]
	v_mfma_f32_16x16x32_bf16 v[100:103], v[152:155], v[204:207], v[100:103]
	v_mfma_f32_16x16x32_bf16 v[96:99], v[160:163], v[204:207], v[96:99]
	v_mfma_f32_16x16x32_bf16 v[124:127], v[156:159], v[172:175], v[124:127]
	v_mfma_f32_16x16x32_bf16 v[120:123], v[164:167], v[172:175], v[120:123]
	v_mfma_f32_16x16x32_bf16 v[116:119], v[156:159], v[180:183], v[116:119]
	v_mfma_f32_16x16x32_bf16 v[112:115], v[164:167], v[180:183], v[112:115]
	v_mfma_f32_16x16x32_bf16 v[108:111], v[156:159], v[188:191], v[108:111]
	v_mfma_f32_16x16x32_bf16 v[104:107], v[164:167], v[188:191], v[104:107]
	v_mfma_f32_16x16x32_bf16 v[100:103], v[156:159], v[208:211], v[100:103]
	v_mfma_f32_16x16x32_bf16 v[96:99], v[164:167], v[208:211], v[96:99]
	s_setprio 0
	s_barrier
	s_mov_b64 vcc, 0x1a00180
	s_mov_b32 m0, s85
	v_or_b32_e32 v147, 0x1c000, v133
	v_add_u32_e32 v149, 0x1c800, v133
	v_lshl_add_u64 v[232:233], v[230:231], 0, vcc
	s_mov_b64 vcc, 0x1a58180
	v_add_u32_e32 v148, 0x1c400, v133
	ds_read_b128 v[212:215], v147
	ds_read_b128 v[216:219], v148
	v_add_u32_e32 v150, 0x1cc00, v133
	ds_read_b128 v[220:223], v149
	ds_read_b128 v[224:227], v150
	global_load_lds_dwordx4 v[232:233], off
	v_lshl_add_u64 v[232:233], v[230:231], 0, vcc
	s_mov_b32 m0, s90
	s_nop 0
	global_load_lds_dwordx4 v[232:233], off
	s_barrier
	s_waitcnt lgkmcnt(0)
	s_setprio 1
	s_waitcnt lgkmcnt(0)
	v_mfma_f32_16x16x32_bf16 v[92:95], v[212:215], v[168:171], v[92:95]
	v_mfma_f32_16x16x32_bf16 v[88:91], v[220:223], v[168:171], v[88:91]
	v_mfma_f32_16x16x32_bf16 v[84:87], v[212:215], v[176:179], v[84:87]
	v_mfma_f32_16x16x32_bf16 v[80:83], v[220:223], v[176:179], v[80:83]
	v_mfma_f32_16x16x32_bf16 v[76:79], v[212:215], v[184:187], v[76:79]
	v_mfma_f32_16x16x32_bf16 v[72:75], v[220:223], v[184:187], v[72:75]
	v_mfma_f32_16x16x32_bf16 v[68:71], v[212:215], v[204:207], v[68:71]
	v_mfma_f32_16x16x32_bf16 v[64:67], v[220:223], v[204:207], v[64:67]
	v_mfma_f32_16x16x32_bf16 v[92:95], v[216:219], v[172:175], v[92:95]
	v_mfma_f32_16x16x32_bf16 v[88:91], v[224:227], v[172:175], v[88:91]
	v_mfma_f32_16x16x32_bf16 v[84:87], v[216:219], v[180:183], v[84:87]
	v_mfma_f32_16x16x32_bf16 v[80:83], v[224:227], v[180:183], v[80:83]
	v_mfma_f32_16x16x32_bf16 v[76:79], v[216:219], v[188:191], v[76:79]
	v_mfma_f32_16x16x32_bf16 v[72:75], v[224:227], v[188:191], v[72:75]
	v_mfma_f32_16x16x32_bf16 v[68:71], v[216:219], v[208:211], v[68:71]
	v_mfma_f32_16x16x32_bf16 v[64:67], v[224:227], v[208:211], v[64:67]
	s_setprio 0
	s_mov_b64 vcc, 0x11200180
	s_mov_b32 m0, s91
	v_lshl_add_u64 v[232:233], v[228:229], 0, vcc
	s_mov_b64 vcc, 0x11258180
	s_barrier
; #define LDA8(dst, b, h)                                                                                               \
;   _Pragma("unroll") for (int m = 0; m < 4; ++m) _Pragma("unroll") for (int k = 0; k < 2; ++k)                         \
;     dst[m][k] = *(const bf16x8*)(SA8(b, h) + la + m * 2048 + k * 1024)
; #define LDB8(dst, b, h)                                                                                               \
;   _Pragma("unroll") for (int n = 0; n < 2; ++n) _Pragma("unroll") for (int k = 0; k < 2; ++k)                         \
;     dst[n][k] = *(const bf16x8*)(SB8(b, h) + lb + n * 2048 + k * 1024)
; #define WAITV8(n) asm volatile("s_waitcnt vmcnt(" #n ")" ::: "memory")
; #define WAITL8(n) asm volatile("s_waitcnt lgkmcnt(" #n ")" ::: "memory")
; #define BAR8 __builtin_amdgcn_s_barrier()
; #define SCHED8 __builtin_amdgcn_sched_barrier(0)
; template <class Epi>
; DEV void gemm_tile8(char* shm, const u16* __restrict__ A, const u16* __restrict__ Bt, int K, int brow, int bcol, Epi& epi) {
;     ...
;     BAR8; WAITL8(0); MMA8(0, 1, At, B1); BAR8;
;     LDA8(At, 1, 1); STAGE8(SA8(1, 0), A, brow, t + 3);
;     BAR8; WAITL8(0); MMA8(1, 0, At, B0); BAR8; SCHED8;
;     STAGE8(SB8(1, 1), Bt, bcol + HALF, t + 3);
;     WAITV8(6); BAR8; MMA8(1, 1, At, B1); BAR8;
;   }
;   { LDB8(B0, 0, 0); LDA8(At, 0, 0); STAGE8(SA8(1, 1), A, brow + HALF, nt - 1);
;     BAR8; WAITL8(0); MMA8(0, 0, At, B0); BAR8;
	ds_read_b128 v[168:171], v132 offset:49152
	ds_read_b128 v[172:175], v132 offset:50176
	ds_read_b128 v[176:179], v132 offset:51200
	ds_read_b128 v[180:183], v132 offset:52224
	ds_read_b128 v[184:187], v132 offset:53248
	ds_read_b128 v[188:191], v132 offset:54272
	ds_read_b128 v[204:207], v132 offset:55296
	ds_read_b128 v[208:211], v132 offset:56320
	global_load_lds_dwordx4 v[232:233], off
	v_lshl_add_u64 v[228:229], v[228:229], 0, vcc
	s_mov_b32 m0, s92
	s_nop 0
	global_load_lds_dwordx4 v[228:229], off
	s_barrier
	s_waitcnt lgkmcnt(0)
	s_setprio 1
	s_waitcnt lgkmcnt(0)
	v_mfma_f32_16x16x32_bf16 v[60:63], v[152:155], v[168:171], v[60:63]
	v_mfma_f32_16x16x32_bf16 v[56:59], v[160:163], v[168:171], v[56:59]
	v_mfma_f32_16x16x32_bf16 v[52:55], v[152:155], v[176:179], v[52:55]
	v_mfma_f32_16x16x32_bf16 v[48:51], v[160:163], v[176:179], v[48:51]
	v_mfma_f32_16x16x32_bf16 v[44:47], v[152:155], v[184:187], v[44:47]
	v_mfma_f32_16x16x32_bf16 v[40:43], v[160:163], v[184:187], v[40:43]
	v_mfma_f32_16x16x32_bf16 v[36:39], v[152:155], v[204:207], v[36:39]
	v_mfma_f32_16x16x32_bf16 v[32:35], v[160:163], v[204:207], v[32:35]
	v_mfma_f32_16x16x32_bf16 v[60:63], v[156:159], v[172:175], v[60:63]
	v_mfma_f32_16x16x32_bf16 v[56:59], v[164:167], v[172:175], v[56:59]
	v_mfma_f32_16x16x32_bf16 v[52:55], v[156:159], v[180:183], v[52:55]
	v_mfma_f32_16x16x32_bf16 v[48:51], v[164:167], v[180:183], v[48:51]
	v_mfma_f32_16x16x32_bf16 v[44:47], v[156:159], v[188:191], v[44:47]
	v_mfma_f32_16x16x32_bf16 v[40:43], v[164:167], v[188:191], v[40:43]
	v_mfma_f32_16x16x32_bf16 v[36:39], v[156:159], v[208:211], v[36:39]
	v_mfma_f32_16x16x32_bf16 v[32:35], v[164:167], v[208:211], v[32:35]
	s_setprio 0
	s_barrier
	s_mov_b64 vcc, 0x1ab0180
	s_mov_b32 m0, s93
	v_lshl_add_u64 v[152:153], v[230:231], 0, vcc
	s_mov_b64 vcc, 0x1b08180
	global_load_lds_dwordx4 v[152:153], off
	v_lshl_add_u64 v[152:153], v[230:231], 0, vcc
	s_mov_b32 m0, s94
	s_nop 0
	global_load_lds_dwordx4 v[152:153], off
	s_waitcnt vmcnt(6)
	s_barrier
	s_setprio 1
	v_mfma_f32_16x16x32_bf16 v[28:31], v[212:215], v[168:171], v[28:31]
	v_mfma_f32_16x16x32_bf16 v[24:27], v[220:223], v[168:171], v[24:27]
	v_mfma_f32_16x16x32_bf16 v[20:23], v[212:215], v[176:179], v[20:23]
	v_mfma_f32_16x16x32_bf16 v[16:19], v[220:223], v[176:179], v[16:19]
	v_mfma_f32_16x16x32_bf16 v[12:15], v[212:215], v[184:187], v[12:15]
	v_mfma_f32_16x16x32_bf16 v[8:11], v[220:223], v[184:187], v[8:11]
	v_mfma_f32_16x16x32_bf16 v[4:7], v[212:215], v[204:207], v[4:7]
	v_mfma_f32_16x16x32_bf16 v[0:3], v[220:223], v[204:207], v[0:3]
	v_mfma_f32_16x16x32_bf16 v[28:31], v[216:219], v[172:175], v[28:31]
	v_mfma_f32_16x16x32_bf16 v[24:27], v[224:227], v[172:175], v[24:27]
	v_mfma_f32_16x16x32_bf16 v[20:23], v[216:219], v[180:183], v[20:23]
	v_mfma_f32_16x16x32_bf16 v[16:19], v[224:227], v[180:183], v[16:19]
	v_mfma_f32_16x16x32_bf16 v[12:15], v[216:219], v[188:191], v[12:15]
	v_mfma_f32_16x16x32_bf16 v[8:11], v[224:227], v[188:191], v[8:11]
	v_mfma_f32_16x16x32_bf16 v[4:7], v[216:219], v[208:211], v[4:7]
	v_mfma_f32_16x16x32_bf16 v[0:3], v[224:227], v[208:211], v[0:3]
	s_setprio 0
	s_add_i32 s95, s95, 2
	s_add_u32 s20, s20, 0x100
	s_addc_u32 s21, s21, 0
	s_add_u32 s22, s22, 0x100
	s_addc_u32 s23, s23, 0
	s_cmp_lt_u32 s95, 40
	s_barrier
	s_cbranch_scc1 .LBB0_424
	v_lshl_add_u64 v[128:129], v[128:129], 1, s[6:7]
	s_mov_b64 s[6:7], 0x1580
	s_mov_b32 m0, s97
	v_lshl_add_u64 v[130:131], v[128:129], 0, s[6:7]
	s_mov_b64 s[6:7], 0x59580
	s_waitcnt vmcnt(0)
	ds_read_b128 v[152:155], v134
	ds_read_b128 v[156:159], v135
	ds_read_b128 v[160:163], v136
	ds_read_b128 v[134:137], v137
	ds_read_b128 v[164:167], v132
	ds_read_b128 v[168:171], v132 offset:1024
	ds_read_b128 v[172:175], v132 offset:2048
	ds_read_b128 v[176:179], v132 offset:3072
	ds_read_b128 v[180:183], v132 offset:4096
	ds_read_b128 v[184:187], v132 offset:5120
	ds_read_b128 v[188:191], v132 offset:6144
	ds_read_b128 v[204:207], v132 offset:7168
	global_load_lds_dwordx4 v[130:131], off
	v_lshl_add_u64 v[128:129], v[128:129], 0, s[6:7]
	s_mov_b32 m0, s96
	s_nop 0
	global_load_lds_dwordx4 v[128:129], off
	s_barrier
	s_waitcnt lgkmcnt(0)
	s_setprio 1
	s_waitcnt lgkmcnt(0)
	v_mfma_f32_16x16x32_bf16 v[124:127], v[152:155], v[164:167], v[124:127]
	v_mfma_f32_16x16x32_bf16 v[120:123], v[160:163], v[164:167], v[120:123]
	v_mfma_f32_16x16x32_bf16 v[116:119], v[152:155], v[172:175], v[116:119]
	v_mfma_f32_16x16x32_bf16 v[112:115], v[160:163], v[172:175], v[112:115]
	v_mfma_f32_16x16x32_bf16 v[108:111], v[152:155], v[180:183], v[108:111]
	v_mfma_f32_16x16x32_bf16 v[104:107], v[160:163], v[180:183], v[104:107]
	v_mfma_f32_16x16x32_bf16 v[100:103], v[152:155], v[188:191], v[100:103]
	v_mfma_f32_16x16x32_bf16 v[96:99], v[160:163], v[188:191], v[96:99]
	v_mfma_f32_16x16x32_bf16 v[124:127], v[156:159], v[168:171], v[124:127]
	v_mfma_f32_16x16x32_bf16 v[120:123], v[134:137], v[168:171], v[120:123]
	v_mfma_f32_16x16x32_bf16 v[116:119], v[156:159], v[176:179], v[116:119]
	v_mfma_f32_16x16x32_bf16 v[112:115], v[134:137], v[176:179], v[112:115]
	v_mfma_f32_16x16x32_bf16 v[108:111], v[156:159], v[184:187], v[108:111]
	v_mfma_f32_16x16x32_bf16 v[104:107], v[134:137], v[184:187], v[104:107]
	v_mfma_f32_16x16x32_bf16 v[100:103], v[156:159], v[204:207], v[100:103]
	v_mfma_f32_16x16x32_bf16 v[96:99], v[134:137], v[204:207], v[96:99]
	s_setprio 0
	s_barrier
	s_waitcnt vmcnt(0)
	ds_read_b128 v[128:131], v138
	ds_read_b128 v[208:211], v139
	ds_read_b128 v[212:215], v140
	ds_read_b128 v[216:219], v142
	s_barrier
; #define LDA8(dst, b, h)                                                                                               \
;   _Pragma("unroll") for (int m = 0; m < 4; ++m) _Pragma("unroll") for (int k = 0; k < 2; ++k)                         \
;     dst[m][k] = *(const bf16x8*)(SA8(b, h) + la + m * 2048 + k * 1024)
; #define LDB8(dst, b, h)                                                                                               \
;   _Pragma("unroll") for (int n = 0; n < 2; ++n) _Pragma("unroll") for (int k = 0; k < 2; ++k)                         \
;     dst[n][k] = *(const bf16x8*)(SB8(b, h) + lb + n * 2048 + k * 1024)
; #define WAITV8(n) asm volatile("s_waitcnt vmcnt(" #n ")" ::: "memory")
; #define WAITL8(n) asm volatile("s_waitcnt lgkmcnt(" #n ")" ::: "memory")
; #define BAR8 __builtin_amdgcn_s_barrier()
; template <class Epi>
; DEV void gemm_tile8(char* shm, const u16* __restrict__ A, const u16* __restrict__ Bt, int K, int brow, int bcol, Epi& epi) {
;     ...
;     BAR8; WAITL8(0); MMA8(0, 0, At, B0); BAR8;
;     LDB8(B1, 0, 1); BAR8; WAITL8(0); MMA8(0, 1, At, B1); BAR8;
;     LDA8(At, 0, 1); WAITV8(4); BAR8; WAITL8(0); MMA8(1, 0, At, B0); MMA8(1, 1, At, B1); BAR8; }
;   { LDB8(B0, 1, 0); LDA8(At, 1, 0); WAITV8(2); BAR8; WAITL8(0); MMA8(0, 0, At, B0); BAR8;
;     LDB8(B1, 1, 1); WAITV8(0); BAR8; WAITL8(0); MMA8(0, 1, At, B1); BAR8;
	s_waitcnt lgkmcnt(0)
	s_setprio 1
	s_waitcnt lgkmcnt(3)
	v_mfma_f32_16x16x32_bf16 v[92:95], v[128:131], v[164:167], v[92:95]
	s_waitcnt lgkmcnt(1)
	v_mfma_f32_16x16x32_bf16 v[88:91], v[212:215], v[164:167], v[88:91]
	v_mfma_f32_16x16x32_bf16 v[84:87], v[128:131], v[172:175], v[84:87]
	v_mfma_f32_16x16x32_bf16 v[80:83], v[212:215], v[172:175], v[80:83]
	v_mfma_f32_16x16x32_bf16 v[76:79], v[128:131], v[180:183], v[76:79]
	v_mfma_f32_16x16x32_bf16 v[72:75], v[212:215], v[180:183], v[72:75]
	v_mfma_f32_16x16x32_bf16 v[68:71], v[128:131], v[188:191], v[68:71]
	v_mfma_f32_16x16x32_bf16 v[64:67], v[212:215], v[188:191], v[64:67]
	v_mfma_f32_16x16x32_bf16 v[220:223], v[208:211], v[168:171], v[92:95]
	s_waitcnt lgkmcnt(0)
	v_mfma_f32_16x16x32_bf16 v[164:167], v[216:219], v[168:171], v[88:91]
	v_mfma_f32_16x16x32_bf16 v[168:171], v[208:211], v[176:179], v[84:87]
	v_mfma_f32_16x16x32_bf16 v[172:175], v[216:219], v[176:179], v[80:83]
	v_mfma_f32_16x16x32_bf16 v[176:179], v[208:211], v[184:187], v[76:79]
	v_mfma_f32_16x16x32_bf16 v[180:183], v[216:219], v[184:187], v[72:75]
	v_mfma_f32_16x16x32_bf16 v[184:187], v[208:211], v[204:207], v[68:71]
	v_mfma_f32_16x16x32_bf16 v[188:191], v[216:219], v[204:207], v[64:67]
	s_setprio 0
	s_barrier
	s_nop 0
	ds_read_b128 v[64:67], v132 offset:16384
	ds_read_b128 v[68:71], v132 offset:17408
	ds_read_b128 v[72:75], v132 offset:18432
	ds_read_b128 v[76:79], v132 offset:19456
	ds_read_b128 v[80:83], v132 offset:20480
	ds_read_b128 v[84:87], v132 offset:21504
	ds_read_b128 v[88:91], v132 offset:22528
	ds_read_b128 v[92:95], v132 offset:23552
	s_waitcnt vmcnt(4)
	s_barrier
	s_waitcnt lgkmcnt(0)
	s_setprio 1
	s_waitcnt lgkmcnt(7)
	v_mfma_f32_16x16x32_bf16 v[60:63], v[152:155], v[64:67], v[60:63]
	v_mfma_f32_16x16x32_bf16 v[56:59], v[160:163], v[64:67], v[56:59]
	s_waitcnt lgkmcnt(5)
	v_mfma_f32_16x16x32_bf16 v[52:55], v[152:155], v[72:75], v[52:55]
	v_mfma_f32_16x16x32_bf16 v[48:51], v[160:163], v[72:75], v[48:51]
	s_waitcnt lgkmcnt(3)
	v_mfma_f32_16x16x32_bf16 v[44:47], v[152:155], v[80:83], v[44:47]
	v_mfma_f32_16x16x32_bf16 v[40:43], v[160:163], v[80:83], v[40:43]
	s_waitcnt lgkmcnt(1)
	v_mfma_f32_16x16x32_bf16 v[36:39], v[152:155], v[88:91], v[36:39]
	v_mfma_f32_16x16x32_bf16 v[32:35], v[160:163], v[88:91], v[32:35]
	v_mfma_f32_16x16x32_bf16 v[60:63], v[156:159], v[68:71], v[60:63]
	v_mfma_f32_16x16x32_bf16 v[56:59], v[134:137], v[68:71], v[56:59]
	v_mfma_f32_16x16x32_bf16 v[52:55], v[156:159], v[76:79], v[52:55]
	v_mfma_f32_16x16x32_bf16 v[48:51], v[134:137], v[76:79], v[48:51]
	v_mfma_f32_16x16x32_bf16 v[44:47], v[156:159], v[84:87], v[44:47]
	v_mfma_f32_16x16x32_bf16 v[40:43], v[134:137], v[84:87], v[40:43]
	s_waitcnt lgkmcnt(0)
	v_mfma_f32_16x16x32_bf16 v[36:39], v[156:159], v[92:95], v[36:39]
	v_mfma_f32_16x16x32_bf16 v[32:35], v[134:137], v[92:95], v[32:35]
	s_setprio 0
	s_setprio 1
	v_mfma_f32_16x16x32_bf16 v[28:31], v[128:131], v[64:67], v[28:31]
	v_mfma_f32_16x16x32_bf16 v[24:27], v[212:215], v[64:67], v[24:27]
	v_mfma_f32_16x16x32_bf16 v[20:23], v[128:131], v[72:75], v[20:23]
	v_mfma_f32_16x16x32_bf16 v[16:19], v[212:215], v[72:75], v[16:19]
	v_mfma_f32_16x16x32_bf16 v[12:15], v[128:131], v[80:83], v[12:15]
	v_mfma_f32_16x16x32_bf16 v[8:11], v[212:215], v[80:83], v[8:11]
	v_mfma_f32_16x16x32_bf16 v[4:7], v[128:131], v[88:91], v[4:7]
	v_mfma_f32_16x16x32_bf16 v[0:3], v[212:215], v[88:91], v[0:3]
	v_mfma_f32_16x16x32_bf16 v[134:137], v[208:211], v[68:71], v[28:31]
	v_mfma_f32_16x16x32_bf16 v[152:155], v[216:219], v[68:71], v[24:27]
	v_mfma_f32_16x16x32_bf16 v[156:159], v[208:211], v[76:79], v[20:23]
	v_mfma_f32_16x16x32_bf16 v[160:163], v[216:219], v[76:79], v[16:19]
	v_mfma_f32_16x16x32_bf16 v[204:207], v[208:211], v[84:87], v[12:15]
	v_mfma_f32_16x16x32_bf16 v[224:227], v[216:219], v[84:87], v[8:11]
	v_mfma_f32_16x16x32_bf16 v[128:131], v[208:211], v[92:95], v[4:7]
	v_mfma_f32_16x16x32_bf16 v[208:211], v[216:219], v[92:95], v[0:3]
	s_setprio 0
	s_barrier
	ds_read_b128 v[24:27], v143
	ds_read_b128 v[28:31], v144
	ds_read_b128 v[142:145], v145
	ds_read_b128 v[212:215], v146
	ds_read_b128 v[0:3], v132 offset:32768
	ds_read_b128 v[4:7], v132 offset:33792
	ds_read_b128 v[8:11], v132 offset:34816
	ds_read_b128 v[12:15], v132 offset:35840
	ds_read_b128 v[16:19], v132 offset:36864
	ds_read_b128 v[20:23], v132 offset:37888
	ds_read_b128 v[216:219], v132 offset:38912
	ds_read_b128 v[228:231], v132 offset:39936
	s_waitcnt vmcnt(2)
	s_barrier
; #define LDA8(dst, b, h)                                                                                               \
;   _Pragma("unroll") for (int m = 0; m < 4; ++m) _Pragma("unroll") for (int k = 0; k < 2; ++k)                         \
;     dst[m][k] = *(const bf16x8*)(SA8(b, h) + la + m * 2048 + k * 1024)
; #define LDB8(dst, b, h)                                                                                               \
;   _Pragma("unroll") for (int n = 0; n < 2; ++n) _Pragma("unroll") for (int k = 0; k < 2; ++k)                         \
;     dst[n][k] = *(const bf16x8*)(SB8(b, h) + lb + n * 2048 + k * 1024)
; #define WAITV8(n) asm volatile("s_waitcnt vmcnt(" #n ")" ::: "memory")
; #define WAITL8(n) asm volatile("s_waitcnt lgkmcnt(" #n ")" ::: "memory")
; #define BAR8 __builtin_amdgcn_s_barrier()
; template <class Epi>
; DEV void gemm_tile8(char* shm, const u16* __restrict__ A, const u16* __restrict__ Bt, int K, int brow, int bcol, Epi& epi) {
;     ...
;   { LDB8(B0, 1, 0); LDA8(At, 1, 0); WAITV8(2); BAR8; WAITL8(0); MMA8(0, 0, At, B0); BAR8;
;     LDB8(B1, 1, 1); WAITV8(0); BAR8; WAITL8(0); MMA8(0, 1, At, B1); BAR8;
;     LDA8(At, 1, 1); BAR8; WAITL8(0); MMA8(1, 0, At, B0); MMA8(1, 1, At, B1); BAR8; }
;   if (wrs == 0) BAR8;
	s_waitcnt lgkmcnt(0)
	s_setprio 1
	s_waitcnt lgkmcnt(7)
	v_mfma_f32_16x16x32_bf16 v[64:67], v[24:27], v[0:3], v[124:127]
	s_waitcnt lgkmcnt(6)
	v_mfma_f32_16x16x32_bf16 v[72:75], v[28:31], v[4:7], v[64:67]
	v_mfma_f32_16x16x32_bf16 v[64:67], v[142:145], v[0:3], v[120:123]
	s_waitcnt lgkmcnt(5)
	v_mfma_f32_16x16x32_bf16 v[68:71], v[24:27], v[8:11], v[116:119]
	v_mfma_f32_16x16x32_bf16 v[76:79], v[142:145], v[8:11], v[112:115]
	s_waitcnt lgkmcnt(3)
	v_mfma_f32_16x16x32_bf16 v[80:83], v[24:27], v[16:19], v[108:111]
	v_mfma_f32_16x16x32_bf16 v[84:87], v[142:145], v[16:19], v[104:107]
	s_waitcnt lgkmcnt(1)
	v_mfma_f32_16x16x32_bf16 v[88:91], v[24:27], v[216:219], v[100:103]
	v_mfma_f32_16x16x32_bf16 v[92:95], v[142:145], v[216:219], v[96:99]
	v_mfma_f32_16x16x32_bf16 v[64:67], v[212:215], v[4:7], v[64:67]
	v_mfma_f32_16x16x32_bf16 v[68:71], v[28:31], v[12:15], v[68:71]
	v_mfma_f32_16x16x32_bf16 v[76:79], v[212:215], v[12:15], v[76:79]
	v_mfma_f32_16x16x32_bf16 v[80:83], v[28:31], v[20:23], v[80:83]
	v_mfma_f32_16x16x32_bf16 v[84:87], v[212:215], v[20:23], v[84:87]
	s_waitcnt lgkmcnt(0)
	v_mfma_f32_16x16x32_bf16 v[88:91], v[28:31], v[228:231], v[88:91]
	v_mfma_f32_16x16x32_bf16 v[92:95], v[212:215], v[228:231], v[92:95]
	s_setprio 0
	s_barrier
	ds_read_b128 v[232:235], v147
	ds_read_b128 v[236:239], v148
	ds_read_b128 v[146:149], v149
	ds_read_b128 v[240:243], v150
	s_waitcnt vmcnt(0)
	s_barrier
	s_waitcnt lgkmcnt(0)
	s_setprio 1
	s_waitcnt lgkmcnt(3)
	v_mfma_f32_16x16x32_bf16 v[96:99], v[232:235], v[0:3], v[220:223]
	s_waitcnt lgkmcnt(1)
	v_mfma_f32_16x16x32_bf16 v[0:3], v[146:149], v[0:3], v[164:167]
	v_mfma_f32_16x16x32_bf16 v[104:107], v[236:239], v[4:7], v[96:99]
	s_waitcnt lgkmcnt(0)
	v_mfma_f32_16x16x32_bf16 v[96:99], v[240:243], v[4:7], v[0:3]
	v_mfma_f32_16x16x32_bf16 v[0:3], v[232:235], v[8:11], v[168:171]
	v_mfma_f32_16x16x32_bf16 v[100:103], v[236:239], v[12:15], v[0:3]
	v_mfma_f32_16x16x32_bf16 v[0:3], v[146:149], v[8:11], v[172:175]
	v_mfma_f32_16x16x32_bf16 v[108:111], v[240:243], v[12:15], v[0:3]
	v_mfma_f32_16x16x32_bf16 v[0:3], v[232:235], v[16:19], v[176:179]
	v_mfma_f32_16x16x32_bf16 v[112:115], v[236:239], v[20:23], v[0:3]
	v_mfma_f32_16x16x32_bf16 v[0:3], v[146:149], v[16:19], v[180:183]
	v_mfma_f32_16x16x32_bf16 v[116:119], v[240:243], v[20:23], v[0:3]
	v_mfma_f32_16x16x32_bf16 v[0:3], v[232:235], v[216:219], v[184:187]
	v_mfma_f32_16x16x32_bf16 v[120:123], v[236:239], v[228:231], v[0:3]
	v_mfma_f32_16x16x32_bf16 v[0:3], v[146:149], v[216:219], v[188:191]
	v_mfma_f32_16x16x32_bf16 v[124:127], v[240:243], v[228:231], v[0:3]
	s_setprio 0
	s_barrier
	ds_read_b128 v[164:167], v132 offset:49152
	ds_read_b128 v[168:171], v132 offset:50176
	ds_read_b128 v[172:175], v132 offset:51200
	ds_read_b128 v[176:179], v132 offset:52224
	ds_read_b128 v[180:183], v132 offset:53248
	ds_read_b128 v[184:187], v132 offset:54272
	ds_read_b128 v[188:191], v132 offset:55296
	ds_read_b128 v[216:219], v132 offset:56320
	s_barrier
	s_waitcnt lgkmcnt(0)
	s_setprio 1
	s_waitcnt lgkmcnt(7)
	v_mfma_f32_16x16x32_bf16 v[0:3], v[24:27], v[164:167], v[60:63]
	s_waitcnt lgkmcnt(5)
	v_mfma_f32_16x16x32_bf16 v[8:11], v[24:27], v[172:175], v[52:55]
	s_waitcnt lgkmcnt(3)
	v_mfma_f32_16x16x32_bf16 v[16:19], v[24:27], v[180:183], v[44:47]
	s_waitcnt lgkmcnt(1)
	v_mfma_f32_16x16x32_bf16 v[24:27], v[24:27], v[188:191], v[36:39]
	v_mfma_f32_16x16x32_bf16 v[0:3], v[28:31], v[168:171], v[0:3]
	v_mfma_f32_16x16x32_bf16 v[4:7], v[142:145], v[164:167], v[56:59]
	v_mfma_f32_16x16x32_bf16 v[8:11], v[28:31], v[176:179], v[8:11]
	v_mfma_f32_16x16x32_bf16 v[12:15], v[142:145], v[172:175], v[48:51]
	v_mfma_f32_16x16x32_bf16 v[16:19], v[28:31], v[184:187], v[16:19]
	v_mfma_f32_16x16x32_bf16 v[20:23], v[142:145], v[180:183], v[40:43]
	s_waitcnt lgkmcnt(0)
	v_mfma_f32_16x16x32_bf16 v[24:27], v[28:31], v[216:219], v[24:27]
	v_mfma_f32_16x16x32_bf16 v[28:31], v[142:145], v[188:191], v[32:35]
	v_mfma_f32_16x16x32_bf16 v[4:7], v[212:215], v[168:171], v[4:7]
	v_mfma_f32_16x16x32_bf16 v[12:15], v[212:215], v[176:179], v[12:15]
	v_mfma_f32_16x16x32_bf16 v[20:23], v[212:215], v[184:187], v[20:23]
	v_mfma_f32_16x16x32_bf16 v[28:31], v[212:215], v[216:219], v[28:31]
	s_setprio 0
	s_setprio 1
	v_mfma_f32_16x16x32_bf16 v[32:35], v[232:235], v[164:167], v[134:137]
	v_mfma_f32_16x16x32_bf16 v[36:39], v[146:149], v[164:167], v[152:155]
	v_mfma_f32_16x16x32_bf16 v[40:43], v[232:235], v[172:175], v[156:159]
	v_mfma_f32_16x16x32_bf16 v[44:47], v[146:149], v[172:175], v[160:163]
	v_mfma_f32_16x16x32_bf16 v[48:51], v[232:235], v[180:183], v[204:207]
	v_mfma_f32_16x16x32_bf16 v[52:55], v[146:149], v[180:183], v[224:227]
	v_mfma_f32_16x16x32_bf16 v[56:59], v[232:235], v[188:191], v[128:131]
	v_mfma_f32_16x16x32_bf16 v[60:63], v[146:149], v[188:191], v[208:211]
	v_mfma_f32_16x16x32_bf16 v[32:35], v[236:239], v[168:171], v[32:35]
	v_mfma_f32_16x16x32_bf16 v[36:39], v[240:243], v[168:171], v[36:39]
	v_mfma_f32_16x16x32_bf16 v[40:43], v[236:239], v[176:179], v[40:43]
	v_mfma_f32_16x16x32_bf16 v[44:47], v[240:243], v[176:179], v[44:47]
	v_mfma_f32_16x16x32_bf16 v[48:51], v[236:239], v[184:187], v[48:51]
	v_mfma_f32_16x16x32_bf16 v[52:55], v[240:243], v[184:187], v[52:55]
	v_mfma_f32_16x16x32_bf16 v[56:59], v[236:239], v[216:219], v[56:59]
	v_mfma_f32_16x16x32_bf16 v[60:63], v[240:243], v[216:219], v[60:63]
	s_setprio 0
	s_cmp_lg_u32 s48, 0
	s_barrier
	s_cbranch_scc1 .LBB0_427
	s_barrier

; #define LDA8(dst, b, h)                                                                                               \
;   _Pragma("unroll") for (int m = 0; m < 4; ++m) _Pragma("unroll") for (int k = 0; k < 2; ++k)                         \
;     dst[m][k] = *(const bf16x8*)(SA8(b, h) + la + m * 2048 + k * 1024)
; #define LDB8(dst, b, h)                                                                                               \
;   _Pragma("unroll") for (int n = 0; n < 2; ++n) _Pragma("unroll") for (int k = 0; k < 2; ++k)                         \
;     dst[n][k] = *(const bf16x8*)(SB8(b, h) + lb + n * 2048 + k * 1024)
; #define WAITL8(n) asm volatile("s_waitcnt lgkmcnt(" #n ")" ::: "memory")
; #define BAR8 __builtin_amdgcn_s_barrier()
; #define SCHED8 __builtin_amdgcn_sched_barrier(0)
; template <class Epi>
; DEV void gemm_tile8(char* shm, const u16* __restrict__ A, const u16* __restrict__ Bt, int K, int brow, int bcol, Epi& epi) {
;     ...
; #pragma unroll 1
;   for (int t = 0; t < nt - 2; t += 2) {
;     LDB8(B0, 0, 0); SCHED8; LDA8(At, 0, 0); STAGE8(SA8(1, 1), A, brow + HALF, t + 1);
;     WAITL8(8); BAR8; WAITL8(0); MMA8(0, 0, At, B0); BAR8; SCHED8;
;     LDB8(B1, 0, 1); STAGE8(SB8(0, 0), Bt, bcol, t + 2);
;     BAR8; WAITL8(0); MMA8(0, 1, At, B1); BAR8;
;     LDA8(At, 0, 1); STAGE8(SA8(0, 0), A, brow, t + 2);
;     BAR8; WAITL8(0); MMA8(1, 0, At, B0); BAR8; SCHED8;
.LBB0_468:
	v_or_b32_e32 v134, 0x10000, v133
	v_add_u32_e32 v136, 0x10800, v133
	v_add_u32_e32 v135, 0x10400, v133
	ds_read_b128 v[144:147], v134
	ds_read_b128 v[148:151], v135
	v_add_u32_e32 v137, 0x10c00, v133
	ds_read_b128 v[152:155], v136
	ds_read_b128 v[156:159], v137
	v_lshl_add_u64 v[228:229], s[10:11], 0, v[130:131]
	s_add_i32 s93, s7, 0xc000
	v_lshl_add_u64 v[138:139], v[228:229], 0, s[96:97]
	s_mov_b32 m0, s93
	s_add_i32 s25, s7, 0xe000
	ds_read_b128 v[160:163], v132
	ds_read_b128 v[164:167], v132 offset:1024
	ds_read_b128 v[168:171], v132 offset:2048
	ds_read_b128 v[172:175], v132 offset:3072
	ds_read_b128 v[176:179], v132 offset:4096
	ds_read_b128 v[180:183], v132 offset:5120
	ds_read_b128 v[184:187], v132 offset:6144
	ds_read_b128 v[188:191], v132 offset:7168
	global_load_lds_dwordx4 v[138:139], off
	v_lshl_add_u64 v[138:139], v[228:229], 0, vcc
	s_mov_b32 m0, s25
	s_nop 0
	global_load_lds_dwordx4 v[138:139], off
	s_waitcnt lgkmcnt(8)
	s_barrier
	s_waitcnt lgkmcnt(0)
	s_setprio 1
	s_waitcnt lgkmcnt(0)
	v_mfma_f32_16x16x32_bf16 v[124:127], v[144:147], v[160:163], v[124:127]
	v_mfma_f32_16x16x32_bf16 v[120:123], v[152:155], v[160:163], v[120:123]
	v_mfma_f32_16x16x32_bf16 v[116:119], v[144:147], v[168:171], v[116:119]
	v_mfma_f32_16x16x32_bf16 v[112:115], v[152:155], v[168:171], v[112:115]
	v_mfma_f32_16x16x32_bf16 v[108:111], v[144:147], v[176:179], v[108:111]
	v_mfma_f32_16x16x32_bf16 v[104:107], v[152:155], v[176:179], v[104:107]
	v_mfma_f32_16x16x32_bf16 v[100:103], v[144:147], v[184:187], v[100:103]
	v_mfma_f32_16x16x32_bf16 v[96:99], v[152:155], v[184:187], v[96:99]
	v_mfma_f32_16x16x32_bf16 v[124:127], v[148:151], v[164:167], v[124:127]
	v_mfma_f32_16x16x32_bf16 v[120:123], v[156:159], v[164:167], v[120:123]
	v_mfma_f32_16x16x32_bf16 v[116:119], v[148:151], v[172:175], v[116:119]
	v_mfma_f32_16x16x32_bf16 v[112:115], v[156:159], v[172:175], v[112:115]
	v_mfma_f32_16x16x32_bf16 v[108:111], v[148:151], v[180:183], v[108:111]
	v_mfma_f32_16x16x32_bf16 v[104:107], v[156:159], v[180:183], v[104:107]
	v_mfma_f32_16x16x32_bf16 v[100:103], v[148:151], v[188:191], v[100:103]
	v_mfma_f32_16x16x32_bf16 v[96:99], v[156:159], v[188:191], v[96:99]
	s_setprio 0
	s_barrier
	v_lshl_add_u64 v[230:231], s[22:23], 0, v[130:131]
	s_mov_b64 s[94:95], 0xf00100
	s_mov_b32 m0, s48
	v_or_b32_e32 v138, 0x14000, v133
	v_add_u32_e32 v140, 0x14800, v133
	v_lshl_add_u64 v[220:221], v[230:231], 0, s[94:95]
	s_mov_b64 s[94:95], 0xf20100
	v_add_u32_e32 v139, 0x14400, v133
	ds_read_b128 v[204:207], v138
	ds_read_b128 v[208:211], v139
	v_add_u32_e32 v142, 0x14c00, v133
	ds_read_b128 v[212:215], v140
	ds_read_b128 v[216:219], v142
	global_load_lds_dwordx4 v[220:221], off
	v_lshl_add_u64 v[220:221], v[230:231], 0, s[94:95]
	s_mov_b32 m0, s54
	s_nop 0
	global_load_lds_dwordx4 v[220:221], off
	s_barrier
	s_waitcnt lgkmcnt(0)
	s_setprio 1
	s_waitcnt lgkmcnt(0)
	v_mfma_f32_16x16x32_bf16 v[92:95], v[204:207], v[160:163], v[92:95]
	v_mfma_f32_16x16x32_bf16 v[88:91], v[212:215], v[160:163], v[88:91]
	v_mfma_f32_16x16x32_bf16 v[84:87], v[204:207], v[168:171], v[84:87]
	v_mfma_f32_16x16x32_bf16 v[80:83], v[212:215], v[168:171], v[80:83]
	v_mfma_f32_16x16x32_bf16 v[76:79], v[204:207], v[176:179], v[76:79]
	v_mfma_f32_16x16x32_bf16 v[72:75], v[212:215], v[176:179], v[72:75]
	v_mfma_f32_16x16x32_bf16 v[68:71], v[204:207], v[184:187], v[68:71]
	v_mfma_f32_16x16x32_bf16 v[64:67], v[212:215], v[184:187], v[64:67]
	v_mfma_f32_16x16x32_bf16 v[92:95], v[208:211], v[164:167], v[92:95]
	v_mfma_f32_16x16x32_bf16 v[88:91], v[216:219], v[164:167], v[88:91]
	v_mfma_f32_16x16x32_bf16 v[84:87], v[208:211], v[172:175], v[84:87]
	v_mfma_f32_16x16x32_bf16 v[80:83], v[216:219], v[172:175], v[80:83]
	v_mfma_f32_16x16x32_bf16 v[76:79], v[208:211], v[180:183], v[76:79]
	v_mfma_f32_16x16x32_bf16 v[72:75], v[216:219], v[180:183], v[72:75]
	v_mfma_f32_16x16x32_bf16 v[68:71], v[208:211], v[188:191], v[68:71]
	v_mfma_f32_16x16x32_bf16 v[64:67], v[216:219], v[188:191], v[64:67]
	s_setprio 0
	s_mov_b32 m0, s7
	v_lshl_add_u64 v[220:221], v[228:229], 0, s[2:3]
	s_barrier
	ds_read_b128 v[160:163], v132 offset:16384
	ds_read_b128 v[164:167], v132 offset:17408
	ds_read_b128 v[168:171], v132 offset:18432
	ds_read_b128 v[172:175], v132 offset:19456
	ds_read_b128 v[176:179], v132 offset:20480
	ds_read_b128 v[180:183], v132 offset:21504
	ds_read_b128 v[184:187], v132 offset:22528
	ds_read_b128 v[188:191], v132 offset:23552
	global_load_lds_dwordx4 v[220:221], off
	v_lshl_add_u64 v[220:221], v[228:229], 0, s[74:75]
	s_mov_b32 m0, s55
	s_nop 0
	global_load_lds_dwordx4 v[220:221], off
	s_barrier
	s_waitcnt lgkmcnt(0)
	s_setprio 1
	s_waitcnt lgkmcnt(0)
	v_mfma_f32_16x16x32_bf16 v[60:63], v[144:147], v[160:163], v[60:63]
	v_mfma_f32_16x16x32_bf16 v[56:59], v[152:155], v[160:163], v[56:59]
	v_mfma_f32_16x16x32_bf16 v[52:55], v[144:147], v[168:171], v[52:55]
	v_mfma_f32_16x16x32_bf16 v[48:51], v[152:155], v[168:171], v[48:51]
	v_mfma_f32_16x16x32_bf16 v[44:47], v[144:147], v[176:179], v[44:47]
	v_mfma_f32_16x16x32_bf16 v[40:43], v[152:155], v[176:179], v[40:43]
	v_mfma_f32_16x16x32_bf16 v[36:39], v[144:147], v[184:187], v[36:39]
	v_mfma_f32_16x16x32_bf16 v[32:35], v[152:155], v[184:187], v[32:35]
	v_mfma_f32_16x16x32_bf16 v[60:63], v[148:151], v[164:167], v[60:63]
	v_mfma_f32_16x16x32_bf16 v[56:59], v[156:159], v[164:167], v[56:59]
	v_mfma_f32_16x16x32_bf16 v[52:55], v[148:151], v[172:175], v[52:55]
	v_mfma_f32_16x16x32_bf16 v[48:51], v[156:159], v[172:175], v[48:51]
	v_mfma_f32_16x16x32_bf16 v[44:47], v[148:151], v[180:183], v[44:47]
	v_mfma_f32_16x16x32_bf16 v[40:43], v[156:159], v[180:183], v[40:43]
	v_mfma_f32_16x16x32_bf16 v[36:39], v[148:151], v[188:191], v[36:39]
	v_mfma_f32_16x16x32_bf16 v[32:35], v[156:159], v[188:191], v[32:35]
	s_setprio 0
	s_barrier
; #define LDA8(dst, b, h)                                                                                               \
;   _Pragma("unroll") for (int m = 0; m < 4; ++m) _Pragma("unroll") for (int k = 0; k < 2; ++k)                         \
;     dst[m][k] = *(const bf16x8*)(SA8(b, h) + la + m * 2048 + k * 1024)
; #define LDB8(dst, b, h)                                                                                               \
;   _Pragma("unroll") for (int n = 0; n < 2; ++n) _Pragma("unroll") for (int k = 0; k < 2; ++k)                         \
;     dst[n][k] = *(const bf16x8*)(SB8(b, h) + lb + n * 2048 + k * 1024)
; #define WAITV8(n) asm volatile("s_waitcnt vmcnt(" #n ")" ::: "memory")
; #define WAITL8(n) asm volatile("s_waitcnt lgkmcnt(" #n ")" ::: "memory")
; #define BAR8 __builtin_amdgcn_s_barrier()
; #define SCHED8 __builtin_amdgcn_sched_barrier(0)
; template <class Epi>
; DEV void gemm_tile8(char* shm, const u16* __restrict__ A, const u16* __restrict__ Bt, int K, int brow, int bcol, Epi& epi) {
;     ...
;     STAGE8(SB8(0, 1), Bt, bcol + HALF, t + 2);
;     WAITV8(6); BAR8; MMA8(1, 1, At, B1); BAR8;
;     LDB8(B0, 1, 0); SCHED8; LDA8(At, 1, 0); STAGE8(SA8(0, 1), A, brow + HALF, t + 2);
;     WAITL8(8); BAR8; WAITL8(0); MMA8(0, 0, At, B0); BAR8; SCHED8;
;     LDB8(B1, 1, 1); STAGE8(SB8(1, 0), Bt, bcol, t + 3);
	s_mov_b64 s[94:95], 0xf40100
	s_mov_b32 m0, s70
	v_lshl_add_u64 v[144:145], v[230:231], 0, s[94:95]
	s_mov_b64 s[94:95], 0xf60100
	global_load_lds_dwordx4 v[144:145], off
	v_lshl_add_u64 v[144:145], v[230:231], 0, s[94:95]
	s_mov_b32 m0, s71
	s_nop 0
	global_load_lds_dwordx4 v[144:145], off
	s_waitcnt vmcnt(6)
	s_barrier
	s_setprio 1
	v_mfma_f32_16x16x32_bf16 v[28:31], v[204:207], v[160:163], v[28:31]
	v_mfma_f32_16x16x32_bf16 v[24:27], v[212:215], v[160:163], v[24:27]
	v_mfma_f32_16x16x32_bf16 v[20:23], v[204:207], v[168:171], v[20:23]
	v_mfma_f32_16x16x32_bf16 v[16:19], v[212:215], v[168:171], v[16:19]
	v_mfma_f32_16x16x32_bf16 v[12:15], v[204:207], v[176:179], v[12:15]
	v_mfma_f32_16x16x32_bf16 v[8:11], v[212:215], v[176:179], v[8:11]
	v_mfma_f32_16x16x32_bf16 v[4:7], v[204:207], v[184:187], v[4:7]
	v_mfma_f32_16x16x32_bf16 v[0:3], v[212:215], v[184:187], v[0:3]
	v_mfma_f32_16x16x32_bf16 v[28:31], v[208:211], v[164:167], v[28:31]
	v_mfma_f32_16x16x32_bf16 v[24:27], v[216:219], v[164:167], v[24:27]
	v_mfma_f32_16x16x32_bf16 v[20:23], v[208:211], v[172:175], v[20:23]
	v_mfma_f32_16x16x32_bf16 v[16:19], v[216:219], v[172:175], v[16:19]
	v_mfma_f32_16x16x32_bf16 v[12:15], v[208:211], v[180:183], v[12:15]
	v_mfma_f32_16x16x32_bf16 v[8:11], v[216:219], v[180:183], v[8:11]
	v_mfma_f32_16x16x32_bf16 v[4:7], v[208:211], v[188:191], v[4:7]
	v_mfma_f32_16x16x32_bf16 v[0:3], v[216:219], v[188:191], v[0:3]
	s_setprio 0
	v_or_b32_e32 v143, 0x18000, v133
	v_add_u32_e32 v145, 0x18800, v133
	s_barrier
	v_add_u32_e32 v144, 0x18400, v133
	ds_read_b128 v[152:155], v143
	ds_read_b128 v[156:159], v144
	v_add_u32_e32 v146, 0x18c00, v133
	ds_read_b128 v[160:163], v145
	ds_read_b128 v[164:167], v146
	s_mov_b32 m0, s72
	v_lshl_add_u64 v[148:149], v[228:229], 0, s[14:15]
	ds_read_b128 v[168:171], v132 offset:32768
	ds_read_b128 v[172:175], v132 offset:33792
	ds_read_b128 v[176:179], v132 offset:34816
	ds_read_b128 v[180:183], v132 offset:35840
	ds_read_b128 v[184:187], v132 offset:36864
	ds_read_b128 v[188:191], v132 offset:37888
	ds_read_b128 v[204:207], v132 offset:38912
	ds_read_b128 v[208:211], v132 offset:39936
	global_load_lds_dwordx4 v[148:149], off
	v_lshl_add_u64 v[148:149], v[228:229], 0, s[16:17]
	s_mov_b32 m0, s73
	s_nop 0
	global_load_lds_dwordx4 v[148:149], off
	s_waitcnt lgkmcnt(8)
	s_barrier
	s_waitcnt lgkmcnt(0)
	s_setprio 1
	s_waitcnt lgkmcnt(0)
	v_mfma_f32_16x16x32_bf16 v[124:127], v[152:155], v[168:171], v[124:127]
	v_mfma_f32_16x16x32_bf16 v[120:123], v[160:163], v[168:171], v[120:123]
	v_mfma_f32_16x16x32_bf16 v[116:119], v[152:155], v[176:179], v[116:119]
	v_mfma_f32_16x16x32_bf16 v[112:115], v[160:163], v[176:179], v[112:115]
	v_mfma_f32_16x16x32_bf16 v[108:111], v[152:155], v[184:187], v[108:111]
	v_mfma_f32_16x16x32_bf16 v[104:107], v[160:163], v[184:187], v[104:107]
	v_mfma_f32_16x16x32_bf16 v[100:103], v[152:155], v[204:207], v[100:103]
	v_mfma_f32_16x16x32_bf16 v[96:99], v[160:163], v[204:207], v[96:99]
	v_mfma_f32_16x16x32_bf16 v[124:127], v[156:159], v[172:175], v[124:127]
	v_mfma_f32_16x16x32_bf16 v[120:123], v[164:167], v[172:175], v[120:123]
	v_mfma_f32_16x16x32_bf16 v[116:119], v[156:159], v[180:183], v[116:119]
	v_mfma_f32_16x16x32_bf16 v[112:115], v[164:167], v[180:183], v[112:115]
	v_mfma_f32_16x16x32_bf16 v[108:111], v[156:159], v[188:191], v[108:111]
	v_mfma_f32_16x16x32_bf16 v[104:107], v[164:167], v[188:191], v[104:107]
	v_mfma_f32_16x16x32_bf16 v[100:103], v[156:159], v[208:211], v[100:103]
	v_mfma_f32_16x16x32_bf16 v[96:99], v[164:167], v[208:211], v[96:99]
	s_setprio 0
	s_barrier
	s_mov_b64 s[94:95], 0xf00180
	s_mov_b32 m0, s81
	v_or_b32_e32 v147, 0x1c000, v133
	v_add_u32_e32 v149, 0x1c800, v133
	v_lshl_add_u64 v[232:233], v[230:231], 0, s[94:95]
	s_mov_b64 s[94:95], 0xf20180
	v_add_u32_e32 v148, 0x1c400, v133
	ds_read_b128 v[212:215], v147
	ds_read_b128 v[216:219], v148
	v_add_u32_e32 v150, 0x1cc00, v133
	ds_read_b128 v[220:223], v149
	ds_read_b128 v[224:227], v150
	global_load_lds_dwordx4 v[232:233], off
	v_lshl_add_u64 v[232:233], v[230:231], 0, s[94:95]
	s_mov_b32 m0, s84
	s_nop 0
	global_load_lds_dwordx4 v[232:233], off
	s_barrier
	s_waitcnt lgkmcnt(0)
	s_setprio 1
	s_waitcnt lgkmcnt(0)
	v_mfma_f32_16x16x32_bf16 v[92:95], v[212:215], v[168:171], v[92:95]
	v_mfma_f32_16x16x32_bf16 v[88:91], v[220:223], v[168:171], v[88:91]
	v_mfma_f32_16x16x32_bf16 v[84:87], v[212:215], v[176:179], v[84:87]
	v_mfma_f32_16x16x32_bf16 v[80:83], v[220:223], v[176:179], v[80:83]
	v_mfma_f32_16x16x32_bf16 v[76:79], v[212:215], v[184:187], v[76:79]
	v_mfma_f32_16x16x32_bf16 v[72:75], v[220:223], v[184:187], v[72:75]
	v_mfma_f32_16x16x32_bf16 v[68:71], v[212:215], v[204:207], v[68:71]
	v_mfma_f32_16x16x32_bf16 v[64:67], v[220:223], v[204:207], v[64:67]
	v_mfma_f32_16x16x32_bf16 v[92:95], v[216:219], v[172:175], v[92:95]
	v_mfma_f32_16x16x32_bf16 v[88:91], v[224:227], v[172:175], v[88:91]
	v_mfma_f32_16x16x32_bf16 v[84:87], v[216:219], v[180:183], v[84:87]
	v_mfma_f32_16x16x32_bf16 v[80:83], v[224:227], v[180:183], v[80:83]
	v_mfma_f32_16x16x32_bf16 v[76:79], v[216:219], v[188:191], v[76:79]
	v_mfma_f32_16x16x32_bf16 v[72:75], v[224:227], v[188:191], v[72:75]
	v_mfma_f32_16x16x32_bf16 v[68:71], v[216:219], v[208:211], v[68:71]
	v_mfma_f32_16x16x32_bf16 v[64:67], v[224:227], v[208:211], v[64:67]
	s_setprio 0
	s_mov_b32 m0, s85
	v_lshl_add_u64 v[232:233], v[228:229], 0, s[64:65]
	s_barrier
; #define LDA8(dst, b, h)                                                                                               \
;   _Pragma("unroll") for (int m = 0; m < 4; ++m) _Pragma("unroll") for (int k = 0; k < 2; ++k)                         \
;     dst[m][k] = *(const bf16x8*)(SA8(b, h) + la + m * 2048 + k * 1024)
; #define LDB8(dst, b, h)                                                                                               \
;   _Pragma("unroll") for (int n = 0; n < 2; ++n) _Pragma("unroll") for (int k = 0; k < 2; ++k)                         \
;     dst[n][k] = *(const bf16x8*)(SB8(b, h) + lb + n * 2048 + k * 1024)
; #define WAITV8(n) asm volatile("s_waitcnt vmcnt(" #n ")" ::: "memory")
; #define WAITL8(n) asm volatile("s_waitcnt lgkmcnt(" #n ")" ::: "memory")
; #define BAR8 __builtin_amdgcn_s_barrier()
; #define SCHED8 __builtin_amdgcn_sched_barrier(0)
; template <class Epi>
; DEV void gemm_tile8(char* shm, const u16* __restrict__ A, const u16* __restrict__ Bt, int K, int brow, int bcol, Epi& epi) {
;     ...
;     BAR8; WAITL8(0); MMA8(0, 1, At, B1); BAR8;
;     LDA8(At, 1, 1); STAGE8(SA8(1, 0), A, brow, t + 3);
;     BAR8; WAITL8(0); MMA8(1, 0, At, B0); BAR8; SCHED8;
;     STAGE8(SB8(1, 1), Bt, bcol + HALF, t + 3);
;     WAITV8(6); BAR8; MMA8(1, 1, At, B1); BAR8;
;   }
;   { LDB8(B0, 0, 0); LDA8(At, 0, 0); STAGE8(SA8(1, 1), A, brow + HALF, nt - 1);
;     BAR8; WAITL8(0); MMA8(0, 0, At, B0); BAR8;
	ds_read_b128 v[168:171], v132 offset:49152
	ds_read_b128 v[172:175], v132 offset:50176
	ds_read_b128 v[176:179], v132 offset:51200
	ds_read_b128 v[180:183], v132 offset:52224
	ds_read_b128 v[184:187], v132 offset:53248
	ds_read_b128 v[188:191], v132 offset:54272
	ds_read_b128 v[204:207], v132 offset:55296
	ds_read_b128 v[208:211], v132 offset:56320
	global_load_lds_dwordx4 v[232:233], off
	v_lshl_add_u64 v[228:229], v[228:229], 0, s[82:83]
	s_mov_b32 m0, s90
	s_nop 0
	global_load_lds_dwordx4 v[228:229], off
	s_barrier
	s_waitcnt lgkmcnt(0)
	s_setprio 1
	s_waitcnt lgkmcnt(0)
	v_mfma_f32_16x16x32_bf16 v[60:63], v[152:155], v[168:171], v[60:63]
	v_mfma_f32_16x16x32_bf16 v[56:59], v[160:163], v[168:171], v[56:59]
	v_mfma_f32_16x16x32_bf16 v[52:55], v[152:155], v[176:179], v[52:55]
	v_mfma_f32_16x16x32_bf16 v[48:51], v[160:163], v[176:179], v[48:51]
	v_mfma_f32_16x16x32_bf16 v[44:47], v[152:155], v[184:187], v[44:47]
	v_mfma_f32_16x16x32_bf16 v[40:43], v[160:163], v[184:187], v[40:43]
	v_mfma_f32_16x16x32_bf16 v[36:39], v[152:155], v[204:207], v[36:39]
	v_mfma_f32_16x16x32_bf16 v[32:35], v[160:163], v[204:207], v[32:35]
	v_mfma_f32_16x16x32_bf16 v[60:63], v[156:159], v[172:175], v[60:63]
	v_mfma_f32_16x16x32_bf16 v[56:59], v[164:167], v[172:175], v[56:59]
	v_mfma_f32_16x16x32_bf16 v[52:55], v[156:159], v[180:183], v[52:55]
	v_mfma_f32_16x16x32_bf16 v[48:51], v[164:167], v[180:183], v[48:51]
	v_mfma_f32_16x16x32_bf16 v[44:47], v[156:159], v[188:191], v[44:47]
	v_mfma_f32_16x16x32_bf16 v[40:43], v[164:167], v[188:191], v[40:43]
	v_mfma_f32_16x16x32_bf16 v[36:39], v[156:159], v[208:211], v[36:39]
	v_mfma_f32_16x16x32_bf16 v[32:35], v[164:167], v[208:211], v[32:35]
	s_setprio 0
	s_barrier
	s_mov_b64 s[94:95], 0xf40180
	s_mov_b32 m0, s91
	v_lshl_add_u64 v[152:153], v[230:231], 0, s[94:95]
	s_mov_b64 s[94:95], 0xf60180
	global_load_lds_dwordx4 v[152:153], off
	v_lshl_add_u64 v[152:153], v[230:231], 0, s[94:95]
	s_mov_b32 m0, s92
	s_nop 0
	global_load_lds_dwordx4 v[152:153], off
	s_waitcnt vmcnt(6)
	s_barrier
	s_setprio 1
	v_mfma_f32_16x16x32_bf16 v[28:31], v[212:215], v[168:171], v[28:31]
	v_mfma_f32_16x16x32_bf16 v[24:27], v[220:223], v[168:171], v[24:27]
	v_mfma_f32_16x16x32_bf16 v[20:23], v[212:215], v[176:179], v[20:23]
	v_mfma_f32_16x16x32_bf16 v[16:19], v[220:223], v[176:179], v[16:19]
	v_mfma_f32_16x16x32_bf16 v[12:15], v[212:215], v[184:187], v[12:15]
	v_mfma_f32_16x16x32_bf16 v[8:11], v[220:223], v[184:187], v[8:11]
	v_mfma_f32_16x16x32_bf16 v[4:7], v[212:215], v[204:207], v[4:7]
	v_mfma_f32_16x16x32_bf16 v[0:3], v[220:223], v[204:207], v[0:3]
	v_mfma_f32_16x16x32_bf16 v[28:31], v[216:219], v[172:175], v[28:31]
	v_mfma_f32_16x16x32_bf16 v[24:27], v[224:227], v[172:175], v[24:27]
	v_mfma_f32_16x16x32_bf16 v[20:23], v[216:219], v[180:183], v[20:23]
	v_mfma_f32_16x16x32_bf16 v[16:19], v[224:227], v[180:183], v[16:19]
	v_mfma_f32_16x16x32_bf16 v[12:15], v[216:219], v[188:191], v[12:15]
	v_mfma_f32_16x16x32_bf16 v[8:11], v[224:227], v[188:191], v[8:11]
	v_mfma_f32_16x16x32_bf16 v[4:7], v[216:219], v[208:211], v[4:7]
	v_mfma_f32_16x16x32_bf16 v[0:3], v[224:227], v[208:211], v[0:3]
	s_setprio 0
	s_add_i32 s24, s24, 2
	s_add_u32 s10, s10, 0x100
	s_addc_u32 s11, s11, 0
	s_add_u32 s22, s22, 0x100
	s_addc_u32 s23, s23, 0
	s_cmp_lt_u32 s24, 12
	s_barrier
	s_cbranch_scc1 .LBB0_468
	s_mov_b64 s[10:11], 0x780
	s_mov_b32 m0, s93
	v_lshl_add_u64 v[130:131], v[128:129], 0, s[10:11]
	s_mov_b64 s[10:11], 0x20780
	s_waitcnt vmcnt(0)
	ds_read_b128 v[152:155], v134
	ds_read_b128 v[156:159], v135
	ds_read_b128 v[160:163], v136
	ds_read_b128 v[134:137], v137
	ds_read_b128 v[164:167], v132
	ds_read_b128 v[168:171], v132 offset:1024
	ds_read_b128 v[172:175], v132 offset:2048
	ds_read_b128 v[176:179], v132 offset:3072
	ds_read_b128 v[180:183], v132 offset:4096
	ds_read_b128 v[184:187], v132 offset:5120
	ds_read_b128 v[188:191], v132 offset:6144
	ds_read_b128 v[204:207], v132 offset:7168
	global_load_lds_dwordx4 v[130:131], off
	v_lshl_add_u64 v[128:129], v[128:129], 0, s[10:11]
	s_mov_b32 m0, s25
	s_nop 0
	global_load_lds_dwordx4 v[128:129], off
	s_barrier
	s_waitcnt lgkmcnt(0)
	s_setprio 1
	s_waitcnt lgkmcnt(0)
	v_mfma_f32_16x16x32_bf16 v[124:127], v[152:155], v[164:167], v[124:127]
	v_mfma_f32_16x16x32_bf16 v[120:123], v[160:163], v[164:167], v[120:123]
	v_mfma_f32_16x16x32_bf16 v[116:119], v[152:155], v[172:175], v[116:119]
	v_mfma_f32_16x16x32_bf16 v[112:115], v[160:163], v[172:175], v[112:115]
	v_mfma_f32_16x16x32_bf16 v[108:111], v[152:155], v[180:183], v[108:111]
	v_mfma_f32_16x16x32_bf16 v[104:107], v[160:163], v[180:183], v[104:107]
	v_mfma_f32_16x16x32_bf16 v[100:103], v[152:155], v[188:191], v[100:103]
	v_mfma_f32_16x16x32_bf16 v[96:99], v[160:163], v[188:191], v[96:99]
	v_mfma_f32_16x16x32_bf16 v[124:127], v[156:159], v[168:171], v[124:127]
	v_mfma_f32_16x16x32_bf16 v[120:123], v[134:137], v[168:171], v[120:123]
	v_mfma_f32_16x16x32_bf16 v[116:119], v[156:159], v[176:179], v[116:119]
	v_mfma_f32_16x16x32_bf16 v[112:115], v[134:137], v[176:179], v[112:115]
	v_mfma_f32_16x16x32_bf16 v[108:111], v[156:159], v[184:187], v[108:111]
	v_mfma_f32_16x16x32_bf16 v[104:107], v[134:137], v[184:187], v[104:107]
	v_mfma_f32_16x16x32_bf16 v[100:103], v[156:159], v[204:207], v[100:103]
	v_mfma_f32_16x16x32_bf16 v[96:99], v[134:137], v[204:207], v[96:99]
	s_setprio 0
	s_barrier
	s_waitcnt vmcnt(0)
	ds_read_b128 v[128:131], v138
	ds_read_b128 v[208:211], v139
	ds_read_b128 v[212:215], v140
	ds_read_b128 v[216:219], v142
	s_barrier
; #define LDA8(dst, b, h)                                                                                               \
;   _Pragma("unroll") for (int m = 0; m < 4; ++m) _Pragma("unroll") for (int k = 0; k < 2; ++k)                         \
;     dst[m][k] = *(const bf16x8*)(SA8(b, h) + la + m * 2048 + k * 1024)
; #define LDB8(dst, b, h)                                                                                               \
;   _Pragma("unroll") for (int n = 0; n < 2; ++n) _Pragma("unroll") for (int k = 0; k < 2; ++k)                         \
;     dst[n][k] = *(const bf16x8*)(SB8(b, h) + lb + n * 2048 + k * 1024)
; #define WAITV8(n) asm volatile("s_waitcnt vmcnt(" #n ")" ::: "memory")
; #define WAITL8(n) asm volatile("s_waitcnt lgkmcnt(" #n ")" ::: "memory")
; #define BAR8 __builtin_amdgcn_s_barrier()
; template <class Epi>
; DEV void gemm_tile8(char* shm, const u16* __restrict__ A, const u16* __restrict__ Bt, int K, int brow, int bcol, Epi& epi) {
;     ...
;     BAR8; WAITL8(0); MMA8(0, 0, At, B0); BAR8;
;     LDB8(B1, 0, 1); BAR8; WAITL8(0); MMA8(0, 1, At, B1); BAR8;
;     LDA8(At, 0, 1); WAITV8(4); BAR8; WAITL8(0); MMA8(1, 0, At, B0); MMA8(1, 1, At, B1); BAR8; }
;   { LDB8(B0, 1, 0); LDA8(At, 1, 0); WAITV8(2); BAR8; WAITL8(0); MMA8(0, 0, At, B0); BAR8;
;     LDB8(B1, 1, 1); WAITV8(0); BAR8; WAITL8(0); MMA8(0, 1, At, B1); BAR8;
	s_waitcnt lgkmcnt(0)
	s_setprio 1
	s_waitcnt lgkmcnt(3)
	v_mfma_f32_16x16x32_bf16 v[92:95], v[128:131], v[164:167], v[92:95]
	s_waitcnt lgkmcnt(1)
	v_mfma_f32_16x16x32_bf16 v[88:91], v[212:215], v[164:167], v[88:91]
	v_mfma_f32_16x16x32_bf16 v[84:87], v[128:131], v[172:175], v[84:87]
	v_mfma_f32_16x16x32_bf16 v[80:83], v[212:215], v[172:175], v[80:83]
	v_mfma_f32_16x16x32_bf16 v[76:79], v[128:131], v[180:183], v[76:79]
	v_mfma_f32_16x16x32_bf16 v[72:75], v[212:215], v[180:183], v[72:75]
	v_mfma_f32_16x16x32_bf16 v[68:71], v[128:131], v[188:191], v[68:71]
	v_mfma_f32_16x16x32_bf16 v[64:67], v[212:215], v[188:191], v[64:67]
	v_mfma_f32_16x16x32_bf16 v[220:223], v[208:211], v[168:171], v[92:95]
	s_waitcnt lgkmcnt(0)
	v_mfma_f32_16x16x32_bf16 v[164:167], v[216:219], v[168:171], v[88:91]
	v_mfma_f32_16x16x32_bf16 v[168:171], v[208:211], v[176:179], v[84:87]
	v_mfma_f32_16x16x32_bf16 v[172:175], v[216:219], v[176:179], v[80:83]
	v_mfma_f32_16x16x32_bf16 v[176:179], v[208:211], v[184:187], v[76:79]
	v_mfma_f32_16x16x32_bf16 v[180:183], v[216:219], v[184:187], v[72:75]
	v_mfma_f32_16x16x32_bf16 v[184:187], v[208:211], v[204:207], v[68:71]
	v_mfma_f32_16x16x32_bf16 v[188:191], v[216:219], v[204:207], v[64:67]
	s_setprio 0
	s_barrier
	s_nop 0
	ds_read_b128 v[64:67], v132 offset:16384
	ds_read_b128 v[68:71], v132 offset:17408
	ds_read_b128 v[72:75], v132 offset:18432
	ds_read_b128 v[76:79], v132 offset:19456
	ds_read_b128 v[80:83], v132 offset:20480
	ds_read_b128 v[84:87], v132 offset:21504
	ds_read_b128 v[88:91], v132 offset:22528
	ds_read_b128 v[92:95], v132 offset:23552
	s_waitcnt vmcnt(4)
	s_barrier
	s_waitcnt lgkmcnt(0)
	s_setprio 1
	s_waitcnt lgkmcnt(7)
	v_mfma_f32_16x16x32_bf16 v[60:63], v[152:155], v[64:67], v[60:63]
	v_mfma_f32_16x16x32_bf16 v[56:59], v[160:163], v[64:67], v[56:59]
	s_waitcnt lgkmcnt(5)
	v_mfma_f32_16x16x32_bf16 v[52:55], v[152:155], v[72:75], v[52:55]
	v_mfma_f32_16x16x32_bf16 v[48:51], v[160:163], v[72:75], v[48:51]
	s_waitcnt lgkmcnt(3)
	v_mfma_f32_16x16x32_bf16 v[44:47], v[152:155], v[80:83], v[44:47]
	v_mfma_f32_16x16x32_bf16 v[40:43], v[160:163], v[80:83], v[40:43]
	s_waitcnt lgkmcnt(1)
	v_mfma_f32_16x16x32_bf16 v[36:39], v[152:155], v[88:91], v[36:39]
	v_mfma_f32_16x16x32_bf16 v[32:35], v[160:163], v[88:91], v[32:35]
	v_mfma_f32_16x16x32_bf16 v[60:63], v[156:159], v[68:71], v[60:63]
	v_mfma_f32_16x16x32_bf16 v[56:59], v[134:137], v[68:71], v[56:59]
	v_mfma_f32_16x16x32_bf16 v[52:55], v[156:159], v[76:79], v[52:55]
	v_mfma_f32_16x16x32_bf16 v[48:51], v[134:137], v[76:79], v[48:51]
	v_mfma_f32_16x16x32_bf16 v[44:47], v[156:159], v[84:87], v[44:47]
	v_mfma_f32_16x16x32_bf16 v[40:43], v[134:137], v[84:87], v[40:43]
	s_waitcnt lgkmcnt(0)
	v_mfma_f32_16x16x32_bf16 v[36:39], v[156:159], v[92:95], v[36:39]
	v_mfma_f32_16x16x32_bf16 v[32:35], v[134:137], v[92:95], v[32:35]
	s_setprio 0
	s_setprio 1
	v_mfma_f32_16x16x32_bf16 v[28:31], v[128:131], v[64:67], v[28:31]
	v_mfma_f32_16x16x32_bf16 v[24:27], v[212:215], v[64:67], v[24:27]
	v_mfma_f32_16x16x32_bf16 v[20:23], v[128:131], v[72:75], v[20:23]
	v_mfma_f32_16x16x32_bf16 v[16:19], v[212:215], v[72:75], v[16:19]
	v_mfma_f32_16x16x32_bf16 v[12:15], v[128:131], v[80:83], v[12:15]
	v_mfma_f32_16x16x32_bf16 v[8:11], v[212:215], v[80:83], v[8:11]
	v_mfma_f32_16x16x32_bf16 v[4:7], v[128:131], v[88:91], v[4:7]
	v_mfma_f32_16x16x32_bf16 v[0:3], v[212:215], v[88:91], v[0:3]
	v_mfma_f32_16x16x32_bf16 v[134:137], v[208:211], v[68:71], v[28:31]
	v_mfma_f32_16x16x32_bf16 v[152:155], v[216:219], v[68:71], v[24:27]
	v_mfma_f32_16x16x32_bf16 v[156:159], v[208:211], v[76:79], v[20:23]
	v_mfma_f32_16x16x32_bf16 v[160:163], v[216:219], v[76:79], v[16:19]
	v_mfma_f32_16x16x32_bf16 v[204:207], v[208:211], v[84:87], v[12:15]
	v_mfma_f32_16x16x32_bf16 v[224:227], v[216:219], v[84:87], v[8:11]
	v_mfma_f32_16x16x32_bf16 v[128:131], v[208:211], v[92:95], v[4:7]
	v_mfma_f32_16x16x32_bf16 v[208:211], v[216:219], v[92:95], v[0:3]
	s_setprio 0
	s_barrier
	ds_read_b128 v[24:27], v143
	ds_read_b128 v[28:31], v144
	ds_read_b128 v[142:145], v145
	ds_read_b128 v[212:215], v146
	ds_read_b128 v[0:3], v132 offset:32768
	ds_read_b128 v[4:7], v132 offset:33792
	ds_read_b128 v[8:11], v132 offset:34816
	ds_read_b128 v[12:15], v132 offset:35840
	ds_read_b128 v[16:19], v132 offset:36864
	ds_read_b128 v[20:23], v132 offset:37888
	ds_read_b128 v[216:219], v132 offset:38912
	ds_read_b128 v[228:231], v132 offset:39936
	s_waitcnt vmcnt(2)
	s_barrier
; #define LDA8(dst, b, h)                                                                                               \
;   _Pragma("unroll") for (int m = 0; m < 4; ++m) _Pragma("unroll") for (int k = 0; k < 2; ++k)                         \
;     dst[m][k] = *(const bf16x8*)(SA8(b, h) + la + m * 2048 + k * 1024)
; #define LDB8(dst, b, h)                                                                                               \
;   _Pragma("unroll") for (int n = 0; n < 2; ++n) _Pragma("unroll") for (int k = 0; k < 2; ++k)                         \
;     dst[n][k] = *(const bf16x8*)(SB8(b, h) + lb + n * 2048 + k * 1024)
; #define WAITV8(n) asm volatile("s_waitcnt vmcnt(" #n ")" ::: "memory")
; #define WAITL8(n) asm volatile("s_waitcnt lgkmcnt(" #n ")" ::: "memory")
; #define BAR8 __builtin_amdgcn_s_barrier()
; template <class Epi>
; DEV void gemm_tile8(char* shm, const u16* __restrict__ A, const u16* __restrict__ Bt, int K, int brow, int bcol, Epi& epi) {
;     ...
;   { LDB8(B0, 1, 0); LDA8(At, 1, 0); WAITV8(2); BAR8; WAITL8(0); MMA8(0, 0, At, B0); BAR8;
;     LDB8(B1, 1, 1); WAITV8(0); BAR8; WAITL8(0); MMA8(0, 1, At, B1); BAR8;
;     LDA8(At, 1, 1); BAR8; WAITL8(0); MMA8(1, 0, At, B0); MMA8(1, 1, At, B1); BAR8; }
;   if (wrs == 0) BAR8;
	s_waitcnt lgkmcnt(0)
	s_setprio 1
	s_waitcnt lgkmcnt(7)
	v_mfma_f32_16x16x32_bf16 v[64:67], v[24:27], v[0:3], v[124:127]
	s_waitcnt lgkmcnt(6)
	v_mfma_f32_16x16x32_bf16 v[72:75], v[28:31], v[4:7], v[64:67]
	v_mfma_f32_16x16x32_bf16 v[64:67], v[142:145], v[0:3], v[120:123]
	s_waitcnt lgkmcnt(5)
	v_mfma_f32_16x16x32_bf16 v[68:71], v[24:27], v[8:11], v[116:119]
	v_mfma_f32_16x16x32_bf16 v[76:79], v[142:145], v[8:11], v[112:115]
	s_waitcnt lgkmcnt(3)
	v_mfma_f32_16x16x32_bf16 v[80:83], v[24:27], v[16:19], v[108:111]
	v_mfma_f32_16x16x32_bf16 v[84:87], v[142:145], v[16:19], v[104:107]
	s_waitcnt lgkmcnt(1)
	v_mfma_f32_16x16x32_bf16 v[88:91], v[24:27], v[216:219], v[100:103]
	v_mfma_f32_16x16x32_bf16 v[92:95], v[142:145], v[216:219], v[96:99]
	v_mfma_f32_16x16x32_bf16 v[64:67], v[212:215], v[4:7], v[64:67]
	v_mfma_f32_16x16x32_bf16 v[68:71], v[28:31], v[12:15], v[68:71]
	v_mfma_f32_16x16x32_bf16 v[76:79], v[212:215], v[12:15], v[76:79]
	v_mfma_f32_16x16x32_bf16 v[80:83], v[28:31], v[20:23], v[80:83]
	v_mfma_f32_16x16x32_bf16 v[84:87], v[212:215], v[20:23], v[84:87]
	s_waitcnt lgkmcnt(0)
	v_mfma_f32_16x16x32_bf16 v[88:91], v[28:31], v[228:231], v[88:91]
	v_mfma_f32_16x16x32_bf16 v[92:95], v[212:215], v[228:231], v[92:95]
	s_setprio 0
	s_barrier
	ds_read_b128 v[232:235], v147
	ds_read_b128 v[236:239], v148
	ds_read_b128 v[146:149], v149
	ds_read_b128 v[240:243], v150
	s_waitcnt vmcnt(0)
	s_barrier
	s_waitcnt lgkmcnt(0)
	s_setprio 1
	s_waitcnt lgkmcnt(3)
	v_mfma_f32_16x16x32_bf16 v[96:99], v[232:235], v[0:3], v[220:223]
	s_waitcnt lgkmcnt(1)
	v_mfma_f32_16x16x32_bf16 v[0:3], v[146:149], v[0:3], v[164:167]
	v_mfma_f32_16x16x32_bf16 v[104:107], v[236:239], v[4:7], v[96:99]
	s_waitcnt lgkmcnt(0)
	v_mfma_f32_16x16x32_bf16 v[96:99], v[240:243], v[4:7], v[0:3]
	v_mfma_f32_16x16x32_bf16 v[0:3], v[232:235], v[8:11], v[168:171]
	v_mfma_f32_16x16x32_bf16 v[100:103], v[236:239], v[12:15], v[0:3]
	v_mfma_f32_16x16x32_bf16 v[0:3], v[146:149], v[8:11], v[172:175]
	v_mfma_f32_16x16x32_bf16 v[108:111], v[240:243], v[12:15], v[0:3]
	v_mfma_f32_16x16x32_bf16 v[0:3], v[232:235], v[16:19], v[176:179]
	v_mfma_f32_16x16x32_bf16 v[112:115], v[236:239], v[20:23], v[0:3]
	v_mfma_f32_16x16x32_bf16 v[0:3], v[146:149], v[16:19], v[180:183]
	v_mfma_f32_16x16x32_bf16 v[116:119], v[240:243], v[20:23], v[0:3]
	v_mfma_f32_16x16x32_bf16 v[0:3], v[232:235], v[216:219], v[184:187]
	v_mfma_f32_16x16x32_bf16 v[120:123], v[236:239], v[228:231], v[0:3]
	v_mfma_f32_16x16x32_bf16 v[0:3], v[146:149], v[216:219], v[188:191]
	v_mfma_f32_16x16x32_bf16 v[124:127], v[240:243], v[228:231], v[0:3]
	s_setprio 0
	s_barrier
	ds_read_b128 v[164:167], v132 offset:49152
	ds_read_b128 v[168:171], v132 offset:50176
	ds_read_b128 v[172:175], v132 offset:51200
	ds_read_b128 v[176:179], v132 offset:52224
	ds_read_b128 v[180:183], v132 offset:53248
	ds_read_b128 v[184:187], v132 offset:54272
	ds_read_b128 v[188:191], v132 offset:55296
	ds_read_b128 v[216:219], v132 offset:56320
	s_barrier
	s_waitcnt lgkmcnt(0)
	s_setprio 1
	s_waitcnt lgkmcnt(7)
	v_mfma_f32_16x16x32_bf16 v[0:3], v[24:27], v[164:167], v[60:63]
	s_waitcnt lgkmcnt(5)
	v_mfma_f32_16x16x32_bf16 v[8:11], v[24:27], v[172:175], v[52:55]
	s_waitcnt lgkmcnt(3)
	v_mfma_f32_16x16x32_bf16 v[16:19], v[24:27], v[180:183], v[44:47]
	s_waitcnt lgkmcnt(1)
	v_mfma_f32_16x16x32_bf16 v[24:27], v[24:27], v[188:191], v[36:39]
	v_mfma_f32_16x16x32_bf16 v[0:3], v[28:31], v[168:171], v[0:3]
	v_mfma_f32_16x16x32_bf16 v[4:7], v[142:145], v[164:167], v[56:59]
	v_mfma_f32_16x16x32_bf16 v[8:11], v[28:31], v[176:179], v[8:11]
	v_mfma_f32_16x16x32_bf16 v[12:15], v[142:145], v[172:175], v[48:51]
	v_mfma_f32_16x16x32_bf16 v[16:19], v[28:31], v[184:187], v[16:19]
	v_mfma_f32_16x16x32_bf16 v[20:23], v[142:145], v[180:183], v[40:43]
	s_waitcnt lgkmcnt(0)
	v_mfma_f32_16x16x32_bf16 v[24:27], v[28:31], v[216:219], v[24:27]
	v_mfma_f32_16x16x32_bf16 v[28:31], v[142:145], v[188:191], v[32:35]
	v_mfma_f32_16x16x32_bf16 v[4:7], v[212:215], v[168:171], v[4:7]
	v_mfma_f32_16x16x32_bf16 v[12:15], v[212:215], v[176:179], v[12:15]
	v_mfma_f32_16x16x32_bf16 v[20:23], v[212:215], v[184:187], v[20:23]
	v_mfma_f32_16x16x32_bf16 v[28:31], v[212:215], v[216:219], v[28:31]
	s_setprio 0
	s_setprio 1
	v_mfma_f32_16x16x32_bf16 v[32:35], v[232:235], v[164:167], v[134:137]
	v_mfma_f32_16x16x32_bf16 v[36:39], v[146:149], v[164:167], v[152:155]
	v_mfma_f32_16x16x32_bf16 v[40:43], v[232:235], v[172:175], v[156:159]
	v_mfma_f32_16x16x32_bf16 v[44:47], v[146:149], v[172:175], v[160:163]
	v_mfma_f32_16x16x32_bf16 v[48:51], v[232:235], v[180:183], v[204:207]
	v_mfma_f32_16x16x32_bf16 v[52:55], v[146:149], v[180:183], v[224:227]
	v_mfma_f32_16x16x32_bf16 v[56:59], v[232:235], v[188:191], v[128:131]
	v_mfma_f32_16x16x32_bf16 v[60:63], v[146:149], v[188:191], v[208:211]
	v_mfma_f32_16x16x32_bf16 v[32:35], v[236:239], v[168:171], v[32:35]
	v_mfma_f32_16x16x32_bf16 v[36:39], v[240:243], v[168:171], v[36:39]
	v_mfma_f32_16x16x32_bf16 v[40:43], v[236:239], v[176:179], v[40:43]
	v_mfma_f32_16x16x32_bf16 v[44:47], v[240:243], v[176:179], v[44:47]
	v_mfma_f32_16x16x32_bf16 v[48:51], v[236:239], v[184:187], v[48:51]
	v_mfma_f32_16x16x32_bf16 v[52:55], v[240:243], v[184:187], v[52:55]
	v_mfma_f32_16x16x32_bf16 v[56:59], v[236:239], v[216:219], v[56:59]
	v_mfma_f32_16x16x32_bf16 v[60:63], v[240:243], v[216:219], v[60:63]
	s_setprio 0
	s_cmp_lg_u32 s45, 0
	s_barrier
	s_cbranch_scc1 .LBB0_471
	s_barrier

; #define LDA8(dst, b, h)                                                                                               \
;   _Pragma("unroll") for (int m = 0; m < 4; ++m) _Pragma("unroll") for (int k = 0; k < 2; ++k)                         \
;     dst[m][k] = *(const bf16x8*)(SA8(b, h) + la + m * 2048 + k * 1024)
; #define LDB8(dst, b, h)                                                                                               \
;   _Pragma("unroll") for (int n = 0; n < 2; ++n) _Pragma("unroll") for (int k = 0; k < 2; ++k)                         \
;     dst[n][k] = *(const bf16x8*)(SB8(b, h) + lb + n * 2048 + k * 1024)
; #define WAITL8(n) asm volatile("s_waitcnt lgkmcnt(" #n ")" ::: "memory")
; #define BAR8 __builtin_amdgcn_s_barrier()
; #define SCHED8 __builtin_amdgcn_sched_barrier(0)
; template <class Epi>
; DEV void gemm_tile8(char* shm, const u16* __restrict__ A, const u16* __restrict__ Bt, int K, int brow, int bcol, Epi& epi) {
;     ...
; #pragma unroll 1
;   for (int t = 0; t < nt - 2; t += 2) {
;     LDB8(B0, 0, 0); SCHED8; LDA8(At, 0, 0); STAGE8(SA8(1, 1), A, brow + HALF, t + 1);
;     WAITL8(8); BAR8; WAITL8(0); MMA8(0, 0, At, B0); BAR8; SCHED8;
;     LDB8(B1, 0, 1); STAGE8(SB8(0, 0), Bt, bcol, t + 2);
;     BAR8; WAITL8(0); MMA8(0, 1, At, B1); BAR8;
;     LDA8(At, 0, 1); STAGE8(SA8(0, 0), A, brow, t + 2);
;     BAR8; WAITL8(0); MMA8(1, 0, At, B0); BAR8; SCHED8;
.LBB0_528:
	v_or_b32_e32 v134, 0x10000, v133
	v_add_u32_e32 v136, 0x10800, v133
	v_add_u32_e32 v135, 0x10400, v133
	ds_read_b128 v[144:147], v134
	ds_read_b128 v[148:151], v135
	v_add_u32_e32 v137, 0x10c00, v133
	ds_read_b128 v[152:155], v136
	ds_read_b128 v[156:159], v137
	v_lshl_add_u64 v[228:229], s[22:23], 0, v[130:131]
	s_mov_b64 s[94:95], 0x6240080
	s_add_i32 s93, s45, 0xc000
	v_lshl_add_u64 v[138:139], v[228:229], 0, s[94:95]
	s_mov_b32 m0, s93
	s_mov_b64 s[94:95], 0x6260080
	s_add_i32 s25, s45, 0xe000
	ds_read_b128 v[160:163], v132
	ds_read_b128 v[164:167], v132 offset:1024
	ds_read_b128 v[168:171], v132 offset:2048
	ds_read_b128 v[172:175], v132 offset:3072
	ds_read_b128 v[176:179], v132 offset:4096
	ds_read_b128 v[180:183], v132 offset:5120
	ds_read_b128 v[184:187], v132 offset:6144
	ds_read_b128 v[188:191], v132 offset:7168
	global_load_lds_dwordx4 v[138:139], off
	v_lshl_add_u64 v[138:139], v[228:229], 0, s[94:95]
	s_mov_b32 m0, s25
	s_nop 0
	global_load_lds_dwordx4 v[138:139], off
	s_waitcnt lgkmcnt(8)
	s_barrier
	s_waitcnt lgkmcnt(0)
	s_setprio 1
	s_waitcnt lgkmcnt(0)
	v_mfma_f32_16x16x32_bf16 v[124:127], v[144:147], v[160:163], v[124:127]
	v_mfma_f32_16x16x32_bf16 v[120:123], v[152:155], v[160:163], v[120:123]
	v_mfma_f32_16x16x32_bf16 v[116:119], v[144:147], v[168:171], v[116:119]
	v_mfma_f32_16x16x32_bf16 v[112:115], v[152:155], v[168:171], v[112:115]
	v_mfma_f32_16x16x32_bf16 v[108:111], v[144:147], v[176:179], v[108:111]
	v_mfma_f32_16x16x32_bf16 v[104:107], v[152:155], v[176:179], v[104:107]
	v_mfma_f32_16x16x32_bf16 v[100:103], v[144:147], v[184:187], v[100:103]
	v_mfma_f32_16x16x32_bf16 v[96:99], v[152:155], v[184:187], v[96:99]
	v_mfma_f32_16x16x32_bf16 v[124:127], v[148:151], v[164:167], v[124:127]
	v_mfma_f32_16x16x32_bf16 v[120:123], v[156:159], v[164:167], v[120:123]
	v_mfma_f32_16x16x32_bf16 v[116:119], v[148:151], v[172:175], v[116:119]
	v_mfma_f32_16x16x32_bf16 v[112:115], v[156:159], v[172:175], v[112:115]
	v_mfma_f32_16x16x32_bf16 v[108:111], v[148:151], v[180:183], v[108:111]
	v_mfma_f32_16x16x32_bf16 v[104:107], v[156:159], v[180:183], v[104:107]
	v_mfma_f32_16x16x32_bf16 v[100:103], v[148:151], v[188:191], v[100:103]
	v_mfma_f32_16x16x32_bf16 v[96:99], v[156:159], v[188:191], v[96:99]
	s_setprio 0
	s_barrier
	v_lshl_add_u64 v[230:231], s[20:21], 0, v[130:131]
	s_mov_b64 s[94:95], 0xd00100
	s_mov_b32 m0, s48
	v_or_b32_e32 v138, 0x14000, v133
	v_add_u32_e32 v140, 0x14800, v133
	v_lshl_add_u64 v[220:221], v[230:231], 0, s[94:95]
	s_mov_b64 s[94:95], 0xd20100
	v_add_u32_e32 v139, 0x14400, v133
	ds_read_b128 v[204:207], v138
	ds_read_b128 v[208:211], v139
	v_add_u32_e32 v142, 0x14c00, v133
	ds_read_b128 v[212:215], v140
	ds_read_b128 v[216:219], v142
	global_load_lds_dwordx4 v[220:221], off
	v_lshl_add_u64 v[220:221], v[230:231], 0, s[94:95]
	s_mov_b32 m0, s54
	s_nop 0
	global_load_lds_dwordx4 v[220:221], off
	s_barrier
	s_waitcnt lgkmcnt(0)
	s_setprio 1
	s_waitcnt lgkmcnt(0)
	v_mfma_f32_16x16x32_bf16 v[92:95], v[204:207], v[160:163], v[92:95]
	v_mfma_f32_16x16x32_bf16 v[88:91], v[212:215], v[160:163], v[88:91]
	v_mfma_f32_16x16x32_bf16 v[84:87], v[204:207], v[168:171], v[84:87]
	v_mfma_f32_16x16x32_bf16 v[80:83], v[212:215], v[168:171], v[80:83]
	v_mfma_f32_16x16x32_bf16 v[76:79], v[204:207], v[176:179], v[76:79]
	v_mfma_f32_16x16x32_bf16 v[72:75], v[212:215], v[176:179], v[72:75]
	v_mfma_f32_16x16x32_bf16 v[68:71], v[204:207], v[184:187], v[68:71]
	v_mfma_f32_16x16x32_bf16 v[64:67], v[212:215], v[184:187], v[64:67]
	v_mfma_f32_16x16x32_bf16 v[92:95], v[208:211], v[164:167], v[92:95]
	v_mfma_f32_16x16x32_bf16 v[88:91], v[216:219], v[164:167], v[88:91]
	v_mfma_f32_16x16x32_bf16 v[84:87], v[208:211], v[172:175], v[84:87]
	v_mfma_f32_16x16x32_bf16 v[80:83], v[216:219], v[172:175], v[80:83]
	v_mfma_f32_16x16x32_bf16 v[76:79], v[208:211], v[180:183], v[76:79]
	v_mfma_f32_16x16x32_bf16 v[72:75], v[216:219], v[180:183], v[72:75]
	v_mfma_f32_16x16x32_bf16 v[68:71], v[208:211], v[188:191], v[68:71]
	v_mfma_f32_16x16x32_bf16 v[64:67], v[216:219], v[188:191], v[64:67]
	s_setprio 0
	s_mov_b64 s[94:95], 0x6200100
	s_mov_b32 m0, s45
	v_lshl_add_u64 v[220:221], v[228:229], 0, s[94:95]
	s_mov_b64 s[94:95], 0x6220100
	s_barrier
	ds_read_b128 v[160:163], v132 offset:16384
	ds_read_b128 v[164:167], v132 offset:17408
	ds_read_b128 v[168:171], v132 offset:18432
	ds_read_b128 v[172:175], v132 offset:19456
	ds_read_b128 v[176:179], v132 offset:20480
	ds_read_b128 v[180:183], v132 offset:21504
	ds_read_b128 v[184:187], v132 offset:22528
	ds_read_b128 v[188:191], v132 offset:23552
	global_load_lds_dwordx4 v[220:221], off
	v_lshl_add_u64 v[220:221], v[228:229], 0, s[94:95]
	s_mov_b32 m0, s55
	s_nop 0
	global_load_lds_dwordx4 v[220:221], off
	s_barrier
	s_waitcnt lgkmcnt(0)
	s_setprio 1
	s_waitcnt lgkmcnt(0)
	v_mfma_f32_16x16x32_bf16 v[60:63], v[144:147], v[160:163], v[60:63]
	v_mfma_f32_16x16x32_bf16 v[56:59], v[152:155], v[160:163], v[56:59]
	v_mfma_f32_16x16x32_bf16 v[52:55], v[144:147], v[168:171], v[52:55]
	v_mfma_f32_16x16x32_bf16 v[48:51], v[152:155], v[168:171], v[48:51]
	v_mfma_f32_16x16x32_bf16 v[44:47], v[144:147], v[176:179], v[44:47]
	v_mfma_f32_16x16x32_bf16 v[40:43], v[152:155], v[176:179], v[40:43]
	v_mfma_f32_16x16x32_bf16 v[36:39], v[144:147], v[184:187], v[36:39]
	v_mfma_f32_16x16x32_bf16 v[32:35], v[152:155], v[184:187], v[32:35]
	v_mfma_f32_16x16x32_bf16 v[60:63], v[148:151], v[164:167], v[60:63]
	v_mfma_f32_16x16x32_bf16 v[56:59], v[156:159], v[164:167], v[56:59]
	v_mfma_f32_16x16x32_bf16 v[52:55], v[148:151], v[172:175], v[52:55]
	v_mfma_f32_16x16x32_bf16 v[48:51], v[156:159], v[172:175], v[48:51]
	v_mfma_f32_16x16x32_bf16 v[44:47], v[148:151], v[180:183], v[44:47]
	v_mfma_f32_16x16x32_bf16 v[40:43], v[156:159], v[180:183], v[40:43]
	v_mfma_f32_16x16x32_bf16 v[36:39], v[148:151], v[188:191], v[36:39]
	v_mfma_f32_16x16x32_bf16 v[32:35], v[156:159], v[188:191], v[32:35]
	s_setprio 0
	s_barrier
; #define LDA8(dst, b, h)                                                                                               \
;   _Pragma("unroll") for (int m = 0; m < 4; ++m) _Pragma("unroll") for (int k = 0; k < 2; ++k)                         \
;     dst[m][k] = *(const bf16x8*)(SA8(b, h) + la + m * 2048 + k * 1024)
; #define LDB8(dst, b, h)                                                                                               \
;   _Pragma("unroll") for (int n = 0; n < 2; ++n) _Pragma("unroll") for (int k = 0; k < 2; ++k)                         \
;     dst[n][k] = *(const bf16x8*)(SB8(b, h) + lb + n * 2048 + k * 1024)
; #define WAITV8(n) asm volatile("s_waitcnt vmcnt(" #n ")" ::: "memory")
; #define WAITL8(n) asm volatile("s_waitcnt lgkmcnt(" #n ")" ::: "memory")
; #define BAR8 __builtin_amdgcn_s_barrier()
; #define SCHED8 __builtin_amdgcn_sched_barrier(0)
; template <class Epi>
; DEV void gemm_tile8(char* shm, const u16* __restrict__ A, const u16* __restrict__ Bt, int K, int brow, int bcol, Epi& epi) {
;     ...
;     STAGE8(SB8(0, 1), Bt, bcol + HALF, t + 2);
;     WAITV8(6); BAR8; MMA8(1, 1, At, B1); BAR8;
;     LDB8(B0, 1, 0); SCHED8; LDA8(At, 1, 0); STAGE8(SA8(0, 1), A, brow + HALF, t + 2);
;     WAITL8(8); BAR8; WAITL8(0); MMA8(0, 0, At, B0); BAR8; SCHED8;
;     LDB8(B1, 1, 1); STAGE8(SB8(1, 0), Bt, bcol, t + 3);
;     BAR8; WAITL8(0); MMA8(0, 1, At, B1); BAR8;
	s_mov_b64 s[94:95], 0xd40100
	s_mov_b32 m0, s70
	v_lshl_add_u64 v[144:145], v[230:231], 0, s[94:95]
	s_mov_b64 s[94:95], 0xd60100
	global_load_lds_dwordx4 v[144:145], off
	v_lshl_add_u64 v[144:145], v[230:231], 0, s[94:95]
	s_mov_b32 m0, s71
	s_nop 0
	global_load_lds_dwordx4 v[144:145], off
	s_waitcnt vmcnt(6)
	s_barrier
	s_setprio 1
	v_mfma_f32_16x16x32_bf16 v[28:31], v[204:207], v[160:163], v[28:31]
	v_mfma_f32_16x16x32_bf16 v[24:27], v[212:215], v[160:163], v[24:27]
	v_mfma_f32_16x16x32_bf16 v[20:23], v[204:207], v[168:171], v[20:23]
	v_mfma_f32_16x16x32_bf16 v[16:19], v[212:215], v[168:171], v[16:19]
	v_mfma_f32_16x16x32_bf16 v[12:15], v[204:207], v[176:179], v[12:15]
	v_mfma_f32_16x16x32_bf16 v[8:11], v[212:215], v[176:179], v[8:11]
	v_mfma_f32_16x16x32_bf16 v[4:7], v[204:207], v[184:187], v[4:7]
	v_mfma_f32_16x16x32_bf16 v[0:3], v[212:215], v[184:187], v[0:3]
	v_mfma_f32_16x16x32_bf16 v[28:31], v[208:211], v[164:167], v[28:31]
	v_mfma_f32_16x16x32_bf16 v[24:27], v[216:219], v[164:167], v[24:27]
	v_mfma_f32_16x16x32_bf16 v[20:23], v[208:211], v[172:175], v[20:23]
	v_mfma_f32_16x16x32_bf16 v[16:19], v[216:219], v[172:175], v[16:19]
	v_mfma_f32_16x16x32_bf16 v[12:15], v[208:211], v[180:183], v[12:15]
	v_mfma_f32_16x16x32_bf16 v[8:11], v[216:219], v[180:183], v[8:11]
	v_mfma_f32_16x16x32_bf16 v[4:7], v[208:211], v[188:191], v[4:7]
	v_mfma_f32_16x16x32_bf16 v[0:3], v[216:219], v[188:191], v[0:3]
	s_setprio 0
	v_or_b32_e32 v143, 0x18000, v133
	v_add_u32_e32 v145, 0x18800, v133
	s_barrier
	v_add_u32_e32 v144, 0x18400, v133
	ds_read_b128 v[152:155], v143
	ds_read_b128 v[156:159], v144
	v_add_u32_e32 v146, 0x18c00, v133
	ds_read_b128 v[160:163], v145
	ds_read_b128 v[164:167], v146
	s_mov_b64 s[94:95], 0x6240100
	s_mov_b32 m0, s72
	v_lshl_add_u64 v[148:149], v[228:229], 0, s[94:95]
	s_mov_b64 s[94:95], 0x6260100
	ds_read_b128 v[168:171], v132 offset:32768
	ds_read_b128 v[172:175], v132 offset:33792
	ds_read_b128 v[176:179], v132 offset:34816
	ds_read_b128 v[180:183], v132 offset:35840
	ds_read_b128 v[184:187], v132 offset:36864
	ds_read_b128 v[188:191], v132 offset:37888
	ds_read_b128 v[204:207], v132 offset:38912
	ds_read_b128 v[208:211], v132 offset:39936
	global_load_lds_dwordx4 v[148:149], off
	v_lshl_add_u64 v[148:149], v[228:229], 0, s[94:95]
	s_mov_b32 m0, s73
	s_nop 0
	global_load_lds_dwordx4 v[148:149], off
	s_waitcnt lgkmcnt(8)
	s_barrier
	s_waitcnt lgkmcnt(0)
	s_setprio 1
	s_waitcnt lgkmcnt(0)
	v_mfma_f32_16x16x32_bf16 v[124:127], v[152:155], v[168:171], v[124:127]
	v_mfma_f32_16x16x32_bf16 v[120:123], v[160:163], v[168:171], v[120:123]
	v_mfma_f32_16x16x32_bf16 v[116:119], v[152:155], v[176:179], v[116:119]
	v_mfma_f32_16x16x32_bf16 v[112:115], v[160:163], v[176:179], v[112:115]
	v_mfma_f32_16x16x32_bf16 v[108:111], v[152:155], v[184:187], v[108:111]
	v_mfma_f32_16x16x32_bf16 v[104:107], v[160:163], v[184:187], v[104:107]
	v_mfma_f32_16x16x32_bf16 v[100:103], v[152:155], v[204:207], v[100:103]
	v_mfma_f32_16x16x32_bf16 v[96:99], v[160:163], v[204:207], v[96:99]
	v_mfma_f32_16x16x32_bf16 v[124:127], v[156:159], v[172:175], v[124:127]
	v_mfma_f32_16x16x32_bf16 v[120:123], v[164:167], v[172:175], v[120:123]
	v_mfma_f32_16x16x32_bf16 v[116:119], v[156:159], v[180:183], v[116:119]
	v_mfma_f32_16x16x32_bf16 v[112:115], v[164:167], v[180:183], v[112:115]
	v_mfma_f32_16x16x32_bf16 v[108:111], v[156:159], v[188:191], v[108:111]
	v_mfma_f32_16x16x32_bf16 v[104:107], v[164:167], v[188:191], v[104:107]
	v_mfma_f32_16x16x32_bf16 v[100:103], v[156:159], v[208:211], v[100:103]
	v_mfma_f32_16x16x32_bf16 v[96:99], v[164:167], v[208:211], v[96:99]
	s_setprio 0
	s_barrier
	s_mov_b64 s[94:95], 0xd00180
	s_mov_b32 m0, s81
	v_or_b32_e32 v147, 0x1c000, v133
	v_add_u32_e32 v149, 0x1c800, v133
	v_lshl_add_u64 v[232:233], v[230:231], 0, s[94:95]
	s_mov_b64 s[94:95], 0xd20180
	v_add_u32_e32 v148, 0x1c400, v133
	ds_read_b128 v[212:215], v147
	ds_read_b128 v[216:219], v148
	v_add_u32_e32 v150, 0x1cc00, v133
	ds_read_b128 v[220:223], v149
	ds_read_b128 v[224:227], v150
	global_load_lds_dwordx4 v[232:233], off
	v_lshl_add_u64 v[232:233], v[230:231], 0, s[94:95]
	s_mov_b32 m0, s84
	s_nop 0
	global_load_lds_dwordx4 v[232:233], off
	s_barrier
	s_waitcnt lgkmcnt(0)
	s_setprio 1
	s_waitcnt lgkmcnt(0)
	v_mfma_f32_16x16x32_bf16 v[92:95], v[212:215], v[168:171], v[92:95]
	v_mfma_f32_16x16x32_bf16 v[88:91], v[220:223], v[168:171], v[88:91]
	v_mfma_f32_16x16x32_bf16 v[84:87], v[212:215], v[176:179], v[84:87]
	v_mfma_f32_16x16x32_bf16 v[80:83], v[220:223], v[176:179], v[80:83]
	v_mfma_f32_16x16x32_bf16 v[76:79], v[212:215], v[184:187], v[76:79]
	v_mfma_f32_16x16x32_bf16 v[72:75], v[220:223], v[184:187], v[72:75]
	v_mfma_f32_16x16x32_bf16 v[68:71], v[212:215], v[204:207], v[68:71]
	v_mfma_f32_16x16x32_bf16 v[64:67], v[220:223], v[204:207], v[64:67]
	v_mfma_f32_16x16x32_bf16 v[92:95], v[216:219], v[172:175], v[92:95]
	v_mfma_f32_16x16x32_bf16 v[88:91], v[224:227], v[172:175], v[88:91]
	v_mfma_f32_16x16x32_bf16 v[84:87], v[216:219], v[180:183], v[84:87]
	v_mfma_f32_16x16x32_bf16 v[80:83], v[224:227], v[180:183], v[80:83]
	v_mfma_f32_16x16x32_bf16 v[76:79], v[216:219], v[188:191], v[76:79]
	v_mfma_f32_16x16x32_bf16 v[72:75], v[224:227], v[188:191], v[72:75]
	v_mfma_f32_16x16x32_bf16 v[68:71], v[216:219], v[208:211], v[68:71]
	v_mfma_f32_16x16x32_bf16 v[64:67], v[224:227], v[208:211], v[64:67]
	s_setprio 0
	s_mov_b64 s[94:95], 0x6200180
	s_mov_b32 m0, s85
	v_lshl_add_u64 v[232:233], v[228:229], 0, s[94:95]
	s_mov_b64 s[94:95], 0x6220180
	s_barrier
; #define LDA8(dst, b, h)                                                                                               \
;   _Pragma("unroll") for (int m = 0; m < 4; ++m) _Pragma("unroll") for (int k = 0; k < 2; ++k)                         \
;     dst[m][k] = *(const bf16x8*)(SA8(b, h) + la + m * 2048 + k * 1024)
; #define LDB8(dst, b, h)                                                                                               \
;   _Pragma("unroll") for (int n = 0; n < 2; ++n) _Pragma("unroll") for (int k = 0; k < 2; ++k)                         \
;     dst[n][k] = *(const bf16x8*)(SB8(b, h) + lb + n * 2048 + k * 1024)
; #define WAITV8(n) asm volatile("s_waitcnt vmcnt(" #n ")" ::: "memory")
; #define WAITL8(n) asm volatile("s_waitcnt lgkmcnt(" #n ")" ::: "memory")
; #define BAR8 __builtin_amdgcn_s_barrier()
; #define SCHED8 __builtin_amdgcn_sched_barrier(0)
; template <class Epi>
; DEV void gemm_tile8(char* shm, const u16* __restrict__ A, const u16* __restrict__ Bt, int K, int brow, int bcol, Epi& epi) {
;     ...
;     LDA8(At, 1, 1); STAGE8(SA8(1, 0), A, brow, t + 3);
;     BAR8; WAITL8(0); MMA8(1, 0, At, B0); BAR8; SCHED8;
;     STAGE8(SB8(1, 1), Bt, bcol + HALF, t + 3);
;     WAITV8(6); BAR8; MMA8(1, 1, At, B1); BAR8;
;   }
;   { LDB8(B0, 0, 0); LDA8(At, 0, 0); STAGE8(SA8(1, 1), A, brow + HALF, nt - 1);
;     BAR8; WAITL8(0); MMA8(0, 0, At, B0); BAR8;
;     LDB8(B1, 0, 1); BAR8; WAITL8(0); MMA8(0, 1, At, B1); BAR8;
	ds_read_b128 v[168:171], v132 offset:49152
	ds_read_b128 v[172:175], v132 offset:50176
	ds_read_b128 v[176:179], v132 offset:51200
	ds_read_b128 v[180:183], v132 offset:52224
	ds_read_b128 v[184:187], v132 offset:53248
	ds_read_b128 v[188:191], v132 offset:54272
	ds_read_b128 v[204:207], v132 offset:55296
	ds_read_b128 v[208:211], v132 offset:56320
	global_load_lds_dwordx4 v[232:233], off
	v_lshl_add_u64 v[228:229], v[228:229], 0, s[94:95]
	s_mov_b32 m0, s90
	s_nop 0
	global_load_lds_dwordx4 v[228:229], off
	s_barrier
	s_waitcnt lgkmcnt(0)
	s_setprio 1
	s_waitcnt lgkmcnt(0)
	v_mfma_f32_16x16x32_bf16 v[60:63], v[152:155], v[168:171], v[60:63]
	v_mfma_f32_16x16x32_bf16 v[56:59], v[160:163], v[168:171], v[56:59]
	v_mfma_f32_16x16x32_bf16 v[52:55], v[152:155], v[176:179], v[52:55]
	v_mfma_f32_16x16x32_bf16 v[48:51], v[160:163], v[176:179], v[48:51]
	v_mfma_f32_16x16x32_bf16 v[44:47], v[152:155], v[184:187], v[44:47]
	v_mfma_f32_16x16x32_bf16 v[40:43], v[160:163], v[184:187], v[40:43]
	v_mfma_f32_16x16x32_bf16 v[36:39], v[152:155], v[204:207], v[36:39]
	v_mfma_f32_16x16x32_bf16 v[32:35], v[160:163], v[204:207], v[32:35]
	v_mfma_f32_16x16x32_bf16 v[60:63], v[156:159], v[172:175], v[60:63]
	v_mfma_f32_16x16x32_bf16 v[56:59], v[164:167], v[172:175], v[56:59]
	v_mfma_f32_16x16x32_bf16 v[52:55], v[156:159], v[180:183], v[52:55]
	v_mfma_f32_16x16x32_bf16 v[48:51], v[164:167], v[180:183], v[48:51]
	v_mfma_f32_16x16x32_bf16 v[44:47], v[156:159], v[188:191], v[44:47]
	v_mfma_f32_16x16x32_bf16 v[40:43], v[164:167], v[188:191], v[40:43]
	v_mfma_f32_16x16x32_bf16 v[36:39], v[156:159], v[208:211], v[36:39]
	v_mfma_f32_16x16x32_bf16 v[32:35], v[164:167], v[208:211], v[32:35]
	s_setprio 0
	s_barrier
	s_mov_b64 s[94:95], 0xd40180
	s_mov_b32 m0, s91
	v_lshl_add_u64 v[152:153], v[230:231], 0, s[94:95]
	s_mov_b64 s[94:95], 0xd60180
	global_load_lds_dwordx4 v[152:153], off
	v_lshl_add_u64 v[152:153], v[230:231], 0, s[94:95]
	s_mov_b32 m0, s92
	s_nop 0
	global_load_lds_dwordx4 v[152:153], off
	s_waitcnt vmcnt(6)
	s_barrier
	s_setprio 1
	v_mfma_f32_16x16x32_bf16 v[28:31], v[212:215], v[168:171], v[28:31]
	v_mfma_f32_16x16x32_bf16 v[24:27], v[220:223], v[168:171], v[24:27]
	v_mfma_f32_16x16x32_bf16 v[20:23], v[212:215], v[176:179], v[20:23]
	v_mfma_f32_16x16x32_bf16 v[16:19], v[220:223], v[176:179], v[16:19]
	v_mfma_f32_16x16x32_bf16 v[12:15], v[212:215], v[184:187], v[12:15]
	v_mfma_f32_16x16x32_bf16 v[8:11], v[220:223], v[184:187], v[8:11]
	v_mfma_f32_16x16x32_bf16 v[4:7], v[212:215], v[204:207], v[4:7]
	v_mfma_f32_16x16x32_bf16 v[0:3], v[220:223], v[204:207], v[0:3]
	v_mfma_f32_16x16x32_bf16 v[28:31], v[216:219], v[172:175], v[28:31]
	v_mfma_f32_16x16x32_bf16 v[24:27], v[224:227], v[172:175], v[24:27]
	v_mfma_f32_16x16x32_bf16 v[20:23], v[216:219], v[180:183], v[20:23]
	v_mfma_f32_16x16x32_bf16 v[16:19], v[224:227], v[180:183], v[16:19]
	v_mfma_f32_16x16x32_bf16 v[12:15], v[216:219], v[188:191], v[12:15]
	v_mfma_f32_16x16x32_bf16 v[8:11], v[224:227], v[188:191], v[8:11]
	v_mfma_f32_16x16x32_bf16 v[4:7], v[216:219], v[208:211], v[4:7]
	v_mfma_f32_16x16x32_bf16 v[0:3], v[224:227], v[208:211], v[0:3]
	s_setprio 0
	s_add_i32 s24, s24, 2
	s_add_u32 s20, s20, 0x100
	s_addc_u32 s21, s21, 0
	s_add_u32 s22, s22, 0x100
	s_addc_u32 s23, s23, 0
	s_cmp_lt_u32 s24, 12
	s_barrier
	s_cbranch_scc1 .LBB0_528
	s_mov_b64 s[20:21], 0x780
	s_mov_b32 m0, s93
	v_lshl_add_u64 v[130:131], v[128:129], 0, s[20:21]
	s_mov_b64 s[20:21], 0x20780
	s_waitcnt vmcnt(0)
	ds_read_b128 v[152:155], v134
	ds_read_b128 v[156:159], v135
	ds_read_b128 v[160:163], v136
	ds_read_b128 v[134:137], v137
	ds_read_b128 v[164:167], v132
	ds_read_b128 v[168:171], v132 offset:1024
	ds_read_b128 v[172:175], v132 offset:2048
	ds_read_b128 v[176:179], v132 offset:3072
	ds_read_b128 v[180:183], v132 offset:4096
	ds_read_b128 v[184:187], v132 offset:5120
	ds_read_b128 v[188:191], v132 offset:6144
	ds_read_b128 v[204:207], v132 offset:7168
	global_load_lds_dwordx4 v[130:131], off
	v_lshl_add_u64 v[128:129], v[128:129], 0, s[20:21]
	s_mov_b32 m0, s25
	s_nop 0
	global_load_lds_dwordx4 v[128:129], off
	s_barrier
	s_waitcnt lgkmcnt(0)
	s_setprio 1
	s_waitcnt lgkmcnt(0)
	v_mfma_f32_16x16x32_bf16 v[124:127], v[152:155], v[164:167], v[124:127]
	v_mfma_f32_16x16x32_bf16 v[120:123], v[160:163], v[164:167], v[120:123]
	v_mfma_f32_16x16x32_bf16 v[116:119], v[152:155], v[172:175], v[116:119]
	v_mfma_f32_16x16x32_bf16 v[112:115], v[160:163], v[172:175], v[112:115]
	v_mfma_f32_16x16x32_bf16 v[108:111], v[152:155], v[180:183], v[108:111]
	v_mfma_f32_16x16x32_bf16 v[104:107], v[160:163], v[180:183], v[104:107]
	v_mfma_f32_16x16x32_bf16 v[100:103], v[152:155], v[188:191], v[100:103]
	v_mfma_f32_16x16x32_bf16 v[96:99], v[160:163], v[188:191], v[96:99]
	v_mfma_f32_16x16x32_bf16 v[124:127], v[156:159], v[168:171], v[124:127]
	v_mfma_f32_16x16x32_bf16 v[120:123], v[134:137], v[168:171], v[120:123]
	v_mfma_f32_16x16x32_bf16 v[116:119], v[156:159], v[176:179], v[116:119]
	v_mfma_f32_16x16x32_bf16 v[112:115], v[134:137], v[176:179], v[112:115]
	v_mfma_f32_16x16x32_bf16 v[108:111], v[156:159], v[184:187], v[108:111]
	v_mfma_f32_16x16x32_bf16 v[104:107], v[134:137], v[184:187], v[104:107]
	v_mfma_f32_16x16x32_bf16 v[100:103], v[156:159], v[204:207], v[100:103]
	v_mfma_f32_16x16x32_bf16 v[96:99], v[134:137], v[204:207], v[96:99]
	s_setprio 0
	s_barrier
	s_waitcnt vmcnt(0)
	ds_read_b128 v[128:131], v138
	ds_read_b128 v[208:211], v139
	ds_read_b128 v[212:215], v140
	ds_read_b128 v[216:219], v142
	s_barrier
; #define LDA8(dst, b, h)                                                                                               \
;   _Pragma("unroll") for (int m = 0; m < 4; ++m) _Pragma("unroll") for (int k = 0; k < 2; ++k)                         \
;     dst[m][k] = *(const bf16x8*)(SA8(b, h) + la + m * 2048 + k * 1024)
; #define LDB8(dst, b, h)                                                                                               \
;   _Pragma("unroll") for (int n = 0; n < 2; ++n) _Pragma("unroll") for (int k = 0; k < 2; ++k)                         \
;     dst[n][k] = *(const bf16x8*)(SB8(b, h) + lb + n * 2048 + k * 1024)
; #define WAITV8(n) asm volatile("s_waitcnt vmcnt(" #n ")" ::: "memory")
; #define WAITL8(n) asm volatile("s_waitcnt lgkmcnt(" #n ")" ::: "memory")
; #define BAR8 __builtin_amdgcn_s_barrier()
; template <class Epi>
; DEV void gemm_tile8(char* shm, const u16* __restrict__ A, const u16* __restrict__ Bt, int K, int brow, int bcol, Epi& epi) {
;     ...
;     LDB8(B1, 0, 1); BAR8; WAITL8(0); MMA8(0, 1, At, B1); BAR8;
;     LDA8(At, 0, 1); WAITV8(4); BAR8; WAITL8(0); MMA8(1, 0, At, B0); MMA8(1, 1, At, B1); BAR8; }
;   { LDB8(B0, 1, 0); LDA8(At, 1, 0); WAITV8(2); BAR8; WAITL8(0); MMA8(0, 0, At, B0); BAR8;
	s_waitcnt lgkmcnt(0)
	s_setprio 1
	s_waitcnt lgkmcnt(3)
	v_mfma_f32_16x16x32_bf16 v[92:95], v[128:131], v[164:167], v[92:95]
	s_waitcnt lgkmcnt(1)
	v_mfma_f32_16x16x32_bf16 v[88:91], v[212:215], v[164:167], v[88:91]
	v_mfma_f32_16x16x32_bf16 v[84:87], v[128:131], v[172:175], v[84:87]
	v_mfma_f32_16x16x32_bf16 v[80:83], v[212:215], v[172:175], v[80:83]
	v_mfma_f32_16x16x32_bf16 v[76:79], v[128:131], v[180:183], v[76:79]
	v_mfma_f32_16x16x32_bf16 v[72:75], v[212:215], v[180:183], v[72:75]
	v_mfma_f32_16x16x32_bf16 v[68:71], v[128:131], v[188:191], v[68:71]
	v_mfma_f32_16x16x32_bf16 v[64:67], v[212:215], v[188:191], v[64:67]
	v_mfma_f32_16x16x32_bf16 v[220:223], v[208:211], v[168:171], v[92:95]
	s_waitcnt lgkmcnt(0)
	v_mfma_f32_16x16x32_bf16 v[164:167], v[216:219], v[168:171], v[88:91]
	v_mfma_f32_16x16x32_bf16 v[168:171], v[208:211], v[176:179], v[84:87]
	v_mfma_f32_16x16x32_bf16 v[172:175], v[216:219], v[176:179], v[80:83]
	v_mfma_f32_16x16x32_bf16 v[176:179], v[208:211], v[184:187], v[76:79]
	v_mfma_f32_16x16x32_bf16 v[180:183], v[216:219], v[184:187], v[72:75]
	v_mfma_f32_16x16x32_bf16 v[184:187], v[208:211], v[204:207], v[68:71]
	v_mfma_f32_16x16x32_bf16 v[188:191], v[216:219], v[204:207], v[64:67]
	s_setprio 0
	s_barrier
	s_nop 0
	ds_read_b128 v[64:67], v132 offset:16384
	ds_read_b128 v[68:71], v132 offset:17408
	ds_read_b128 v[72:75], v132 offset:18432
	ds_read_b128 v[76:79], v132 offset:19456
	ds_read_b128 v[80:83], v132 offset:20480
	ds_read_b128 v[84:87], v132 offset:21504
	ds_read_b128 v[88:91], v132 offset:22528
	ds_read_b128 v[92:95], v132 offset:23552
	s_waitcnt vmcnt(4)
	s_barrier
	s_waitcnt lgkmcnt(0)
	s_setprio 1
	s_waitcnt lgkmcnt(7)
	v_mfma_f32_16x16x32_bf16 v[60:63], v[152:155], v[64:67], v[60:63]
	v_mfma_f32_16x16x32_bf16 v[56:59], v[160:163], v[64:67], v[56:59]
	s_waitcnt lgkmcnt(5)
	v_mfma_f32_16x16x32_bf16 v[52:55], v[152:155], v[72:75], v[52:55]
	v_mfma_f32_16x16x32_bf16 v[48:51], v[160:163], v[72:75], v[48:51]
	s_waitcnt lgkmcnt(3)
	v_mfma_f32_16x16x32_bf16 v[44:47], v[152:155], v[80:83], v[44:47]
	v_mfma_f32_16x16x32_bf16 v[40:43], v[160:163], v[80:83], v[40:43]
	s_waitcnt lgkmcnt(1)
	v_mfma_f32_16x16x32_bf16 v[36:39], v[152:155], v[88:91], v[36:39]
	v_mfma_f32_16x16x32_bf16 v[32:35], v[160:163], v[88:91], v[32:35]
	v_mfma_f32_16x16x32_bf16 v[60:63], v[156:159], v[68:71], v[60:63]
	v_mfma_f32_16x16x32_bf16 v[56:59], v[134:137], v[68:71], v[56:59]
	v_mfma_f32_16x16x32_bf16 v[52:55], v[156:159], v[76:79], v[52:55]
	v_mfma_f32_16x16x32_bf16 v[48:51], v[134:137], v[76:79], v[48:51]
	v_mfma_f32_16x16x32_bf16 v[44:47], v[156:159], v[84:87], v[44:47]
	v_mfma_f32_16x16x32_bf16 v[40:43], v[134:137], v[84:87], v[40:43]
	s_waitcnt lgkmcnt(0)
	v_mfma_f32_16x16x32_bf16 v[36:39], v[156:159], v[92:95], v[36:39]
	v_mfma_f32_16x16x32_bf16 v[32:35], v[134:137], v[92:95], v[32:35]
	s_setprio 0
	s_setprio 1
	v_mfma_f32_16x16x32_bf16 v[28:31], v[128:131], v[64:67], v[28:31]
	v_mfma_f32_16x16x32_bf16 v[24:27], v[212:215], v[64:67], v[24:27]
	v_mfma_f32_16x16x32_bf16 v[20:23], v[128:131], v[72:75], v[20:23]
	v_mfma_f32_16x16x32_bf16 v[16:19], v[212:215], v[72:75], v[16:19]
	v_mfma_f32_16x16x32_bf16 v[12:15], v[128:131], v[80:83], v[12:15]
	v_mfma_f32_16x16x32_bf16 v[8:11], v[212:215], v[80:83], v[8:11]
	v_mfma_f32_16x16x32_bf16 v[4:7], v[128:131], v[88:91], v[4:7]
	v_mfma_f32_16x16x32_bf16 v[0:3], v[212:215], v[88:91], v[0:3]
	v_mfma_f32_16x16x32_bf16 v[134:137], v[208:211], v[68:71], v[28:31]
	v_mfma_f32_16x16x32_bf16 v[152:155], v[216:219], v[68:71], v[24:27]
	v_mfma_f32_16x16x32_bf16 v[156:159], v[208:211], v[76:79], v[20:23]
	v_mfma_f32_16x16x32_bf16 v[160:163], v[216:219], v[76:79], v[16:19]
	v_mfma_f32_16x16x32_bf16 v[204:207], v[208:211], v[84:87], v[12:15]
	v_mfma_f32_16x16x32_bf16 v[224:227], v[216:219], v[84:87], v[8:11]
	v_mfma_f32_16x16x32_bf16 v[128:131], v[208:211], v[92:95], v[4:7]
	v_mfma_f32_16x16x32_bf16 v[208:211], v[216:219], v[92:95], v[0:3]
	s_setprio 0
	s_barrier
	ds_read_b128 v[24:27], v143
	ds_read_b128 v[28:31], v144
	ds_read_b128 v[142:145], v145
	ds_read_b128 v[212:215], v146
	ds_read_b128 v[0:3], v132 offset:32768
	ds_read_b128 v[4:7], v132 offset:33792
	ds_read_b128 v[8:11], v132 offset:34816
	ds_read_b128 v[12:15], v132 offset:35840
	ds_read_b128 v[16:19], v132 offset:36864
	ds_read_b128 v[20:23], v132 offset:37888
	ds_read_b128 v[216:219], v132 offset:38912
	ds_read_b128 v[228:231], v132 offset:39936
	s_waitcnt vmcnt(2)
	s_barrier
; #define LDA8(dst, b, h)                                                                                               \
;   _Pragma("unroll") for (int m = 0; m < 4; ++m) _Pragma("unroll") for (int k = 0; k < 2; ++k)                         \
;     dst[m][k] = *(const bf16x8*)(SA8(b, h) + la + m * 2048 + k * 1024)
; #define LDB8(dst, b, h)                                                                                               \
;   _Pragma("unroll") for (int n = 0; n < 2; ++n) _Pragma("unroll") for (int k = 0; k < 2; ++k)                         \
;     dst[n][k] = *(const bf16x8*)(SB8(b, h) + lb + n * 2048 + k * 1024)
; #define WAITV8(n) asm volatile("s_waitcnt vmcnt(" #n ")" ::: "memory")
; #define WAITL8(n) asm volatile("s_waitcnt lgkmcnt(" #n ")" ::: "memory")
; #define BAR8 __builtin_amdgcn_s_barrier()
; template <class Epi>
; DEV void gemm_tile8(char* shm, const u16* __restrict__ A, const u16* __restrict__ Bt, int K, int brow, int bcol, Epi& epi) {
;     ...
;   { LDB8(B0, 1, 0); LDA8(At, 1, 0); WAITV8(2); BAR8; WAITL8(0); MMA8(0, 0, At, B0); BAR8;
;     LDB8(B1, 1, 1); WAITV8(0); BAR8; WAITL8(0); MMA8(0, 1, At, B1); BAR8;
;     LDA8(At, 1, 1); BAR8; WAITL8(0); MMA8(1, 0, At, B0); MMA8(1, 1, At, B1); BAR8; }
;   if (wrs == 0) BAR8;
	s_waitcnt lgkmcnt(0)
	s_setprio 1
	s_waitcnt lgkmcnt(7)
	v_mfma_f32_16x16x32_bf16 v[64:67], v[24:27], v[0:3], v[124:127]
	s_waitcnt lgkmcnt(6)
	v_mfma_f32_16x16x32_bf16 v[72:75], v[28:31], v[4:7], v[64:67]
	v_mfma_f32_16x16x32_bf16 v[64:67], v[142:145], v[0:3], v[120:123]
	s_waitcnt lgkmcnt(5)
	v_mfma_f32_16x16x32_bf16 v[68:71], v[24:27], v[8:11], v[116:119]
	v_mfma_f32_16x16x32_bf16 v[76:79], v[142:145], v[8:11], v[112:115]
	s_waitcnt lgkmcnt(3)
	v_mfma_f32_16x16x32_bf16 v[80:83], v[24:27], v[16:19], v[108:111]
	v_mfma_f32_16x16x32_bf16 v[84:87], v[142:145], v[16:19], v[104:107]
	s_waitcnt lgkmcnt(1)
	v_mfma_f32_16x16x32_bf16 v[88:91], v[24:27], v[216:219], v[100:103]
	v_mfma_f32_16x16x32_bf16 v[92:95], v[142:145], v[216:219], v[96:99]
	v_mfma_f32_16x16x32_bf16 v[64:67], v[212:215], v[4:7], v[64:67]
	v_mfma_f32_16x16x32_bf16 v[68:71], v[28:31], v[12:15], v[68:71]
	v_mfma_f32_16x16x32_bf16 v[76:79], v[212:215], v[12:15], v[76:79]
	v_mfma_f32_16x16x32_bf16 v[80:83], v[28:31], v[20:23], v[80:83]
	v_mfma_f32_16x16x32_bf16 v[84:87], v[212:215], v[20:23], v[84:87]
	s_waitcnt lgkmcnt(0)
	v_mfma_f32_16x16x32_bf16 v[88:91], v[28:31], v[228:231], v[88:91]
	v_mfma_f32_16x16x32_bf16 v[92:95], v[212:215], v[228:231], v[92:95]
	s_setprio 0
	s_barrier
	ds_read_b128 v[232:235], v147
	ds_read_b128 v[236:239], v148
	ds_read_b128 v[146:149], v149
	ds_read_b128 v[240:243], v150
	s_waitcnt vmcnt(0)
	s_barrier
	s_waitcnt lgkmcnt(0)
	s_setprio 1
	s_waitcnt lgkmcnt(3)
	v_mfma_f32_16x16x32_bf16 v[96:99], v[232:235], v[0:3], v[220:223]
	s_waitcnt lgkmcnt(1)
	v_mfma_f32_16x16x32_bf16 v[0:3], v[146:149], v[0:3], v[164:167]
	v_mfma_f32_16x16x32_bf16 v[104:107], v[236:239], v[4:7], v[96:99]
	s_waitcnt lgkmcnt(0)
	v_mfma_f32_16x16x32_bf16 v[96:99], v[240:243], v[4:7], v[0:3]
	v_mfma_f32_16x16x32_bf16 v[0:3], v[232:235], v[8:11], v[168:171]
	v_mfma_f32_16x16x32_bf16 v[100:103], v[236:239], v[12:15], v[0:3]
	v_mfma_f32_16x16x32_bf16 v[0:3], v[146:149], v[8:11], v[172:175]
	v_mfma_f32_16x16x32_bf16 v[108:111], v[240:243], v[12:15], v[0:3]
	v_mfma_f32_16x16x32_bf16 v[0:3], v[232:235], v[16:19], v[176:179]
	v_mfma_f32_16x16x32_bf16 v[112:115], v[236:239], v[20:23], v[0:3]
	v_mfma_f32_16x16x32_bf16 v[0:3], v[146:149], v[16:19], v[180:183]
	v_mfma_f32_16x16x32_bf16 v[116:119], v[240:243], v[20:23], v[0:3]
	v_mfma_f32_16x16x32_bf16 v[0:3], v[232:235], v[216:219], v[184:187]
	v_mfma_f32_16x16x32_bf16 v[120:123], v[236:239], v[228:231], v[0:3]
	v_mfma_f32_16x16x32_bf16 v[0:3], v[146:149], v[216:219], v[188:191]
	v_mfma_f32_16x16x32_bf16 v[124:127], v[240:243], v[228:231], v[0:3]
	s_setprio 0
	s_barrier
	ds_read_b128 v[164:167], v132 offset:49152
	ds_read_b128 v[168:171], v132 offset:50176
	ds_read_b128 v[172:175], v132 offset:51200
	ds_read_b128 v[176:179], v132 offset:52224
	ds_read_b128 v[180:183], v132 offset:53248
	ds_read_b128 v[184:187], v132 offset:54272
	ds_read_b128 v[188:191], v132 offset:55296
	ds_read_b128 v[216:219], v132 offset:56320
	s_barrier
	s_waitcnt lgkmcnt(0)
	s_setprio 1
	s_waitcnt lgkmcnt(7)
	v_mfma_f32_16x16x32_bf16 v[0:3], v[24:27], v[164:167], v[60:63]
	s_waitcnt lgkmcnt(5)
	v_mfma_f32_16x16x32_bf16 v[8:11], v[24:27], v[172:175], v[52:55]
	s_waitcnt lgkmcnt(3)
	v_mfma_f32_16x16x32_bf16 v[16:19], v[24:27], v[180:183], v[44:47]
	s_waitcnt lgkmcnt(1)
	v_mfma_f32_16x16x32_bf16 v[24:27], v[24:27], v[188:191], v[36:39]
	v_mfma_f32_16x16x32_bf16 v[0:3], v[28:31], v[168:171], v[0:3]
	v_mfma_f32_16x16x32_bf16 v[4:7], v[142:145], v[164:167], v[56:59]
	v_mfma_f32_16x16x32_bf16 v[8:11], v[28:31], v[176:179], v[8:11]
	v_mfma_f32_16x16x32_bf16 v[12:15], v[142:145], v[172:175], v[48:51]
	v_mfma_f32_16x16x32_bf16 v[16:19], v[28:31], v[184:187], v[16:19]
	v_mfma_f32_16x16x32_bf16 v[20:23], v[142:145], v[180:183], v[40:43]
	s_waitcnt lgkmcnt(0)
	v_mfma_f32_16x16x32_bf16 v[24:27], v[28:31], v[216:219], v[24:27]
	v_mfma_f32_16x16x32_bf16 v[28:31], v[142:145], v[188:191], v[32:35]
	v_mfma_f32_16x16x32_bf16 v[4:7], v[212:215], v[168:171], v[4:7]
	v_mfma_f32_16x16x32_bf16 v[12:15], v[212:215], v[176:179], v[12:15]
	v_mfma_f32_16x16x32_bf16 v[20:23], v[212:215], v[184:187], v[20:23]
	v_mfma_f32_16x16x32_bf16 v[28:31], v[212:215], v[216:219], v[28:31]
	s_setprio 0
	s_setprio 1
	v_mfma_f32_16x16x32_bf16 v[32:35], v[232:235], v[164:167], v[134:137]
	v_mfma_f32_16x16x32_bf16 v[36:39], v[146:149], v[164:167], v[152:155]
	v_mfma_f32_16x16x32_bf16 v[40:43], v[232:235], v[172:175], v[156:159]
	v_mfma_f32_16x16x32_bf16 v[44:47], v[146:149], v[172:175], v[160:163]
	v_mfma_f32_16x16x32_bf16 v[48:51], v[232:235], v[180:183], v[204:207]
	v_mfma_f32_16x16x32_bf16 v[52:55], v[146:149], v[180:183], v[224:227]
	v_mfma_f32_16x16x32_bf16 v[56:59], v[232:235], v[188:191], v[128:131]
	v_mfma_f32_16x16x32_bf16 v[60:63], v[146:149], v[188:191], v[208:211]
	v_mfma_f32_16x16x32_bf16 v[32:35], v[236:239], v[168:171], v[32:35]
	v_mfma_f32_16x16x32_bf16 v[36:39], v[240:243], v[168:171], v[36:39]
	v_mfma_f32_16x16x32_bf16 v[40:43], v[236:239], v[176:179], v[40:43]
	v_mfma_f32_16x16x32_bf16 v[44:47], v[240:243], v[176:179], v[44:47]
	v_mfma_f32_16x16x32_bf16 v[48:51], v[236:239], v[184:187], v[48:51]
	v_mfma_f32_16x16x32_bf16 v[52:55], v[240:243], v[184:187], v[52:55]
	v_mfma_f32_16x16x32_bf16 v[56:59], v[236:239], v[216:219], v[56:59]
	v_mfma_f32_16x16x32_bf16 v[60:63], v[240:243], v[216:219], v[60:63]
	s_setprio 0
	s_cmp_lg_u32 s7, 0
	s_barrier
	s_cbranch_scc1 .LBB0_531
	s_barrier

; #define LDA8(dst, b, h)                                                                                               \
;   _Pragma("unroll") for (int m = 0; m < 4; ++m) _Pragma("unroll") for (int k = 0; k < 2; ++k)                         \
;     dst[m][k] = *(const bf16x8*)(SA8(b, h) + la + m * 2048 + k * 1024)
; #define LDB8(dst, b, h)                                                                                               \
;   _Pragma("unroll") for (int n = 0; n < 2; ++n) _Pragma("unroll") for (int k = 0; k < 2; ++k)                         \
;     dst[n][k] = *(const bf16x8*)(SB8(b, h) + lb + n * 2048 + k * 1024)
; #define WAITL8(n) asm volatile("s_waitcnt lgkmcnt(" #n ")" ::: "memory")
; #define BAR8 __builtin_amdgcn_s_barrier()
; #define SCHED8 __builtin_amdgcn_sched_barrier(0)
; template <class Epi>
; DEV void gemm_tile8(char* shm, const u16* __restrict__ A, const u16* __restrict__ Bt, int K, int brow, int bcol, Epi& epi) {
;     ...
;     LDB8(B0, 0, 0); SCHED8; LDA8(At, 0, 0); STAGE8(SA8(1, 1), A, brow + HALF, t + 1);
;     WAITL8(8); BAR8; WAITL8(0); MMA8(0, 0, At, B0); BAR8; SCHED8;
;     LDB8(B1, 0, 1); STAGE8(SB8(0, 0), Bt, bcol, t + 2);
;     BAR8; WAITL8(0); MMA8(0, 1, At, B1); BAR8;
;     LDA8(At, 0, 1); STAGE8(SA8(0, 0), A, brow, t + 2);
;     BAR8; WAITL8(0); MMA8(1, 0, At, B0); BAR8; SCHED8;
.LBB0_563:
	v_or_b32_e32 v134, 0x10000, v133
	v_add_u32_e32 v136, 0x10800, v133
	v_add_u32_e32 v135, 0x10400, v133
	ds_read_b128 v[144:147], v134
	ds_read_b128 v[148:151], v135
	v_add_u32_e32 v137, 0x10c00, v133
	ds_read_b128 v[152:155], v136
	ds_read_b128 v[156:159], v137
	v_lshl_add_u64 v[228:229], s[18:19], 0, v[130:131]
	s_mov_b64 s[92:93], 0x19ca0080
	s_add_i32 s91, s43, 0xc000
	v_lshl_add_u64 v[138:139], v[228:229], 0, s[92:93]
	s_mov_b32 m0, s91
	s_mov_b64 s[92:93], 0x19cb0080
	s_add_i32 s23, s43, 0xe000
	ds_read_b128 v[160:163], v132
	ds_read_b128 v[164:167], v132 offset:1024
	ds_read_b128 v[168:171], v132 offset:2048
	ds_read_b128 v[172:175], v132 offset:3072
	ds_read_b128 v[176:179], v132 offset:4096
	ds_read_b128 v[180:183], v132 offset:5120
	ds_read_b128 v[184:187], v132 offset:6144
	ds_read_b128 v[188:191], v132 offset:7168
	global_load_lds_dwordx4 v[138:139], off
	v_lshl_add_u64 v[138:139], v[228:229], 0, s[92:93]
	s_mov_b32 m0, s23
	s_nop 0
	global_load_lds_dwordx4 v[138:139], off
	s_waitcnt lgkmcnt(8)
	s_barrier
	s_waitcnt lgkmcnt(0)
	s_setprio 1
	s_waitcnt lgkmcnt(0)
	v_mfma_f32_16x16x32_bf16 v[124:127], v[144:147], v[160:163], v[124:127]
	v_mfma_f32_16x16x32_bf16 v[120:123], v[152:155], v[160:163], v[120:123]
	v_mfma_f32_16x16x32_bf16 v[116:119], v[144:147], v[168:171], v[116:119]
	v_mfma_f32_16x16x32_bf16 v[112:115], v[152:155], v[168:171], v[112:115]
	v_mfma_f32_16x16x32_bf16 v[108:111], v[144:147], v[176:179], v[108:111]
	v_mfma_f32_16x16x32_bf16 v[104:107], v[152:155], v[176:179], v[104:107]
	v_mfma_f32_16x16x32_bf16 v[100:103], v[144:147], v[184:187], v[100:103]
	v_mfma_f32_16x16x32_bf16 v[96:99], v[152:155], v[184:187], v[96:99]
	v_mfma_f32_16x16x32_bf16 v[124:127], v[148:151], v[164:167], v[124:127]
	v_mfma_f32_16x16x32_bf16 v[120:123], v[156:159], v[164:167], v[120:123]
	v_mfma_f32_16x16x32_bf16 v[116:119], v[148:151], v[172:175], v[116:119]
	v_mfma_f32_16x16x32_bf16 v[112:115], v[156:159], v[172:175], v[112:115]
	v_mfma_f32_16x16x32_bf16 v[108:111], v[148:151], v[180:183], v[108:111]
	v_mfma_f32_16x16x32_bf16 v[104:107], v[156:159], v[180:183], v[104:107]
	v_mfma_f32_16x16x32_bf16 v[100:103], v[148:151], v[188:191], v[100:103]
	v_mfma_f32_16x16x32_bf16 v[96:99], v[156:159], v[188:191], v[96:99]
	s_setprio 0
	s_barrier
	v_lshl_add_u64 v[230:231], s[20:21], 0, v[130:131]
	s_mov_b64 s[92:93], 0xc00100
	s_mov_b32 m0, s44
	v_or_b32_e32 v138, 0x14000, v133
	v_add_u32_e32 v140, 0x14800, v133
	v_lshl_add_u64 v[220:221], v[230:231], 0, s[92:93]
	s_mov_b64 s[92:93], 0xc10100
	v_add_u32_e32 v139, 0x14400, v133
	ds_read_b128 v[204:207], v138
	ds_read_b128 v[208:211], v139
	v_add_u32_e32 v142, 0x14c00, v133
	ds_read_b128 v[212:215], v140
	ds_read_b128 v[216:219], v142
	global_load_lds_dwordx4 v[220:221], off
	v_lshl_add_u64 v[220:221], v[230:231], 0, s[92:93]
	s_mov_b32 m0, s45
	s_nop 0
	global_load_lds_dwordx4 v[220:221], off
	s_barrier
	s_waitcnt lgkmcnt(0)
	s_setprio 1
	s_waitcnt lgkmcnt(0)
	v_mfma_f32_16x16x32_bf16 v[92:95], v[204:207], v[160:163], v[92:95]
	v_mfma_f32_16x16x32_bf16 v[88:91], v[212:215], v[160:163], v[88:91]
	v_mfma_f32_16x16x32_bf16 v[84:87], v[204:207], v[168:171], v[84:87]
	v_mfma_f32_16x16x32_bf16 v[80:83], v[212:215], v[168:171], v[80:83]
	v_mfma_f32_16x16x32_bf16 v[76:79], v[204:207], v[176:179], v[76:79]
	v_mfma_f32_16x16x32_bf16 v[72:75], v[212:215], v[176:179], v[72:75]
	v_mfma_f32_16x16x32_bf16 v[68:71], v[204:207], v[184:187], v[68:71]
	v_mfma_f32_16x16x32_bf16 v[64:67], v[212:215], v[184:187], v[64:67]
	v_mfma_f32_16x16x32_bf16 v[92:95], v[208:211], v[164:167], v[92:95]
	v_mfma_f32_16x16x32_bf16 v[88:91], v[216:219], v[164:167], v[88:91]
	v_mfma_f32_16x16x32_bf16 v[84:87], v[208:211], v[172:175], v[84:87]
	v_mfma_f32_16x16x32_bf16 v[80:83], v[216:219], v[172:175], v[80:83]
	v_mfma_f32_16x16x32_bf16 v[76:79], v[208:211], v[180:183], v[76:79]
	v_mfma_f32_16x16x32_bf16 v[72:75], v[216:219], v[180:183], v[72:75]
	v_mfma_f32_16x16x32_bf16 v[68:71], v[208:211], v[188:191], v[68:71]
	v_mfma_f32_16x16x32_bf16 v[64:67], v[216:219], v[188:191], v[64:67]
	s_setprio 0
	s_mov_b32 m0, s43
	v_lshl_add_u64 v[220:221], v[228:229], 0, s[2:3]
	s_mov_b64 s[92:93], 0x19c90100
	s_barrier
	ds_read_b128 v[160:163], v132 offset:16384
	ds_read_b128 v[164:167], v132 offset:17408
	ds_read_b128 v[168:171], v132 offset:18432
	ds_read_b128 v[172:175], v132 offset:19456
	ds_read_b128 v[176:179], v132 offset:20480
	ds_read_b128 v[180:183], v132 offset:21504
	ds_read_b128 v[184:187], v132 offset:22528
	ds_read_b128 v[188:191], v132 offset:23552
	global_load_lds_dwordx4 v[220:221], off
	v_lshl_add_u64 v[220:221], v[228:229], 0, s[92:93]
	s_mov_b32 m0, s48
	s_nop 0
	global_load_lds_dwordx4 v[220:221], off
	s_barrier
	s_waitcnt lgkmcnt(0)
	s_setprio 1
	s_waitcnt lgkmcnt(0)
	v_mfma_f32_16x16x32_bf16 v[60:63], v[144:147], v[160:163], v[60:63]
	v_mfma_f32_16x16x32_bf16 v[56:59], v[152:155], v[160:163], v[56:59]
	v_mfma_f32_16x16x32_bf16 v[52:55], v[144:147], v[168:171], v[52:55]
	v_mfma_f32_16x16x32_bf16 v[48:51], v[152:155], v[168:171], v[48:51]
	v_mfma_f32_16x16x32_bf16 v[44:47], v[144:147], v[176:179], v[44:47]
	v_mfma_f32_16x16x32_bf16 v[40:43], v[152:155], v[176:179], v[40:43]
	v_mfma_f32_16x16x32_bf16 v[36:39], v[144:147], v[184:187], v[36:39]
	v_mfma_f32_16x16x32_bf16 v[32:35], v[152:155], v[184:187], v[32:35]
	v_mfma_f32_16x16x32_bf16 v[60:63], v[148:151], v[164:167], v[60:63]
	v_mfma_f32_16x16x32_bf16 v[56:59], v[156:159], v[164:167], v[56:59]
	v_mfma_f32_16x16x32_bf16 v[52:55], v[148:151], v[172:175], v[52:55]
	v_mfma_f32_16x16x32_bf16 v[48:51], v[156:159], v[172:175], v[48:51]
	v_mfma_f32_16x16x32_bf16 v[44:47], v[148:151], v[180:183], v[44:47]
	v_mfma_f32_16x16x32_bf16 v[40:43], v[156:159], v[180:183], v[40:43]
	v_mfma_f32_16x16x32_bf16 v[36:39], v[148:151], v[188:191], v[36:39]
	v_mfma_f32_16x16x32_bf16 v[32:35], v[156:159], v[188:191], v[32:35]
	s_setprio 0
	s_barrier
; #define LDA8(dst, b, h)                                                                                               \
;   _Pragma("unroll") for (int m = 0; m < 4; ++m) _Pragma("unroll") for (int k = 0; k < 2; ++k)                         \
;     dst[m][k] = *(const bf16x8*)(SA8(b, h) + la + m * 2048 + k * 1024)
; #define LDB8(dst, b, h)                                                                                               \
;   _Pragma("unroll") for (int n = 0; n < 2; ++n) _Pragma("unroll") for (int k = 0; k < 2; ++k)                         \
;     dst[n][k] = *(const bf16x8*)(SB8(b, h) + lb + n * 2048 + k * 1024)
; #define WAITV8(n) asm volatile("s_waitcnt vmcnt(" #n ")" ::: "memory")
; #define WAITL8(n) asm volatile("s_waitcnt lgkmcnt(" #n ")" ::: "memory")
; #define BAR8 __builtin_amdgcn_s_barrier()
; #define SCHED8 __builtin_amdgcn_sched_barrier(0)
; template <class Epi>
; DEV void gemm_tile8(char* shm, const u16* __restrict__ A, const u16* __restrict__ Bt, int K, int brow, int bcol, Epi& epi) {
;     ...
;     STAGE8(SB8(0, 1), Bt, bcol + HALF, t + 2);
;     WAITV8(6); BAR8; MMA8(1, 1, At, B1); BAR8;
;     LDB8(B0, 1, 0); SCHED8; LDA8(At, 1, 0); STAGE8(SA8(0, 1), A, brow + HALF, t + 2);
;     WAITL8(8); BAR8; WAITL8(0); MMA8(0, 0, At, B0); BAR8; SCHED8;
;     LDB8(B1, 1, 1); STAGE8(SB8(1, 0), Bt, bcol, t + 3);
;     BAR8; WAITL8(0); MMA8(0, 1, At, B1); BAR8;
	s_mov_b64 s[92:93], 0xc20100
	s_mov_b32 m0, s54
	v_lshl_add_u64 v[144:145], v[230:231], 0, s[92:93]
	s_mov_b64 s[92:93], 0xc30100
	global_load_lds_dwordx4 v[144:145], off
	v_lshl_add_u64 v[144:145], v[230:231], 0, s[92:93]
	s_mov_b32 m0, s55
	s_nop 0
	global_load_lds_dwordx4 v[144:145], off
	s_waitcnt vmcnt(6)
	s_barrier
	s_setprio 1
	v_mfma_f32_16x16x32_bf16 v[28:31], v[204:207], v[160:163], v[28:31]
	v_mfma_f32_16x16x32_bf16 v[24:27], v[212:215], v[160:163], v[24:27]
	v_mfma_f32_16x16x32_bf16 v[20:23], v[204:207], v[168:171], v[20:23]
	v_mfma_f32_16x16x32_bf16 v[16:19], v[212:215], v[168:171], v[16:19]
	v_mfma_f32_16x16x32_bf16 v[12:15], v[204:207], v[176:179], v[12:15]
	v_mfma_f32_16x16x32_bf16 v[8:11], v[212:215], v[176:179], v[8:11]
	v_mfma_f32_16x16x32_bf16 v[4:7], v[204:207], v[184:187], v[4:7]
	v_mfma_f32_16x16x32_bf16 v[0:3], v[212:215], v[184:187], v[0:3]
	v_mfma_f32_16x16x32_bf16 v[28:31], v[208:211], v[164:167], v[28:31]
	v_mfma_f32_16x16x32_bf16 v[24:27], v[216:219], v[164:167], v[24:27]
	v_mfma_f32_16x16x32_bf16 v[20:23], v[208:211], v[172:175], v[20:23]
	v_mfma_f32_16x16x32_bf16 v[16:19], v[216:219], v[172:175], v[16:19]
	v_mfma_f32_16x16x32_bf16 v[12:15], v[208:211], v[180:183], v[12:15]
	v_mfma_f32_16x16x32_bf16 v[8:11], v[216:219], v[180:183], v[8:11]
	v_mfma_f32_16x16x32_bf16 v[4:7], v[208:211], v[188:191], v[4:7]
	v_mfma_f32_16x16x32_bf16 v[0:3], v[216:219], v[188:191], v[0:3]
	s_setprio 0
	v_or_b32_e32 v143, 0x18000, v133
	v_add_u32_e32 v145, 0x18800, v133
	s_barrier
	v_add_u32_e32 v144, 0x18400, v133
	ds_read_b128 v[152:155], v143
	ds_read_b128 v[156:159], v144
	v_add_u32_e32 v146, 0x18c00, v133
	ds_read_b128 v[160:163], v145
	ds_read_b128 v[164:167], v146
	s_mov_b32 m0, s70
	v_lshl_add_u64 v[148:149], v[228:229], 0, s[74:75]
	s_mov_b64 s[92:93], 0x19cb0100
	ds_read_b128 v[168:171], v132 offset:32768
	ds_read_b128 v[172:175], v132 offset:33792
	ds_read_b128 v[176:179], v132 offset:34816
	ds_read_b128 v[180:183], v132 offset:35840
	ds_read_b128 v[184:187], v132 offset:36864
	ds_read_b128 v[188:191], v132 offset:37888
	ds_read_b128 v[204:207], v132 offset:38912
	ds_read_b128 v[208:211], v132 offset:39936
	global_load_lds_dwordx4 v[148:149], off
	v_lshl_add_u64 v[148:149], v[228:229], 0, s[92:93]
	s_mov_b32 m0, s71
	s_nop 0
	global_load_lds_dwordx4 v[148:149], off
	s_waitcnt lgkmcnt(8)
	s_barrier
	s_waitcnt lgkmcnt(0)
	s_setprio 1
	s_waitcnt lgkmcnt(0)
	v_mfma_f32_16x16x32_bf16 v[124:127], v[152:155], v[168:171], v[124:127]
	v_mfma_f32_16x16x32_bf16 v[120:123], v[160:163], v[168:171], v[120:123]
	v_mfma_f32_16x16x32_bf16 v[116:119], v[152:155], v[176:179], v[116:119]
	v_mfma_f32_16x16x32_bf16 v[112:115], v[160:163], v[176:179], v[112:115]
	v_mfma_f32_16x16x32_bf16 v[108:111], v[152:155], v[184:187], v[108:111]
	v_mfma_f32_16x16x32_bf16 v[104:107], v[160:163], v[184:187], v[104:107]
	v_mfma_f32_16x16x32_bf16 v[100:103], v[152:155], v[204:207], v[100:103]
	v_mfma_f32_16x16x32_bf16 v[96:99], v[160:163], v[204:207], v[96:99]
	v_mfma_f32_16x16x32_bf16 v[124:127], v[156:159], v[172:175], v[124:127]
	v_mfma_f32_16x16x32_bf16 v[120:123], v[164:167], v[172:175], v[120:123]
	v_mfma_f32_16x16x32_bf16 v[116:119], v[156:159], v[180:183], v[116:119]
	v_mfma_f32_16x16x32_bf16 v[112:115], v[164:167], v[180:183], v[112:115]
	v_mfma_f32_16x16x32_bf16 v[108:111], v[156:159], v[188:191], v[108:111]
	v_mfma_f32_16x16x32_bf16 v[104:107], v[164:167], v[188:191], v[104:107]
	v_mfma_f32_16x16x32_bf16 v[100:103], v[156:159], v[208:211], v[100:103]
	v_mfma_f32_16x16x32_bf16 v[96:99], v[164:167], v[208:211], v[96:99]
	s_setprio 0
	s_barrier
	s_mov_b64 s[92:93], 0xc00180
	s_mov_b32 m0, s72
	v_or_b32_e32 v147, 0x1c000, v133
	v_add_u32_e32 v149, 0x1c800, v133
	v_lshl_add_u64 v[232:233], v[230:231], 0, s[92:93]
	s_mov_b64 s[92:93], 0xc10180
	v_add_u32_e32 v148, 0x1c400, v133
	ds_read_b128 v[212:215], v147
	ds_read_b128 v[216:219], v148
	v_add_u32_e32 v150, 0x1cc00, v133
	ds_read_b128 v[220:223], v149
	ds_read_b128 v[224:227], v150
	global_load_lds_dwordx4 v[232:233], off
	v_lshl_add_u64 v[232:233], v[230:231], 0, s[92:93]
	s_mov_b32 m0, s73
	s_nop 0
	global_load_lds_dwordx4 v[232:233], off
	s_barrier
	s_waitcnt lgkmcnt(0)
	s_setprio 1
	s_waitcnt lgkmcnt(0)
	v_mfma_f32_16x16x32_bf16 v[92:95], v[212:215], v[168:171], v[92:95]
	v_mfma_f32_16x16x32_bf16 v[88:91], v[220:223], v[168:171], v[88:91]
	v_mfma_f32_16x16x32_bf16 v[84:87], v[212:215], v[176:179], v[84:87]
	v_mfma_f32_16x16x32_bf16 v[80:83], v[220:223], v[176:179], v[80:83]
	v_mfma_f32_16x16x32_bf16 v[76:79], v[212:215], v[184:187], v[76:79]
	v_mfma_f32_16x16x32_bf16 v[72:75], v[220:223], v[184:187], v[72:75]
	v_mfma_f32_16x16x32_bf16 v[68:71], v[212:215], v[204:207], v[68:71]
	v_mfma_f32_16x16x32_bf16 v[64:67], v[220:223], v[204:207], v[64:67]
	v_mfma_f32_16x16x32_bf16 v[92:95], v[216:219], v[172:175], v[92:95]
	v_mfma_f32_16x16x32_bf16 v[88:91], v[224:227], v[172:175], v[88:91]
	v_mfma_f32_16x16x32_bf16 v[84:87], v[216:219], v[180:183], v[84:87]
	v_mfma_f32_16x16x32_bf16 v[80:83], v[224:227], v[180:183], v[80:83]
	v_mfma_f32_16x16x32_bf16 v[76:79], v[216:219], v[188:191], v[76:79]
	v_mfma_f32_16x16x32_bf16 v[72:75], v[224:227], v[188:191], v[72:75]
	v_mfma_f32_16x16x32_bf16 v[68:71], v[216:219], v[208:211], v[68:71]
	v_mfma_f32_16x16x32_bf16 v[64:67], v[224:227], v[208:211], v[64:67]
	s_setprio 0
	s_mov_b32 m0, s81
	v_lshl_add_u64 v[232:233], v[228:229], 0, s[64:65]
	s_mov_b64 s[92:93], 0x19c90180
	s_barrier
; #define LDA8(dst, b, h)                                                                                               \
;   _Pragma("unroll") for (int m = 0; m < 4; ++m) _Pragma("unroll") for (int k = 0; k < 2; ++k)                         \
;     dst[m][k] = *(const bf16x8*)(SA8(b, h) + la + m * 2048 + k * 1024)
; #define LDB8(dst, b, h)                                                                                               \
;   _Pragma("unroll") for (int n = 0; n < 2; ++n) _Pragma("unroll") for (int k = 0; k < 2; ++k)                         \
;     dst[n][k] = *(const bf16x8*)(SB8(b, h) + lb + n * 2048 + k * 1024)
; #define WAITV8(n) asm volatile("s_waitcnt vmcnt(" #n ")" ::: "memory")
; #define WAITL8(n) asm volatile("s_waitcnt lgkmcnt(" #n ")" ::: "memory")
; #define BAR8 __builtin_amdgcn_s_barrier()
; #define SCHED8 __builtin_amdgcn_sched_barrier(0)
; template <class Epi>
; DEV void gemm_tile8(char* shm, const u16* __restrict__ A, const u16* __restrict__ Bt, int K, int brow, int bcol, Epi& epi) {
;     ...
;     LDA8(At, 1, 1); STAGE8(SA8(1, 0), A, brow, t + 3);
;     BAR8; WAITL8(0); MMA8(1, 0, At, B0); BAR8; SCHED8;
;     STAGE8(SB8(1, 1), Bt, bcol + HALF, t + 3);
;     WAITV8(6); BAR8; MMA8(1, 1, At, B1); BAR8;
;   }
;   { LDB8(B0, 0, 0); LDA8(At, 0, 0); STAGE8(SA8(1, 1), A, brow + HALF, nt - 1);
;     BAR8; WAITL8(0); MMA8(0, 0, At, B0); BAR8;
;     LDB8(B1, 0, 1); BAR8; WAITL8(0); MMA8(0, 1, At, B1); BAR8;
	ds_read_b128 v[168:171], v132 offset:49152
	ds_read_b128 v[172:175], v132 offset:50176
	ds_read_b128 v[176:179], v132 offset:51200
	ds_read_b128 v[180:183], v132 offset:52224
	ds_read_b128 v[184:187], v132 offset:53248
	ds_read_b128 v[188:191], v132 offset:54272
	ds_read_b128 v[204:207], v132 offset:55296
	ds_read_b128 v[208:211], v132 offset:56320
	global_load_lds_dwordx4 v[232:233], off
	v_lshl_add_u64 v[228:229], v[228:229], 0, s[92:93]
	s_mov_b32 m0, s84
	s_nop 0
	global_load_lds_dwordx4 v[228:229], off
	s_barrier
	s_waitcnt lgkmcnt(0)
	s_setprio 1
	s_waitcnt lgkmcnt(0)
	v_mfma_f32_16x16x32_bf16 v[60:63], v[152:155], v[168:171], v[60:63]
	v_mfma_f32_16x16x32_bf16 v[56:59], v[160:163], v[168:171], v[56:59]
	v_mfma_f32_16x16x32_bf16 v[52:55], v[152:155], v[176:179], v[52:55]
	v_mfma_f32_16x16x32_bf16 v[48:51], v[160:163], v[176:179], v[48:51]
	v_mfma_f32_16x16x32_bf16 v[44:47], v[152:155], v[184:187], v[44:47]
	v_mfma_f32_16x16x32_bf16 v[40:43], v[160:163], v[184:187], v[40:43]
	v_mfma_f32_16x16x32_bf16 v[36:39], v[152:155], v[204:207], v[36:39]
	v_mfma_f32_16x16x32_bf16 v[32:35], v[160:163], v[204:207], v[32:35]
	v_mfma_f32_16x16x32_bf16 v[60:63], v[156:159], v[172:175], v[60:63]
	v_mfma_f32_16x16x32_bf16 v[56:59], v[164:167], v[172:175], v[56:59]
	v_mfma_f32_16x16x32_bf16 v[52:55], v[156:159], v[180:183], v[52:55]
	v_mfma_f32_16x16x32_bf16 v[48:51], v[164:167], v[180:183], v[48:51]
	v_mfma_f32_16x16x32_bf16 v[44:47], v[156:159], v[188:191], v[44:47]
	v_mfma_f32_16x16x32_bf16 v[40:43], v[164:167], v[188:191], v[40:43]
	v_mfma_f32_16x16x32_bf16 v[36:39], v[156:159], v[208:211], v[36:39]
	v_mfma_f32_16x16x32_bf16 v[32:35], v[164:167], v[208:211], v[32:35]
	s_setprio 0
	s_barrier
	s_mov_b64 s[92:93], 0xc20180
	s_mov_b32 m0, s85
	v_lshl_add_u64 v[152:153], v[230:231], 0, s[92:93]
	s_mov_b64 s[92:93], 0xc30180
	global_load_lds_dwordx4 v[152:153], off
	v_lshl_add_u64 v[152:153], v[230:231], 0, s[92:93]
	s_mov_b32 m0, s90
	s_nop 0
	global_load_lds_dwordx4 v[152:153], off
	s_waitcnt vmcnt(6)
	s_barrier
	s_setprio 1
	v_mfma_f32_16x16x32_bf16 v[28:31], v[212:215], v[168:171], v[28:31]
	v_mfma_f32_16x16x32_bf16 v[24:27], v[220:223], v[168:171], v[24:27]
	v_mfma_f32_16x16x32_bf16 v[20:23], v[212:215], v[176:179], v[20:23]
	v_mfma_f32_16x16x32_bf16 v[16:19], v[220:223], v[176:179], v[16:19]
	v_mfma_f32_16x16x32_bf16 v[12:15], v[212:215], v[184:187], v[12:15]
	v_mfma_f32_16x16x32_bf16 v[8:11], v[220:223], v[184:187], v[8:11]
	v_mfma_f32_16x16x32_bf16 v[4:7], v[212:215], v[204:207], v[4:7]
	v_mfma_f32_16x16x32_bf16 v[0:3], v[220:223], v[204:207], v[0:3]
	v_mfma_f32_16x16x32_bf16 v[28:31], v[216:219], v[172:175], v[28:31]
	v_mfma_f32_16x16x32_bf16 v[24:27], v[224:227], v[172:175], v[24:27]
	v_mfma_f32_16x16x32_bf16 v[20:23], v[216:219], v[180:183], v[20:23]
	v_mfma_f32_16x16x32_bf16 v[16:19], v[224:227], v[180:183], v[16:19]
	v_mfma_f32_16x16x32_bf16 v[12:15], v[216:219], v[188:191], v[12:15]
	v_mfma_f32_16x16x32_bf16 v[8:11], v[224:227], v[188:191], v[8:11]
	v_mfma_f32_16x16x32_bf16 v[4:7], v[216:219], v[208:211], v[4:7]
	v_mfma_f32_16x16x32_bf16 v[0:3], v[224:227], v[208:211], v[0:3]
	s_setprio 0
	s_add_i32 s22, s22, 2
	s_add_u32 s18, s18, 0x100
	s_addc_u32 s19, s19, 0
	s_add_u32 s20, s20, 0x100
	s_addc_u32 s21, s21, 0
	s_cmp_lt_u32 s22, 4
	s_barrier
	s_cbranch_scc1 .LBB0_563
	s_mov_b64 s[18:19], 0x380
	s_mov_b32 m0, s91
	v_lshl_add_u64 v[130:131], v[128:129], 0, s[18:19]
	s_mov_b64 s[18:19], 0x10380
	s_waitcnt vmcnt(0)
	ds_read_b128 v[152:155], v134
	ds_read_b128 v[156:159], v135
	ds_read_b128 v[160:163], v136
	ds_read_b128 v[134:137], v137
	ds_read_b128 v[164:167], v132
	ds_read_b128 v[168:171], v132 offset:1024
	ds_read_b128 v[172:175], v132 offset:2048
	ds_read_b128 v[176:179], v132 offset:3072
	ds_read_b128 v[180:183], v132 offset:4096
	ds_read_b128 v[184:187], v132 offset:5120
	ds_read_b128 v[188:191], v132 offset:6144
	ds_read_b128 v[204:207], v132 offset:7168
	global_load_lds_dwordx4 v[130:131], off
	v_lshl_add_u64 v[128:129], v[128:129], 0, s[18:19]
	s_mov_b32 m0, s23
	s_nop 0
	global_load_lds_dwordx4 v[128:129], off
	s_barrier
	s_waitcnt lgkmcnt(0)
	s_setprio 1
	s_waitcnt lgkmcnt(0)
	v_mfma_f32_16x16x32_bf16 v[124:127], v[152:155], v[164:167], v[124:127]
	v_mfma_f32_16x16x32_bf16 v[120:123], v[160:163], v[164:167], v[120:123]
	v_mfma_f32_16x16x32_bf16 v[116:119], v[152:155], v[172:175], v[116:119]
	v_mfma_f32_16x16x32_bf16 v[112:115], v[160:163], v[172:175], v[112:115]
	v_mfma_f32_16x16x32_bf16 v[108:111], v[152:155], v[180:183], v[108:111]
	v_mfma_f32_16x16x32_bf16 v[104:107], v[160:163], v[180:183], v[104:107]
	v_mfma_f32_16x16x32_bf16 v[100:103], v[152:155], v[188:191], v[100:103]
	v_mfma_f32_16x16x32_bf16 v[96:99], v[160:163], v[188:191], v[96:99]
	v_mfma_f32_16x16x32_bf16 v[124:127], v[156:159], v[168:171], v[124:127]
	v_mfma_f32_16x16x32_bf16 v[120:123], v[134:137], v[168:171], v[120:123]
	v_mfma_f32_16x16x32_bf16 v[116:119], v[156:159], v[176:179], v[116:119]
	v_mfma_f32_16x16x32_bf16 v[112:115], v[134:137], v[176:179], v[112:115]
	v_mfma_f32_16x16x32_bf16 v[108:111], v[156:159], v[184:187], v[108:111]
	v_mfma_f32_16x16x32_bf16 v[104:107], v[134:137], v[184:187], v[104:107]
	v_mfma_f32_16x16x32_bf16 v[100:103], v[156:159], v[204:207], v[100:103]
	v_mfma_f32_16x16x32_bf16 v[96:99], v[134:137], v[204:207], v[96:99]
	s_setprio 0
	s_barrier
	s_waitcnt vmcnt(0)
	ds_read_b128 v[128:131], v138
	ds_read_b128 v[208:211], v139
	ds_read_b128 v[212:215], v140
	ds_read_b128 v[216:219], v142
	s_barrier
; #define LDA8(dst, b, h)                                                                                               \
;   _Pragma("unroll") for (int m = 0; m < 4; ++m) _Pragma("unroll") for (int k = 0; k < 2; ++k)                         \
;     dst[m][k] = *(const bf16x8*)(SA8(b, h) + la + m * 2048 + k * 1024)
; #define LDB8(dst, b, h)                                                                                               \
;   _Pragma("unroll") for (int n = 0; n < 2; ++n) _Pragma("unroll") for (int k = 0; k < 2; ++k)                         \
;     dst[n][k] = *(const bf16x8*)(SB8(b, h) + lb + n * 2048 + k * 1024)
; #define WAITV8(n) asm volatile("s_waitcnt vmcnt(" #n ")" ::: "memory")
; #define WAITL8(n) asm volatile("s_waitcnt lgkmcnt(" #n ")" ::: "memory")
; #define BAR8 __builtin_amdgcn_s_barrier()
; template <class Epi>
; DEV void gemm_tile8(char* shm, const u16* __restrict__ A, const u16* __restrict__ Bt, int K, int brow, int bcol, Epi& epi) {
;     ...
;     LDB8(B1, 0, 1); BAR8; WAITL8(0); MMA8(0, 1, At, B1); BAR8;
;     LDA8(At, 0, 1); WAITV8(4); BAR8; WAITL8(0); MMA8(1, 0, At, B0); MMA8(1, 1, At, B1); BAR8; }
;   { LDB8(B0, 1, 0); LDA8(At, 1, 0); WAITV8(2); BAR8; WAITL8(0); MMA8(0, 0, At, B0); BAR8;
	s_waitcnt lgkmcnt(0)
	s_setprio 1
	s_waitcnt lgkmcnt(3)
	v_mfma_f32_16x16x32_bf16 v[92:95], v[128:131], v[164:167], v[92:95]
	s_waitcnt lgkmcnt(1)
	v_mfma_f32_16x16x32_bf16 v[88:91], v[212:215], v[164:167], v[88:91]
	v_mfma_f32_16x16x32_bf16 v[84:87], v[128:131], v[172:175], v[84:87]
	v_mfma_f32_16x16x32_bf16 v[80:83], v[212:215], v[172:175], v[80:83]
	v_mfma_f32_16x16x32_bf16 v[76:79], v[128:131], v[180:183], v[76:79]
	v_mfma_f32_16x16x32_bf16 v[72:75], v[212:215], v[180:183], v[72:75]
	v_mfma_f32_16x16x32_bf16 v[68:71], v[128:131], v[188:191], v[68:71]
	v_mfma_f32_16x16x32_bf16 v[64:67], v[212:215], v[188:191], v[64:67]
	v_mfma_f32_16x16x32_bf16 v[220:223], v[208:211], v[168:171], v[92:95]
	s_waitcnt lgkmcnt(0)
	v_mfma_f32_16x16x32_bf16 v[164:167], v[216:219], v[168:171], v[88:91]
	v_mfma_f32_16x16x32_bf16 v[168:171], v[208:211], v[176:179], v[84:87]
	v_mfma_f32_16x16x32_bf16 v[172:175], v[216:219], v[176:179], v[80:83]
	v_mfma_f32_16x16x32_bf16 v[176:179], v[208:211], v[184:187], v[76:79]
	v_mfma_f32_16x16x32_bf16 v[180:183], v[216:219], v[184:187], v[72:75]
	v_mfma_f32_16x16x32_bf16 v[184:187], v[208:211], v[204:207], v[68:71]
	v_mfma_f32_16x16x32_bf16 v[188:191], v[216:219], v[204:207], v[64:67]
	s_setprio 0
	s_barrier
	s_nop 0
	ds_read_b128 v[64:67], v132 offset:16384
	ds_read_b128 v[68:71], v132 offset:17408
	ds_read_b128 v[72:75], v132 offset:18432
	ds_read_b128 v[76:79], v132 offset:19456
	ds_read_b128 v[80:83], v132 offset:20480
	ds_read_b128 v[84:87], v132 offset:21504
	ds_read_b128 v[88:91], v132 offset:22528
	ds_read_b128 v[92:95], v132 offset:23552
	s_waitcnt vmcnt(4)
	s_barrier
	s_waitcnt lgkmcnt(0)
	s_setprio 1
	s_waitcnt lgkmcnt(7)
	v_mfma_f32_16x16x32_bf16 v[60:63], v[152:155], v[64:67], v[60:63]
	v_mfma_f32_16x16x32_bf16 v[56:59], v[160:163], v[64:67], v[56:59]
	s_waitcnt lgkmcnt(5)
	v_mfma_f32_16x16x32_bf16 v[52:55], v[152:155], v[72:75], v[52:55]
	v_mfma_f32_16x16x32_bf16 v[48:51], v[160:163], v[72:75], v[48:51]
	s_waitcnt lgkmcnt(3)
	v_mfma_f32_16x16x32_bf16 v[44:47], v[152:155], v[80:83], v[44:47]
	v_mfma_f32_16x16x32_bf16 v[40:43], v[160:163], v[80:83], v[40:43]
	s_waitcnt lgkmcnt(1)
	v_mfma_f32_16x16x32_bf16 v[36:39], v[152:155], v[88:91], v[36:39]
	v_mfma_f32_16x16x32_bf16 v[32:35], v[160:163], v[88:91], v[32:35]
	v_mfma_f32_16x16x32_bf16 v[60:63], v[156:159], v[68:71], v[60:63]
	v_mfma_f32_16x16x32_bf16 v[56:59], v[134:137], v[68:71], v[56:59]
	v_mfma_f32_16x16x32_bf16 v[52:55], v[156:159], v[76:79], v[52:55]
	v_mfma_f32_16x16x32_bf16 v[48:51], v[134:137], v[76:79], v[48:51]
	v_mfma_f32_16x16x32_bf16 v[44:47], v[156:159], v[84:87], v[44:47]
	v_mfma_f32_16x16x32_bf16 v[40:43], v[134:137], v[84:87], v[40:43]
	s_waitcnt lgkmcnt(0)
	v_mfma_f32_16x16x32_bf16 v[36:39], v[156:159], v[92:95], v[36:39]
	v_mfma_f32_16x16x32_bf16 v[32:35], v[134:137], v[92:95], v[32:35]
	s_setprio 0
	s_setprio 1
	v_mfma_f32_16x16x32_bf16 v[28:31], v[128:131], v[64:67], v[28:31]
	v_mfma_f32_16x16x32_bf16 v[24:27], v[212:215], v[64:67], v[24:27]
	v_mfma_f32_16x16x32_bf16 v[20:23], v[128:131], v[72:75], v[20:23]
	v_mfma_f32_16x16x32_bf16 v[16:19], v[212:215], v[72:75], v[16:19]
	v_mfma_f32_16x16x32_bf16 v[12:15], v[128:131], v[80:83], v[12:15]
	v_mfma_f32_16x16x32_bf16 v[8:11], v[212:215], v[80:83], v[8:11]
	v_mfma_f32_16x16x32_bf16 v[4:7], v[128:131], v[88:91], v[4:7]
	v_mfma_f32_16x16x32_bf16 v[0:3], v[212:215], v[88:91], v[0:3]
	v_mfma_f32_16x16x32_bf16 v[134:137], v[208:211], v[68:71], v[28:31]
	v_mfma_f32_16x16x32_bf16 v[152:155], v[216:219], v[68:71], v[24:27]
	v_mfma_f32_16x16x32_bf16 v[156:159], v[208:211], v[76:79], v[20:23]
	v_mfma_f32_16x16x32_bf16 v[160:163], v[216:219], v[76:79], v[16:19]
	v_mfma_f32_16x16x32_bf16 v[204:207], v[208:211], v[84:87], v[12:15]
	v_mfma_f32_16x16x32_bf16 v[224:227], v[216:219], v[84:87], v[8:11]
	v_mfma_f32_16x16x32_bf16 v[128:131], v[208:211], v[92:95], v[4:7]
	v_mfma_f32_16x16x32_bf16 v[208:211], v[216:219], v[92:95], v[0:3]
	s_setprio 0
	s_barrier
	ds_read_b128 v[24:27], v143
	ds_read_b128 v[28:31], v144
	ds_read_b128 v[142:145], v145
	ds_read_b128 v[212:215], v146
	ds_read_b128 v[0:3], v132 offset:32768
	ds_read_b128 v[4:7], v132 offset:33792
	ds_read_b128 v[8:11], v132 offset:34816
	ds_read_b128 v[12:15], v132 offset:35840
	ds_read_b128 v[16:19], v132 offset:36864
	ds_read_b128 v[20:23], v132 offset:37888
	ds_read_b128 v[216:219], v132 offset:38912
	ds_read_b128 v[228:231], v132 offset:39936
	s_waitcnt vmcnt(2)
	s_barrier
; #define LDA8(dst, b, h)                                                                                               \
;   _Pragma("unroll") for (int m = 0; m < 4; ++m) _Pragma("unroll") for (int k = 0; k < 2; ++k)                         \
;     dst[m][k] = *(const bf16x8*)(SA8(b, h) + la + m * 2048 + k * 1024)
; #define LDB8(dst, b, h)                                                                                               \
;   _Pragma("unroll") for (int n = 0; n < 2; ++n) _Pragma("unroll") for (int k = 0; k < 2; ++k)                         \
;     dst[n][k] = *(const bf16x8*)(SB8(b, h) + lb + n * 2048 + k * 1024)
; #define WAITV8(n) asm volatile("s_waitcnt vmcnt(" #n ")" ::: "memory")
; #define WAITL8(n) asm volatile("s_waitcnt lgkmcnt(" #n ")" ::: "memory")
; #define BAR8 __builtin_amdgcn_s_barrier()
; template <class Epi>
; DEV void gemm_tile8(char* shm, const u16* __restrict__ A, const u16* __restrict__ Bt, int K, int brow, int bcol, Epi& epi) {
;     ...
;   { LDB8(B0, 1, 0); LDA8(At, 1, 0); WAITV8(2); BAR8; WAITL8(0); MMA8(0, 0, At, B0); BAR8;
;     LDB8(B1, 1, 1); WAITV8(0); BAR8; WAITL8(0); MMA8(0, 1, At, B1); BAR8;
;     LDA8(At, 1, 1); BAR8; WAITL8(0); MMA8(1, 0, At, B0); MMA8(1, 1, At, B1); BAR8; }
;   if (wrs == 0) BAR8;
	s_waitcnt lgkmcnt(0)
	s_setprio 1
	s_waitcnt lgkmcnt(7)
	v_mfma_f32_16x16x32_bf16 v[64:67], v[24:27], v[0:3], v[124:127]
	s_waitcnt lgkmcnt(6)
	v_mfma_f32_16x16x32_bf16 v[72:75], v[28:31], v[4:7], v[64:67]
	v_mfma_f32_16x16x32_bf16 v[64:67], v[142:145], v[0:3], v[120:123]
	s_waitcnt lgkmcnt(5)
	v_mfma_f32_16x16x32_bf16 v[68:71], v[24:27], v[8:11], v[116:119]
	v_mfma_f32_16x16x32_bf16 v[76:79], v[142:145], v[8:11], v[112:115]
	s_waitcnt lgkmcnt(3)
	v_mfma_f32_16x16x32_bf16 v[80:83], v[24:27], v[16:19], v[108:111]
	v_mfma_f32_16x16x32_bf16 v[84:87], v[142:145], v[16:19], v[104:107]
	s_waitcnt lgkmcnt(1)
	v_mfma_f32_16x16x32_bf16 v[88:91], v[24:27], v[216:219], v[100:103]
	v_mfma_f32_16x16x32_bf16 v[92:95], v[142:145], v[216:219], v[96:99]
	v_mfma_f32_16x16x32_bf16 v[64:67], v[212:215], v[4:7], v[64:67]
	v_mfma_f32_16x16x32_bf16 v[68:71], v[28:31], v[12:15], v[68:71]
	v_mfma_f32_16x16x32_bf16 v[76:79], v[212:215], v[12:15], v[76:79]
	v_mfma_f32_16x16x32_bf16 v[80:83], v[28:31], v[20:23], v[80:83]
	v_mfma_f32_16x16x32_bf16 v[84:87], v[212:215], v[20:23], v[84:87]
	s_waitcnt lgkmcnt(0)
	v_mfma_f32_16x16x32_bf16 v[88:91], v[28:31], v[228:231], v[88:91]
	v_mfma_f32_16x16x32_bf16 v[92:95], v[212:215], v[228:231], v[92:95]
	s_setprio 0
	s_barrier
	ds_read_b128 v[232:235], v147
	ds_read_b128 v[236:239], v148
	ds_read_b128 v[146:149], v149
	ds_read_b128 v[240:243], v150
	s_waitcnt vmcnt(0)
	s_barrier
	s_waitcnt lgkmcnt(0)
	s_setprio 1
	s_waitcnt lgkmcnt(3)
	v_mfma_f32_16x16x32_bf16 v[96:99], v[232:235], v[0:3], v[220:223]
	s_waitcnt lgkmcnt(1)
	v_mfma_f32_16x16x32_bf16 v[0:3], v[146:149], v[0:3], v[164:167]
	v_mfma_f32_16x16x32_bf16 v[104:107], v[236:239], v[4:7], v[96:99]
	s_waitcnt lgkmcnt(0)
	v_mfma_f32_16x16x32_bf16 v[96:99], v[240:243], v[4:7], v[0:3]
	v_mfma_f32_16x16x32_bf16 v[0:3], v[232:235], v[8:11], v[168:171]
	v_mfma_f32_16x16x32_bf16 v[100:103], v[236:239], v[12:15], v[0:3]
	v_mfma_f32_16x16x32_bf16 v[0:3], v[146:149], v[8:11], v[172:175]
	v_mfma_f32_16x16x32_bf16 v[108:111], v[240:243], v[12:15], v[0:3]
	v_mfma_f32_16x16x32_bf16 v[0:3], v[232:235], v[16:19], v[176:179]
	v_mfma_f32_16x16x32_bf16 v[112:115], v[236:239], v[20:23], v[0:3]
	v_mfma_f32_16x16x32_bf16 v[0:3], v[146:149], v[16:19], v[180:183]
	v_mfma_f32_16x16x32_bf16 v[116:119], v[240:243], v[20:23], v[0:3]
	v_mfma_f32_16x16x32_bf16 v[0:3], v[232:235], v[216:219], v[184:187]
	v_mfma_f32_16x16x32_bf16 v[120:123], v[236:239], v[228:231], v[0:3]
	v_mfma_f32_16x16x32_bf16 v[0:3], v[146:149], v[216:219], v[188:191]
	v_mfma_f32_16x16x32_bf16 v[124:127], v[240:243], v[228:231], v[0:3]
	s_setprio 0
	s_barrier
	ds_read_b128 v[164:167], v132 offset:49152
	ds_read_b128 v[168:171], v132 offset:50176
	ds_read_b128 v[172:175], v132 offset:51200
	ds_read_b128 v[176:179], v132 offset:52224
	ds_read_b128 v[180:183], v132 offset:53248
	ds_read_b128 v[184:187], v132 offset:54272
	ds_read_b128 v[188:191], v132 offset:55296
	ds_read_b128 v[216:219], v132 offset:56320
	s_barrier
	s_waitcnt lgkmcnt(0)
	s_setprio 1
	s_waitcnt lgkmcnt(7)
	v_mfma_f32_16x16x32_bf16 v[0:3], v[24:27], v[164:167], v[60:63]
	s_waitcnt lgkmcnt(5)
	v_mfma_f32_16x16x32_bf16 v[8:11], v[24:27], v[172:175], v[52:55]
	s_waitcnt lgkmcnt(3)
	v_mfma_f32_16x16x32_bf16 v[16:19], v[24:27], v[180:183], v[44:47]
	s_waitcnt lgkmcnt(1)
	v_mfma_f32_16x16x32_bf16 v[24:27], v[24:27], v[188:191], v[36:39]
	v_mfma_f32_16x16x32_bf16 v[0:3], v[28:31], v[168:171], v[0:3]
	v_mfma_f32_16x16x32_bf16 v[4:7], v[142:145], v[164:167], v[56:59]
	v_mfma_f32_16x16x32_bf16 v[8:11], v[28:31], v[176:179], v[8:11]
	v_mfma_f32_16x16x32_bf16 v[12:15], v[142:145], v[172:175], v[48:51]
	v_mfma_f32_16x16x32_bf16 v[16:19], v[28:31], v[184:187], v[16:19]
	v_mfma_f32_16x16x32_bf16 v[20:23], v[142:145], v[180:183], v[40:43]
	s_waitcnt lgkmcnt(0)
	v_mfma_f32_16x16x32_bf16 v[24:27], v[28:31], v[216:219], v[24:27]
	v_mfma_f32_16x16x32_bf16 v[28:31], v[142:145], v[188:191], v[32:35]
	v_mfma_f32_16x16x32_bf16 v[4:7], v[212:215], v[168:171], v[4:7]
	v_mfma_f32_16x16x32_bf16 v[12:15], v[212:215], v[176:179], v[12:15]
	v_mfma_f32_16x16x32_bf16 v[20:23], v[212:215], v[184:187], v[20:23]
	v_mfma_f32_16x16x32_bf16 v[28:31], v[212:215], v[216:219], v[28:31]
	s_setprio 0
	s_setprio 1
	v_mfma_f32_16x16x32_bf16 v[32:35], v[232:235], v[164:167], v[134:137]
	v_mfma_f32_16x16x32_bf16 v[36:39], v[146:149], v[164:167], v[152:155]
	v_mfma_f32_16x16x32_bf16 v[40:43], v[232:235], v[172:175], v[156:159]
	v_mfma_f32_16x16x32_bf16 v[44:47], v[146:149], v[172:175], v[160:163]
	v_mfma_f32_16x16x32_bf16 v[48:51], v[232:235], v[180:183], v[204:207]
	v_mfma_f32_16x16x32_bf16 v[52:55], v[146:149], v[180:183], v[224:227]
	v_mfma_f32_16x16x32_bf16 v[56:59], v[232:235], v[188:191], v[128:131]
	v_mfma_f32_16x16x32_bf16 v[60:63], v[146:149], v[188:191], v[208:211]
	v_mfma_f32_16x16x32_bf16 v[32:35], v[236:239], v[168:171], v[32:35]
	v_mfma_f32_16x16x32_bf16 v[36:39], v[240:243], v[168:171], v[36:39]
	v_mfma_f32_16x16x32_bf16 v[40:43], v[236:239], v[176:179], v[40:43]
	v_mfma_f32_16x16x32_bf16 v[44:47], v[240:243], v[176:179], v[44:47]
	v_mfma_f32_16x16x32_bf16 v[48:51], v[236:239], v[184:187], v[48:51]
	v_mfma_f32_16x16x32_bf16 v[52:55], v[240:243], v[184:187], v[52:55]
	v_mfma_f32_16x16x32_bf16 v[56:59], v[236:239], v[216:219], v[56:59]
	v_mfma_f32_16x16x32_bf16 v[60:63], v[240:243], v[216:219], v[60:63]
	s_setprio 0
	s_cmp_lg_u32 s7, 0
	s_barrier
	s_cbranch_scc1 .LBB0_566
	s_barrier

; #define LDA8(dst, b, h)                                                                                               \
;   _Pragma("unroll") for (int m = 0; m < 4; ++m) _Pragma("unroll") for (int k = 0; k < 2; ++k)                         \
;     dst[m][k] = *(const bf16x8*)(SA8(b, h) + la + m * 2048 + k * 1024)
; #define LDB8(dst, b, h)                                                                                               \
;   _Pragma("unroll") for (int n = 0; n < 2; ++n) _Pragma("unroll") for (int k = 0; k < 2; ++k)                         \
;     dst[n][k] = *(const bf16x8*)(SB8(b, h) + lb + n * 2048 + k * 1024)
; #define WAITL8(n) asm volatile("s_waitcnt lgkmcnt(" #n ")" ::: "memory")
; #define BAR8 __builtin_amdgcn_s_barrier()
; #define SCHED8 __builtin_amdgcn_sched_barrier(0)
; template <class Epi>
; DEV void gemm_tile8(char* shm, const u16* __restrict__ A, const u16* __restrict__ Bt, int K, int brow, int bcol, Epi& epi) {
;     ...
;     LDB8(B0, 0, 0); SCHED8; LDA8(At, 0, 0); STAGE8(SA8(1, 1), A, brow + HALF, t + 1);
;     WAITL8(8); BAR8; WAITL8(0); MMA8(0, 0, At, B0); BAR8; SCHED8;
;     LDB8(B1, 0, 1); STAGE8(SB8(0, 0), Bt, bcol, t + 2);
;     BAR8; WAITL8(0); MMA8(0, 1, At, B1); BAR8;
;     LDA8(At, 0, 1); STAGE8(SA8(0, 0), A, brow, t + 2);
;     BAR8; WAITL8(0); MMA8(1, 0, At, B0); BAR8; SCHED8;
.LBB0_599:
	v_or_b32_e32 v134, 0x10000, v133
	v_add_u32_e32 v136, 0x10800, v133
	v_add_u32_e32 v135, 0x10400, v133
	ds_read_b128 v[144:147], v134
	ds_read_b128 v[148:151], v135
	v_add_u32_e32 v137, 0x10c00, v133
	ds_read_b128 v[152:155], v136
	ds_read_b128 v[156:159], v137
	v_lshl_add_u64 v[228:229], s[18:19], 0, v[130:131]
	s_mov_b64 s[92:93], 0x1aca0080
	s_add_i32 s91, s40, 0xc000
	v_lshl_add_u64 v[138:139], v[228:229], 0, s[92:93]
	s_mov_b32 m0, s91
	s_mov_b64 s[92:93], 0x1acb0080
	s_add_i32 s23, s40, 0xe000
	ds_read_b128 v[160:163], v132
	ds_read_b128 v[164:167], v132 offset:1024
	ds_read_b128 v[168:171], v132 offset:2048
	ds_read_b128 v[172:175], v132 offset:3072
	ds_read_b128 v[176:179], v132 offset:4096
	ds_read_b128 v[180:183], v132 offset:5120
	ds_read_b128 v[184:187], v132 offset:6144
	ds_read_b128 v[188:191], v132 offset:7168
	global_load_lds_dwordx4 v[138:139], off
	v_lshl_add_u64 v[138:139], v[228:229], 0, s[92:93]
	s_mov_b32 m0, s23
	s_nop 0
	global_load_lds_dwordx4 v[138:139], off
	s_waitcnt lgkmcnt(8)
	s_barrier
	s_waitcnt lgkmcnt(0)
	s_setprio 1
	s_waitcnt lgkmcnt(0)
	v_mfma_f32_16x16x32_bf16 v[124:127], v[144:147], v[160:163], v[124:127]
	v_mfma_f32_16x16x32_bf16 v[120:123], v[152:155], v[160:163], v[120:123]
	v_mfma_f32_16x16x32_bf16 v[116:119], v[144:147], v[168:171], v[116:119]
	v_mfma_f32_16x16x32_bf16 v[112:115], v[152:155], v[168:171], v[112:115]
	v_mfma_f32_16x16x32_bf16 v[108:111], v[144:147], v[176:179], v[108:111]
	v_mfma_f32_16x16x32_bf16 v[104:107], v[152:155], v[176:179], v[104:107]
	v_mfma_f32_16x16x32_bf16 v[100:103], v[144:147], v[184:187], v[100:103]
	v_mfma_f32_16x16x32_bf16 v[96:99], v[152:155], v[184:187], v[96:99]
	v_mfma_f32_16x16x32_bf16 v[124:127], v[148:151], v[164:167], v[124:127]
	v_mfma_f32_16x16x32_bf16 v[120:123], v[156:159], v[164:167], v[120:123]
	v_mfma_f32_16x16x32_bf16 v[116:119], v[148:151], v[172:175], v[116:119]
	v_mfma_f32_16x16x32_bf16 v[112:115], v[156:159], v[172:175], v[112:115]
	v_mfma_f32_16x16x32_bf16 v[108:111], v[148:151], v[180:183], v[108:111]
	v_mfma_f32_16x16x32_bf16 v[104:107], v[156:159], v[180:183], v[104:107]
	v_mfma_f32_16x16x32_bf16 v[100:103], v[148:151], v[188:191], v[100:103]
	v_mfma_f32_16x16x32_bf16 v[96:99], v[156:159], v[188:191], v[96:99]
	s_setprio 0
	s_barrier
	v_lshl_add_u64 v[230:231], s[20:21], 0, v[130:131]
	s_mov_b64 s[92:93], 0xb00100
	s_mov_b32 m0, s41
	v_or_b32_e32 v138, 0x14000, v133
	v_add_u32_e32 v140, 0x14800, v133
	v_lshl_add_u64 v[220:221], v[230:231], 0, s[92:93]
	s_mov_b64 s[92:93], 0xb10100
	v_add_u32_e32 v139, 0x14400, v133
	ds_read_b128 v[204:207], v138
	ds_read_b128 v[208:211], v139
	v_add_u32_e32 v142, 0x14c00, v133
	ds_read_b128 v[212:215], v140
	ds_read_b128 v[216:219], v142
	global_load_lds_dwordx4 v[220:221], off
	v_lshl_add_u64 v[220:221], v[230:231], 0, s[92:93]
	s_mov_b32 m0, s45
	s_nop 0
	global_load_lds_dwordx4 v[220:221], off
	s_barrier
	s_waitcnt lgkmcnt(0)
	s_setprio 1
	s_waitcnt lgkmcnt(0)
	v_mfma_f32_16x16x32_bf16 v[92:95], v[204:207], v[160:163], v[92:95]
	v_mfma_f32_16x16x32_bf16 v[88:91], v[212:215], v[160:163], v[88:91]
	v_mfma_f32_16x16x32_bf16 v[84:87], v[204:207], v[168:171], v[84:87]
	v_mfma_f32_16x16x32_bf16 v[80:83], v[212:215], v[168:171], v[80:83]
	v_mfma_f32_16x16x32_bf16 v[76:79], v[204:207], v[176:179], v[76:79]
	v_mfma_f32_16x16x32_bf16 v[72:75], v[212:215], v[176:179], v[72:75]
	v_mfma_f32_16x16x32_bf16 v[68:71], v[204:207], v[184:187], v[68:71]
	v_mfma_f32_16x16x32_bf16 v[64:67], v[212:215], v[184:187], v[64:67]
	v_mfma_f32_16x16x32_bf16 v[92:95], v[208:211], v[164:167], v[92:95]
	v_mfma_f32_16x16x32_bf16 v[88:91], v[216:219], v[164:167], v[88:91]
	v_mfma_f32_16x16x32_bf16 v[84:87], v[208:211], v[172:175], v[84:87]
	v_mfma_f32_16x16x32_bf16 v[80:83], v[216:219], v[172:175], v[80:83]
	v_mfma_f32_16x16x32_bf16 v[76:79], v[208:211], v[180:183], v[76:79]
	v_mfma_f32_16x16x32_bf16 v[72:75], v[216:219], v[180:183], v[72:75]
	v_mfma_f32_16x16x32_bf16 v[68:71], v[208:211], v[188:191], v[68:71]
	v_mfma_f32_16x16x32_bf16 v[64:67], v[216:219], v[188:191], v[64:67]
	s_setprio 0
	s_mov_b64 s[92:93], 0x1ac80100
	s_mov_b32 m0, s40
	v_lshl_add_u64 v[220:221], v[228:229], 0, s[92:93]
	s_mov_b64 s[92:93], 0x1ac90100
	s_barrier
	ds_read_b128 v[160:163], v132 offset:16384
	ds_read_b128 v[164:167], v132 offset:17408
	ds_read_b128 v[168:171], v132 offset:18432
	ds_read_b128 v[172:175], v132 offset:19456
	ds_read_b128 v[176:179], v132 offset:20480
	ds_read_b128 v[180:183], v132 offset:21504
	ds_read_b128 v[184:187], v132 offset:22528
	ds_read_b128 v[188:191], v132 offset:23552
	global_load_lds_dwordx4 v[220:221], off
	v_lshl_add_u64 v[220:221], v[228:229], 0, s[92:93]
	s_mov_b32 m0, s48
	s_nop 0
	global_load_lds_dwordx4 v[220:221], off
	s_barrier
	s_waitcnt lgkmcnt(0)
	s_setprio 1
	s_waitcnt lgkmcnt(0)
	v_mfma_f32_16x16x32_bf16 v[60:63], v[144:147], v[160:163], v[60:63]
	v_mfma_f32_16x16x32_bf16 v[56:59], v[152:155], v[160:163], v[56:59]
	v_mfma_f32_16x16x32_bf16 v[52:55], v[144:147], v[168:171], v[52:55]
	v_mfma_f32_16x16x32_bf16 v[48:51], v[152:155], v[168:171], v[48:51]
	v_mfma_f32_16x16x32_bf16 v[44:47], v[144:147], v[176:179], v[44:47]
	v_mfma_f32_16x16x32_bf16 v[40:43], v[152:155], v[176:179], v[40:43]
	v_mfma_f32_16x16x32_bf16 v[36:39], v[144:147], v[184:187], v[36:39]
	v_mfma_f32_16x16x32_bf16 v[32:35], v[152:155], v[184:187], v[32:35]
	v_mfma_f32_16x16x32_bf16 v[60:63], v[148:151], v[164:167], v[60:63]
	v_mfma_f32_16x16x32_bf16 v[56:59], v[156:159], v[164:167], v[56:59]
	v_mfma_f32_16x16x32_bf16 v[52:55], v[148:151], v[172:175], v[52:55]
	v_mfma_f32_16x16x32_bf16 v[48:51], v[156:159], v[172:175], v[48:51]
	v_mfma_f32_16x16x32_bf16 v[44:47], v[148:151], v[180:183], v[44:47]
	v_mfma_f32_16x16x32_bf16 v[40:43], v[156:159], v[180:183], v[40:43]
	v_mfma_f32_16x16x32_bf16 v[36:39], v[148:151], v[188:191], v[36:39]
	v_mfma_f32_16x16x32_bf16 v[32:35], v[156:159], v[188:191], v[32:35]
	s_setprio 0
	s_barrier
; #define LDA8(dst, b, h)                                                                                               \
;   _Pragma("unroll") for (int m = 0; m < 4; ++m) _Pragma("unroll") for (int k = 0; k < 2; ++k)                         \
;     dst[m][k] = *(const bf16x8*)(SA8(b, h) + la + m * 2048 + k * 1024)
; #define LDB8(dst, b, h)                                                                                               \
;   _Pragma("unroll") for (int n = 0; n < 2; ++n) _Pragma("unroll") for (int k = 0; k < 2; ++k)                         \
;     dst[n][k] = *(const bf16x8*)(SB8(b, h) + lb + n * 2048 + k * 1024)
; #define WAITV8(n) asm volatile("s_waitcnt vmcnt(" #n ")" ::: "memory")
; #define WAITL8(n) asm volatile("s_waitcnt lgkmcnt(" #n ")" ::: "memory")
; #define BAR8 __builtin_amdgcn_s_barrier()
; #define SCHED8 __builtin_amdgcn_sched_barrier(0)
; template <class Epi>
; DEV void gemm_tile8(char* shm, const u16* __restrict__ A, const u16* __restrict__ Bt, int K, int brow, int bcol, Epi& epi) {
;     ...
;     STAGE8(SB8(0, 1), Bt, bcol + HALF, t + 2);
;     WAITV8(6); BAR8; MMA8(1, 1, At, B1); BAR8;
;     LDB8(B0, 1, 0); SCHED8; LDA8(At, 1, 0); STAGE8(SA8(0, 1), A, brow + HALF, t + 2);
;     WAITL8(8); BAR8; WAITL8(0); MMA8(0, 0, At, B0); BAR8; SCHED8;
;     LDB8(B1, 1, 1); STAGE8(SB8(1, 0), Bt, bcol, t + 3);
;     BAR8; WAITL8(0); MMA8(0, 1, At, B1); BAR8;
	s_mov_b64 s[92:93], 0xb20100
	s_mov_b32 m0, s54
	v_lshl_add_u64 v[144:145], v[230:231], 0, s[92:93]
	s_mov_b64 s[92:93], 0xb30100
	global_load_lds_dwordx4 v[144:145], off
	v_lshl_add_u64 v[144:145], v[230:231], 0, s[92:93]
	s_mov_b32 m0, s55
	s_nop 0
	global_load_lds_dwordx4 v[144:145], off
	s_waitcnt vmcnt(6)
	s_barrier
	s_setprio 1
	v_mfma_f32_16x16x32_bf16 v[28:31], v[204:207], v[160:163], v[28:31]
	v_mfma_f32_16x16x32_bf16 v[24:27], v[212:215], v[160:163], v[24:27]
	v_mfma_f32_16x16x32_bf16 v[20:23], v[204:207], v[168:171], v[20:23]
	v_mfma_f32_16x16x32_bf16 v[16:19], v[212:215], v[168:171], v[16:19]
	v_mfma_f32_16x16x32_bf16 v[12:15], v[204:207], v[176:179], v[12:15]
	v_mfma_f32_16x16x32_bf16 v[8:11], v[212:215], v[176:179], v[8:11]
	v_mfma_f32_16x16x32_bf16 v[4:7], v[204:207], v[184:187], v[4:7]
	v_mfma_f32_16x16x32_bf16 v[0:3], v[212:215], v[184:187], v[0:3]
	v_mfma_f32_16x16x32_bf16 v[28:31], v[208:211], v[164:167], v[28:31]
	v_mfma_f32_16x16x32_bf16 v[24:27], v[216:219], v[164:167], v[24:27]
	v_mfma_f32_16x16x32_bf16 v[20:23], v[208:211], v[172:175], v[20:23]
	v_mfma_f32_16x16x32_bf16 v[16:19], v[216:219], v[172:175], v[16:19]
	v_mfma_f32_16x16x32_bf16 v[12:15], v[208:211], v[180:183], v[12:15]
	v_mfma_f32_16x16x32_bf16 v[8:11], v[216:219], v[180:183], v[8:11]
	v_mfma_f32_16x16x32_bf16 v[4:7], v[208:211], v[188:191], v[4:7]
	v_mfma_f32_16x16x32_bf16 v[0:3], v[216:219], v[188:191], v[0:3]
	s_setprio 0
	v_or_b32_e32 v143, 0x18000, v133
	v_add_u32_e32 v145, 0x18800, v133
	s_barrier
	v_add_u32_e32 v144, 0x18400, v133
	ds_read_b128 v[152:155], v143
	ds_read_b128 v[156:159], v144
	v_add_u32_e32 v146, 0x18c00, v133
	ds_read_b128 v[160:163], v145
	ds_read_b128 v[164:167], v146
	s_mov_b64 s[92:93], 0x1aca0100
	s_mov_b32 m0, s70
	v_lshl_add_u64 v[148:149], v[228:229], 0, s[92:93]
	s_mov_b64 s[92:93], 0x1acb0100
	ds_read_b128 v[168:171], v132 offset:32768
	ds_read_b128 v[172:175], v132 offset:33792
	ds_read_b128 v[176:179], v132 offset:34816
	ds_read_b128 v[180:183], v132 offset:35840
	ds_read_b128 v[184:187], v132 offset:36864
	ds_read_b128 v[188:191], v132 offset:37888
	ds_read_b128 v[204:207], v132 offset:38912
	ds_read_b128 v[208:211], v132 offset:39936
	global_load_lds_dwordx4 v[148:149], off
	v_lshl_add_u64 v[148:149], v[228:229], 0, s[92:93]
	s_mov_b32 m0, s71
	s_nop 0
	global_load_lds_dwordx4 v[148:149], off
	s_waitcnt lgkmcnt(8)
	s_barrier
	s_waitcnt lgkmcnt(0)
	s_setprio 1
	s_waitcnt lgkmcnt(0)
	v_mfma_f32_16x16x32_bf16 v[124:127], v[152:155], v[168:171], v[124:127]
	v_mfma_f32_16x16x32_bf16 v[120:123], v[160:163], v[168:171], v[120:123]
	v_mfma_f32_16x16x32_bf16 v[116:119], v[152:155], v[176:179], v[116:119]
	v_mfma_f32_16x16x32_bf16 v[112:115], v[160:163], v[176:179], v[112:115]
	v_mfma_f32_16x16x32_bf16 v[108:111], v[152:155], v[184:187], v[108:111]
	v_mfma_f32_16x16x32_bf16 v[104:107], v[160:163], v[184:187], v[104:107]
	v_mfma_f32_16x16x32_bf16 v[100:103], v[152:155], v[204:207], v[100:103]
	v_mfma_f32_16x16x32_bf16 v[96:99], v[160:163], v[204:207], v[96:99]
	v_mfma_f32_16x16x32_bf16 v[124:127], v[156:159], v[172:175], v[124:127]
	v_mfma_f32_16x16x32_bf16 v[120:123], v[164:167], v[172:175], v[120:123]
	v_mfma_f32_16x16x32_bf16 v[116:119], v[156:159], v[180:183], v[116:119]
	v_mfma_f32_16x16x32_bf16 v[112:115], v[164:167], v[180:183], v[112:115]
	v_mfma_f32_16x16x32_bf16 v[108:111], v[156:159], v[188:191], v[108:111]
	v_mfma_f32_16x16x32_bf16 v[104:107], v[164:167], v[188:191], v[104:107]
	v_mfma_f32_16x16x32_bf16 v[100:103], v[156:159], v[208:211], v[100:103]
	v_mfma_f32_16x16x32_bf16 v[96:99], v[164:167], v[208:211], v[96:99]
	s_setprio 0
	s_barrier
	s_mov_b64 s[92:93], 0xb00180
	s_mov_b32 m0, s72
	v_or_b32_e32 v147, 0x1c000, v133
	v_add_u32_e32 v149, 0x1c800, v133
	v_lshl_add_u64 v[232:233], v[230:231], 0, s[92:93]
	s_mov_b64 s[92:93], 0xb10180
	v_add_u32_e32 v148, 0x1c400, v133
	ds_read_b128 v[212:215], v147
	ds_read_b128 v[216:219], v148
	v_add_u32_e32 v150, 0x1cc00, v133
	ds_read_b128 v[220:223], v149
	ds_read_b128 v[224:227], v150
	global_load_lds_dwordx4 v[232:233], off
	v_lshl_add_u64 v[232:233], v[230:231], 0, s[92:93]
	s_mov_b32 m0, s73
	s_nop 0
	global_load_lds_dwordx4 v[232:233], off
	s_barrier
	s_waitcnt lgkmcnt(0)
	s_setprio 1
	s_waitcnt lgkmcnt(0)
	v_mfma_f32_16x16x32_bf16 v[92:95], v[212:215], v[168:171], v[92:95]
	v_mfma_f32_16x16x32_bf16 v[88:91], v[220:223], v[168:171], v[88:91]
	v_mfma_f32_16x16x32_bf16 v[84:87], v[212:215], v[176:179], v[84:87]
	v_mfma_f32_16x16x32_bf16 v[80:83], v[220:223], v[176:179], v[80:83]
	v_mfma_f32_16x16x32_bf16 v[76:79], v[212:215], v[184:187], v[76:79]
	v_mfma_f32_16x16x32_bf16 v[72:75], v[220:223], v[184:187], v[72:75]
	v_mfma_f32_16x16x32_bf16 v[68:71], v[212:215], v[204:207], v[68:71]
	v_mfma_f32_16x16x32_bf16 v[64:67], v[220:223], v[204:207], v[64:67]
	v_mfma_f32_16x16x32_bf16 v[92:95], v[216:219], v[172:175], v[92:95]
	v_mfma_f32_16x16x32_bf16 v[88:91], v[224:227], v[172:175], v[88:91]
	v_mfma_f32_16x16x32_bf16 v[84:87], v[216:219], v[180:183], v[84:87]
	v_mfma_f32_16x16x32_bf16 v[80:83], v[224:227], v[180:183], v[80:83]
	v_mfma_f32_16x16x32_bf16 v[76:79], v[216:219], v[188:191], v[76:79]
	v_mfma_f32_16x16x32_bf16 v[72:75], v[224:227], v[188:191], v[72:75]
	v_mfma_f32_16x16x32_bf16 v[68:71], v[216:219], v[208:211], v[68:71]
	v_mfma_f32_16x16x32_bf16 v[64:67], v[224:227], v[208:211], v[64:67]
	s_setprio 0
	s_mov_b64 s[92:93], 0x1ac80180
	s_mov_b32 m0, s81
	v_lshl_add_u64 v[232:233], v[228:229], 0, s[92:93]
	s_mov_b64 s[92:93], 0x1ac90180
	s_barrier
; #define LDA8(dst, b, h)                                                                                               \
;   _Pragma("unroll") for (int m = 0; m < 4; ++m) _Pragma("unroll") for (int k = 0; k < 2; ++k)                         \
;     dst[m][k] = *(const bf16x8*)(SA8(b, h) + la + m * 2048 + k * 1024)
; #define LDB8(dst, b, h)                                                                                               \
;   _Pragma("unroll") for (int n = 0; n < 2; ++n) _Pragma("unroll") for (int k = 0; k < 2; ++k)                         \
;     dst[n][k] = *(const bf16x8*)(SB8(b, h) + lb + n * 2048 + k * 1024)
; #define WAITV8(n) asm volatile("s_waitcnt vmcnt(" #n ")" ::: "memory")
; #define WAITL8(n) asm volatile("s_waitcnt lgkmcnt(" #n ")" ::: "memory")
; #define BAR8 __builtin_amdgcn_s_barrier()
; #define SCHED8 __builtin_amdgcn_sched_barrier(0)
; template <class Epi>
; DEV void gemm_tile8(char* shm, const u16* __restrict__ A, const u16* __restrict__ Bt, int K, int brow, int bcol, Epi& epi) {
;     ...
;     LDA8(At, 1, 1); STAGE8(SA8(1, 0), A, brow, t + 3);
;     BAR8; WAITL8(0); MMA8(1, 0, At, B0); BAR8; SCHED8;
;     STAGE8(SB8(1, 1), Bt, bcol + HALF, t + 3);
;     WAITV8(6); BAR8; MMA8(1, 1, At, B1); BAR8;
;   }
;   { LDB8(B0, 0, 0); LDA8(At, 0, 0); STAGE8(SA8(1, 1), A, brow + HALF, nt - 1);
;     BAR8; WAITL8(0); MMA8(0, 0, At, B0); BAR8;
;     LDB8(B1, 0, 1); BAR8; WAITL8(0); MMA8(0, 1, At, B1); BAR8;
	ds_read_b128 v[168:171], v132 offset:49152
	ds_read_b128 v[172:175], v132 offset:50176
	ds_read_b128 v[176:179], v132 offset:51200
	ds_read_b128 v[180:183], v132 offset:52224
	ds_read_b128 v[184:187], v132 offset:53248
	ds_read_b128 v[188:191], v132 offset:54272
	ds_read_b128 v[204:207], v132 offset:55296
	ds_read_b128 v[208:211], v132 offset:56320
	global_load_lds_dwordx4 v[232:233], off
	v_lshl_add_u64 v[228:229], v[228:229], 0, s[92:93]
	s_mov_b32 m0, s84
	s_nop 0
	global_load_lds_dwordx4 v[228:229], off
	s_barrier
	s_waitcnt lgkmcnt(0)
	s_setprio 1
	s_waitcnt lgkmcnt(0)
	v_mfma_f32_16x16x32_bf16 v[60:63], v[152:155], v[168:171], v[60:63]
	v_mfma_f32_16x16x32_bf16 v[56:59], v[160:163], v[168:171], v[56:59]
	v_mfma_f32_16x16x32_bf16 v[52:55], v[152:155], v[176:179], v[52:55]
	v_mfma_f32_16x16x32_bf16 v[48:51], v[160:163], v[176:179], v[48:51]
	v_mfma_f32_16x16x32_bf16 v[44:47], v[152:155], v[184:187], v[44:47]
	v_mfma_f32_16x16x32_bf16 v[40:43], v[160:163], v[184:187], v[40:43]
	v_mfma_f32_16x16x32_bf16 v[36:39], v[152:155], v[204:207], v[36:39]
	v_mfma_f32_16x16x32_bf16 v[32:35], v[160:163], v[204:207], v[32:35]
	v_mfma_f32_16x16x32_bf16 v[60:63], v[156:159], v[172:175], v[60:63]
	v_mfma_f32_16x16x32_bf16 v[56:59], v[164:167], v[172:175], v[56:59]
	v_mfma_f32_16x16x32_bf16 v[52:55], v[156:159], v[180:183], v[52:55]
	v_mfma_f32_16x16x32_bf16 v[48:51], v[164:167], v[180:183], v[48:51]
	v_mfma_f32_16x16x32_bf16 v[44:47], v[156:159], v[188:191], v[44:47]
	v_mfma_f32_16x16x32_bf16 v[40:43], v[164:167], v[188:191], v[40:43]
	v_mfma_f32_16x16x32_bf16 v[36:39], v[156:159], v[208:211], v[36:39]
	v_mfma_f32_16x16x32_bf16 v[32:35], v[164:167], v[208:211], v[32:35]
	s_setprio 0
	s_barrier
	s_mov_b64 s[92:93], 0xb20180
	s_mov_b32 m0, s85
	v_lshl_add_u64 v[152:153], v[230:231], 0, s[92:93]
	s_mov_b64 s[92:93], 0xb30180
	global_load_lds_dwordx4 v[152:153], off
	v_lshl_add_u64 v[152:153], v[230:231], 0, s[92:93]
	s_mov_b32 m0, s90
	s_nop 0
	global_load_lds_dwordx4 v[152:153], off
	s_waitcnt vmcnt(6)
	s_barrier
	s_setprio 1
	v_mfma_f32_16x16x32_bf16 v[28:31], v[212:215], v[168:171], v[28:31]
	v_mfma_f32_16x16x32_bf16 v[24:27], v[220:223], v[168:171], v[24:27]
	v_mfma_f32_16x16x32_bf16 v[20:23], v[212:215], v[176:179], v[20:23]
	v_mfma_f32_16x16x32_bf16 v[16:19], v[220:223], v[176:179], v[16:19]
	v_mfma_f32_16x16x32_bf16 v[12:15], v[212:215], v[184:187], v[12:15]
	v_mfma_f32_16x16x32_bf16 v[8:11], v[220:223], v[184:187], v[8:11]
	v_mfma_f32_16x16x32_bf16 v[4:7], v[212:215], v[204:207], v[4:7]
	v_mfma_f32_16x16x32_bf16 v[0:3], v[220:223], v[204:207], v[0:3]
	v_mfma_f32_16x16x32_bf16 v[28:31], v[216:219], v[172:175], v[28:31]
	v_mfma_f32_16x16x32_bf16 v[24:27], v[224:227], v[172:175], v[24:27]
	v_mfma_f32_16x16x32_bf16 v[20:23], v[216:219], v[180:183], v[20:23]
	v_mfma_f32_16x16x32_bf16 v[16:19], v[224:227], v[180:183], v[16:19]
	v_mfma_f32_16x16x32_bf16 v[12:15], v[216:219], v[188:191], v[12:15]
	v_mfma_f32_16x16x32_bf16 v[8:11], v[224:227], v[188:191], v[8:11]
	v_mfma_f32_16x16x32_bf16 v[4:7], v[216:219], v[208:211], v[4:7]
	v_mfma_f32_16x16x32_bf16 v[0:3], v[224:227], v[208:211], v[0:3]
	s_setprio 0
	s_add_i32 s22, s22, 2
	s_add_u32 s18, s18, 0x100
	s_addc_u32 s19, s19, 0
	s_add_u32 s20, s20, 0x100
	s_addc_u32 s21, s21, 0
	s_cmp_lt_u32 s22, 4
	s_barrier
	s_cbranch_scc1 .LBB0_599
	s_mov_b64 s[18:19], 0x380
	s_mov_b32 m0, s91
	v_lshl_add_u64 v[130:131], v[128:129], 0, s[18:19]
	s_mov_b64 s[18:19], 0x10380
	s_waitcnt vmcnt(0)
	ds_read_b128 v[152:155], v134
	ds_read_b128 v[156:159], v135
	ds_read_b128 v[160:163], v136
	ds_read_b128 v[134:137], v137
	ds_read_b128 v[164:167], v132
	ds_read_b128 v[168:171], v132 offset:1024
	ds_read_b128 v[172:175], v132 offset:2048
	ds_read_b128 v[176:179], v132 offset:3072
	ds_read_b128 v[180:183], v132 offset:4096
	ds_read_b128 v[184:187], v132 offset:5120
	ds_read_b128 v[188:191], v132 offset:6144
	ds_read_b128 v[204:207], v132 offset:7168
	global_load_lds_dwordx4 v[130:131], off
	v_lshl_add_u64 v[128:129], v[128:129], 0, s[18:19]
	s_mov_b32 m0, s23
	s_nop 0
	global_load_lds_dwordx4 v[128:129], off
	s_barrier
	s_waitcnt lgkmcnt(0)
	s_setprio 1
	s_waitcnt lgkmcnt(0)
	v_mfma_f32_16x16x32_bf16 v[124:127], v[152:155], v[164:167], v[124:127]
	v_mfma_f32_16x16x32_bf16 v[120:123], v[160:163], v[164:167], v[120:123]
	v_mfma_f32_16x16x32_bf16 v[116:119], v[152:155], v[172:175], v[116:119]
	v_mfma_f32_16x16x32_bf16 v[112:115], v[160:163], v[172:175], v[112:115]
	v_mfma_f32_16x16x32_bf16 v[108:111], v[152:155], v[180:183], v[108:111]
	v_mfma_f32_16x16x32_bf16 v[104:107], v[160:163], v[180:183], v[104:107]
	v_mfma_f32_16x16x32_bf16 v[100:103], v[152:155], v[188:191], v[100:103]
	v_mfma_f32_16x16x32_bf16 v[96:99], v[160:163], v[188:191], v[96:99]
	v_mfma_f32_16x16x32_bf16 v[124:127], v[156:159], v[168:171], v[124:127]
	v_mfma_f32_16x16x32_bf16 v[120:123], v[134:137], v[168:171], v[120:123]
	v_mfma_f32_16x16x32_bf16 v[116:119], v[156:159], v[176:179], v[116:119]
	v_mfma_f32_16x16x32_bf16 v[112:115], v[134:137], v[176:179], v[112:115]
	v_mfma_f32_16x16x32_bf16 v[108:111], v[156:159], v[184:187], v[108:111]
	v_mfma_f32_16x16x32_bf16 v[104:107], v[134:137], v[184:187], v[104:107]
	v_mfma_f32_16x16x32_bf16 v[100:103], v[156:159], v[204:207], v[100:103]
	v_mfma_f32_16x16x32_bf16 v[96:99], v[134:137], v[204:207], v[96:99]
	s_setprio 0
	s_barrier
	s_waitcnt vmcnt(0)
	ds_read_b128 v[128:131], v138
	ds_read_b128 v[208:211], v139
	ds_read_b128 v[212:215], v140
	ds_read_b128 v[216:219], v142
	s_barrier
; #define LDA8(dst, b, h)                                                                                               \
;   _Pragma("unroll") for (int m = 0; m < 4; ++m) _Pragma("unroll") for (int k = 0; k < 2; ++k)                         \
;     dst[m][k] = *(const bf16x8*)(SA8(b, h) + la + m * 2048 + k * 1024)
; #define LDB8(dst, b, h)                                                                                               \
;   _Pragma("unroll") for (int n = 0; n < 2; ++n) _Pragma("unroll") for (int k = 0; k < 2; ++k)                         \
;     dst[n][k] = *(const bf16x8*)(SB8(b, h) + lb + n * 2048 + k * 1024)
; #define WAITV8(n) asm volatile("s_waitcnt vmcnt(" #n ")" ::: "memory")
; #define WAITL8(n) asm volatile("s_waitcnt lgkmcnt(" #n ")" ::: "memory")
; #define BAR8 __builtin_amdgcn_s_barrier()
; template <class Epi>
; DEV void gemm_tile8(char* shm, const u16* __restrict__ A, const u16* __restrict__ Bt, int K, int brow, int bcol, Epi& epi) {
;     ...
;     LDB8(B1, 0, 1); BAR8; WAITL8(0); MMA8(0, 1, At, B1); BAR8;
;     LDA8(At, 0, 1); WAITV8(4); BAR8; WAITL8(0); MMA8(1, 0, At, B0); MMA8(1, 1, At, B1); BAR8; }
;   { LDB8(B0, 1, 0); LDA8(At, 1, 0); WAITV8(2); BAR8; WAITL8(0); MMA8(0, 0, At, B0); BAR8;
	s_waitcnt lgkmcnt(0)
	s_setprio 1
	s_waitcnt lgkmcnt(3)
	v_mfma_f32_16x16x32_bf16 v[92:95], v[128:131], v[164:167], v[92:95]
	s_waitcnt lgkmcnt(1)
	v_mfma_f32_16x16x32_bf16 v[88:91], v[212:215], v[164:167], v[88:91]
	v_mfma_f32_16x16x32_bf16 v[84:87], v[128:131], v[172:175], v[84:87]
	v_mfma_f32_16x16x32_bf16 v[80:83], v[212:215], v[172:175], v[80:83]
	v_mfma_f32_16x16x32_bf16 v[76:79], v[128:131], v[180:183], v[76:79]
	v_mfma_f32_16x16x32_bf16 v[72:75], v[212:215], v[180:183], v[72:75]
	v_mfma_f32_16x16x32_bf16 v[68:71], v[128:131], v[188:191], v[68:71]
	v_mfma_f32_16x16x32_bf16 v[64:67], v[212:215], v[188:191], v[64:67]
	v_mfma_f32_16x16x32_bf16 v[220:223], v[208:211], v[168:171], v[92:95]
	s_waitcnt lgkmcnt(0)
	v_mfma_f32_16x16x32_bf16 v[164:167], v[216:219], v[168:171], v[88:91]
	v_mfma_f32_16x16x32_bf16 v[168:171], v[208:211], v[176:179], v[84:87]
	v_mfma_f32_16x16x32_bf16 v[172:175], v[216:219], v[176:179], v[80:83]
	v_mfma_f32_16x16x32_bf16 v[176:179], v[208:211], v[184:187], v[76:79]
	v_mfma_f32_16x16x32_bf16 v[180:183], v[216:219], v[184:187], v[72:75]
	v_mfma_f32_16x16x32_bf16 v[184:187], v[208:211], v[204:207], v[68:71]
	v_mfma_f32_16x16x32_bf16 v[188:191], v[216:219], v[204:207], v[64:67]
	s_setprio 0
	s_barrier
	s_nop 0
	ds_read_b128 v[64:67], v132 offset:16384
	ds_read_b128 v[68:71], v132 offset:17408
	ds_read_b128 v[72:75], v132 offset:18432
	ds_read_b128 v[76:79], v132 offset:19456
	ds_read_b128 v[80:83], v132 offset:20480
	ds_read_b128 v[84:87], v132 offset:21504
	ds_read_b128 v[88:91], v132 offset:22528
	ds_read_b128 v[92:95], v132 offset:23552
	s_waitcnt vmcnt(4)
	s_barrier
	s_waitcnt lgkmcnt(0)
	s_setprio 1
	s_waitcnt lgkmcnt(7)
	v_mfma_f32_16x16x32_bf16 v[60:63], v[152:155], v[64:67], v[60:63]
	v_mfma_f32_16x16x32_bf16 v[56:59], v[160:163], v[64:67], v[56:59]
	s_waitcnt lgkmcnt(5)
	v_mfma_f32_16x16x32_bf16 v[52:55], v[152:155], v[72:75], v[52:55]
	v_mfma_f32_16x16x32_bf16 v[48:51], v[160:163], v[72:75], v[48:51]
	s_waitcnt lgkmcnt(3)
	v_mfma_f32_16x16x32_bf16 v[44:47], v[152:155], v[80:83], v[44:47]
	v_mfma_f32_16x16x32_bf16 v[40:43], v[160:163], v[80:83], v[40:43]
	s_waitcnt lgkmcnt(1)
	v_mfma_f32_16x16x32_bf16 v[36:39], v[152:155], v[88:91], v[36:39]
	v_mfma_f32_16x16x32_bf16 v[32:35], v[160:163], v[88:91], v[32:35]
	v_mfma_f32_16x16x32_bf16 v[60:63], v[156:159], v[68:71], v[60:63]
	v_mfma_f32_16x16x32_bf16 v[56:59], v[134:137], v[68:71], v[56:59]
	v_mfma_f32_16x16x32_bf16 v[52:55], v[156:159], v[76:79], v[52:55]
	v_mfma_f32_16x16x32_bf16 v[48:51], v[134:137], v[76:79], v[48:51]
	v_mfma_f32_16x16x32_bf16 v[44:47], v[156:159], v[84:87], v[44:47]
	v_mfma_f32_16x16x32_bf16 v[40:43], v[134:137], v[84:87], v[40:43]
	s_waitcnt lgkmcnt(0)
	v_mfma_f32_16x16x32_bf16 v[36:39], v[156:159], v[92:95], v[36:39]
	v_mfma_f32_16x16x32_bf16 v[32:35], v[134:137], v[92:95], v[32:35]
	s_setprio 0
	s_setprio 1
	v_mfma_f32_16x16x32_bf16 v[28:31], v[128:131], v[64:67], v[28:31]
	v_mfma_f32_16x16x32_bf16 v[24:27], v[212:215], v[64:67], v[24:27]
	v_mfma_f32_16x16x32_bf16 v[20:23], v[128:131], v[72:75], v[20:23]
	v_mfma_f32_16x16x32_bf16 v[16:19], v[212:215], v[72:75], v[16:19]
	v_mfma_f32_16x16x32_bf16 v[12:15], v[128:131], v[80:83], v[12:15]
	v_mfma_f32_16x16x32_bf16 v[8:11], v[212:215], v[80:83], v[8:11]
	v_mfma_f32_16x16x32_bf16 v[4:7], v[128:131], v[88:91], v[4:7]
	v_mfma_f32_16x16x32_bf16 v[0:3], v[212:215], v[88:91], v[0:3]
	v_mfma_f32_16x16x32_bf16 v[134:137], v[208:211], v[68:71], v[28:31]
	v_mfma_f32_16x16x32_bf16 v[152:155], v[216:219], v[68:71], v[24:27]
	v_mfma_f32_16x16x32_bf16 v[156:159], v[208:211], v[76:79], v[20:23]
	v_mfma_f32_16x16x32_bf16 v[160:163], v[216:219], v[76:79], v[16:19]
	v_mfma_f32_16x16x32_bf16 v[204:207], v[208:211], v[84:87], v[12:15]
	v_mfma_f32_16x16x32_bf16 v[224:227], v[216:219], v[84:87], v[8:11]
	v_mfma_f32_16x16x32_bf16 v[128:131], v[208:211], v[92:95], v[4:7]
	v_mfma_f32_16x16x32_bf16 v[208:211], v[216:219], v[92:95], v[0:3]
	s_setprio 0
	s_barrier
	ds_read_b128 v[24:27], v143
	ds_read_b128 v[28:31], v144
	ds_read_b128 v[142:145], v145
	ds_read_b128 v[212:215], v146
	ds_read_b128 v[0:3], v132 offset:32768
	ds_read_b128 v[4:7], v132 offset:33792
	ds_read_b128 v[8:11], v132 offset:34816
	ds_read_b128 v[12:15], v132 offset:35840
	ds_read_b128 v[16:19], v132 offset:36864
	ds_read_b128 v[20:23], v132 offset:37888
	ds_read_b128 v[216:219], v132 offset:38912
	ds_read_b128 v[228:231], v132 offset:39936
	s_waitcnt vmcnt(2)
	s_barrier
; #define LDA8(dst, b, h)                                                                                               \
;   _Pragma("unroll") for (int m = 0; m < 4; ++m) _Pragma("unroll") for (int k = 0; k < 2; ++k)                         \
;     dst[m][k] = *(const bf16x8*)(SA8(b, h) + la + m * 2048 + k * 1024)
; #define LDB8(dst, b, h)                                                                                               \
;   _Pragma("unroll") for (int n = 0; n < 2; ++n) _Pragma("unroll") for (int k = 0; k < 2; ++k)                         \
;     dst[n][k] = *(const bf16x8*)(SB8(b, h) + lb + n * 2048 + k * 1024)
; #define WAITV8(n) asm volatile("s_waitcnt vmcnt(" #n ")" ::: "memory")
; #define WAITL8(n) asm volatile("s_waitcnt lgkmcnt(" #n ")" ::: "memory")
; #define BAR8 __builtin_amdgcn_s_barrier()
; template <class Epi>
; DEV void gemm_tile8(char* shm, const u16* __restrict__ A, const u16* __restrict__ Bt, int K, int brow, int bcol, Epi& epi) {
;     ...
;   { LDB8(B0, 1, 0); LDA8(At, 1, 0); WAITV8(2); BAR8; WAITL8(0); MMA8(0, 0, At, B0); BAR8;
;     LDB8(B1, 1, 1); WAITV8(0); BAR8; WAITL8(0); MMA8(0, 1, At, B1); BAR8;
;     LDA8(At, 1, 1); BAR8; WAITL8(0); MMA8(1, 0, At, B0); MMA8(1, 1, At, B1); BAR8; }
;   if (wrs == 0) BAR8;
	s_waitcnt lgkmcnt(0)
	s_setprio 1
	s_waitcnt lgkmcnt(7)
	v_mfma_f32_16x16x32_bf16 v[64:67], v[24:27], v[0:3], v[124:127]
	s_waitcnt lgkmcnt(6)
	v_mfma_f32_16x16x32_bf16 v[72:75], v[28:31], v[4:7], v[64:67]
	v_mfma_f32_16x16x32_bf16 v[64:67], v[142:145], v[0:3], v[120:123]
	s_waitcnt lgkmcnt(5)
	v_mfma_f32_16x16x32_bf16 v[68:71], v[24:27], v[8:11], v[116:119]
	v_mfma_f32_16x16x32_bf16 v[76:79], v[142:145], v[8:11], v[112:115]
	s_waitcnt lgkmcnt(3)
	v_mfma_f32_16x16x32_bf16 v[80:83], v[24:27], v[16:19], v[108:111]
	v_mfma_f32_16x16x32_bf16 v[84:87], v[142:145], v[16:19], v[104:107]
	s_waitcnt lgkmcnt(1)
	v_mfma_f32_16x16x32_bf16 v[88:91], v[24:27], v[216:219], v[100:103]
	v_mfma_f32_16x16x32_bf16 v[92:95], v[142:145], v[216:219], v[96:99]
	v_mfma_f32_16x16x32_bf16 v[64:67], v[212:215], v[4:7], v[64:67]
	v_mfma_f32_16x16x32_bf16 v[68:71], v[28:31], v[12:15], v[68:71]
	v_mfma_f32_16x16x32_bf16 v[76:79], v[212:215], v[12:15], v[76:79]
	v_mfma_f32_16x16x32_bf16 v[80:83], v[28:31], v[20:23], v[80:83]
	v_mfma_f32_16x16x32_bf16 v[84:87], v[212:215], v[20:23], v[84:87]
	s_waitcnt lgkmcnt(0)
	v_mfma_f32_16x16x32_bf16 v[88:91], v[28:31], v[228:231], v[88:91]
	v_mfma_f32_16x16x32_bf16 v[92:95], v[212:215], v[228:231], v[92:95]
	s_setprio 0
	s_barrier
	ds_read_b128 v[232:235], v147
	ds_read_b128 v[236:239], v148
	ds_read_b128 v[146:149], v149
	ds_read_b128 v[240:243], v150
	s_waitcnt vmcnt(0)
	s_barrier
	s_waitcnt lgkmcnt(0)
	s_setprio 1
	s_waitcnt lgkmcnt(3)
	v_mfma_f32_16x16x32_bf16 v[96:99], v[232:235], v[0:3], v[220:223]
	s_waitcnt lgkmcnt(1)
	v_mfma_f32_16x16x32_bf16 v[0:3], v[146:149], v[0:3], v[164:167]
	v_mfma_f32_16x16x32_bf16 v[104:107], v[236:239], v[4:7], v[96:99]
	s_waitcnt lgkmcnt(0)
	v_mfma_f32_16x16x32_bf16 v[96:99], v[240:243], v[4:7], v[0:3]
	v_mfma_f32_16x16x32_bf16 v[0:3], v[232:235], v[8:11], v[168:171]
	v_mfma_f32_16x16x32_bf16 v[100:103], v[236:239], v[12:15], v[0:3]
	v_mfma_f32_16x16x32_bf16 v[0:3], v[146:149], v[8:11], v[172:175]
	v_mfma_f32_16x16x32_bf16 v[108:111], v[240:243], v[12:15], v[0:3]
	v_mfma_f32_16x16x32_bf16 v[0:3], v[232:235], v[16:19], v[176:179]
	v_mfma_f32_16x16x32_bf16 v[112:115], v[236:239], v[20:23], v[0:3]
	v_mfma_f32_16x16x32_bf16 v[0:3], v[146:149], v[16:19], v[180:183]
	v_mfma_f32_16x16x32_bf16 v[116:119], v[240:243], v[20:23], v[0:3]
	v_mfma_f32_16x16x32_bf16 v[0:3], v[232:235], v[216:219], v[184:187]
	v_mfma_f32_16x16x32_bf16 v[120:123], v[236:239], v[228:231], v[0:3]
	v_mfma_f32_16x16x32_bf16 v[0:3], v[146:149], v[216:219], v[188:191]
	v_mfma_f32_16x16x32_bf16 v[124:127], v[240:243], v[228:231], v[0:3]
	s_setprio 0
	s_barrier
	ds_read_b128 v[164:167], v132 offset:49152
	ds_read_b128 v[168:171], v132 offset:50176
	ds_read_b128 v[172:175], v132 offset:51200
	ds_read_b128 v[176:179], v132 offset:52224
	ds_read_b128 v[180:183], v132 offset:53248
	ds_read_b128 v[184:187], v132 offset:54272
	ds_read_b128 v[188:191], v132 offset:55296
	ds_read_b128 v[216:219], v132 offset:56320
	s_barrier
	s_waitcnt lgkmcnt(0)
	s_setprio 1
	s_waitcnt lgkmcnt(7)
	v_mfma_f32_16x16x32_bf16 v[0:3], v[24:27], v[164:167], v[60:63]
	s_waitcnt lgkmcnt(5)
	v_mfma_f32_16x16x32_bf16 v[8:11], v[24:27], v[172:175], v[52:55]
	s_waitcnt lgkmcnt(3)
	v_mfma_f32_16x16x32_bf16 v[16:19], v[24:27], v[180:183], v[44:47]
	s_waitcnt lgkmcnt(1)
	v_mfma_f32_16x16x32_bf16 v[24:27], v[24:27], v[188:191], v[36:39]
	v_mfma_f32_16x16x32_bf16 v[0:3], v[28:31], v[168:171], v[0:3]
	v_mfma_f32_16x16x32_bf16 v[4:7], v[142:145], v[164:167], v[56:59]
	v_mfma_f32_16x16x32_bf16 v[8:11], v[28:31], v[176:179], v[8:11]
	v_mfma_f32_16x16x32_bf16 v[12:15], v[142:145], v[172:175], v[48:51]
	v_mfma_f32_16x16x32_bf16 v[16:19], v[28:31], v[184:187], v[16:19]
	v_mfma_f32_16x16x32_bf16 v[20:23], v[142:145], v[180:183], v[40:43]
	s_waitcnt lgkmcnt(0)
	v_mfma_f32_16x16x32_bf16 v[24:27], v[28:31], v[216:219], v[24:27]
	v_mfma_f32_16x16x32_bf16 v[28:31], v[142:145], v[188:191], v[32:35]
	v_mfma_f32_16x16x32_bf16 v[4:7], v[212:215], v[168:171], v[4:7]
	v_mfma_f32_16x16x32_bf16 v[12:15], v[212:215], v[176:179], v[12:15]
	v_mfma_f32_16x16x32_bf16 v[20:23], v[212:215], v[184:187], v[20:23]
	v_mfma_f32_16x16x32_bf16 v[28:31], v[212:215], v[216:219], v[28:31]
	s_setprio 0
	s_setprio 1
	v_mfma_f32_16x16x32_bf16 v[32:35], v[232:235], v[164:167], v[134:137]
	v_mfma_f32_16x16x32_bf16 v[36:39], v[146:149], v[164:167], v[152:155]
	v_mfma_f32_16x16x32_bf16 v[40:43], v[232:235], v[172:175], v[156:159]
	v_mfma_f32_16x16x32_bf16 v[44:47], v[146:149], v[172:175], v[160:163]
	v_mfma_f32_16x16x32_bf16 v[48:51], v[232:235], v[180:183], v[204:207]
	v_mfma_f32_16x16x32_bf16 v[52:55], v[146:149], v[180:183], v[224:227]
	v_mfma_f32_16x16x32_bf16 v[56:59], v[232:235], v[188:191], v[128:131]
	v_mfma_f32_16x16x32_bf16 v[60:63], v[146:149], v[188:191], v[208:211]
	v_mfma_f32_16x16x32_bf16 v[32:35], v[236:239], v[168:171], v[32:35]
	v_mfma_f32_16x16x32_bf16 v[36:39], v[240:243], v[168:171], v[36:39]
	v_mfma_f32_16x16x32_bf16 v[40:43], v[236:239], v[176:179], v[40:43]
	v_mfma_f32_16x16x32_bf16 v[44:47], v[240:243], v[176:179], v[44:47]
	v_mfma_f32_16x16x32_bf16 v[48:51], v[236:239], v[184:187], v[48:51]
	v_mfma_f32_16x16x32_bf16 v[52:55], v[240:243], v[184:187], v[52:55]
	v_mfma_f32_16x16x32_bf16 v[56:59], v[236:239], v[216:219], v[56:59]
	v_mfma_f32_16x16x32_bf16 v[60:63], v[240:243], v[216:219], v[60:63]
	s_setprio 0
	s_cmp_lg_u32 s7, 0
	s_barrier
	s_cbranch_scc1 .LBB0_602
	s_barrier

; #define LDA8(dst, b, h)                                                                                               \
;   _Pragma("unroll") for (int m = 0; m < 4; ++m) _Pragma("unroll") for (int k = 0; k < 2; ++k)                         \
;     dst[m][k] = *(const bf16x8*)(SA8(b, h) + la + m * 2048 + k * 1024)
; #define LDB8(dst, b, h)                                                                                               \
;   _Pragma("unroll") for (int n = 0; n < 2; ++n) _Pragma("unroll") for (int k = 0; k < 2; ++k)                         \
;     dst[n][k] = *(const bf16x8*)(SB8(b, h) + lb + n * 2048 + k * 1024)
; #define WAITL8(n) asm volatile("s_waitcnt lgkmcnt(" #n ")" ::: "memory")
; #define BAR8 __builtin_amdgcn_s_barrier()
; #define SCHED8 __builtin_amdgcn_sched_barrier(0)
; template <class Epi>
; DEV void gemm_tile8(char* shm, const u16* __restrict__ A, const u16* __restrict__ Bt, int K, int brow, int bcol, Epi& epi) {
;     ...
;     LDB8(B0, 0, 0); SCHED8; LDA8(At, 0, 0); STAGE8(SA8(1, 1), A, brow + HALF, t + 1);
;     WAITL8(8); BAR8; WAITL8(0); MMA8(0, 0, At, B0); BAR8; SCHED8;
;     LDB8(B1, 0, 1); STAGE8(SB8(0, 0), Bt, bcol, t + 2);
;     BAR8; WAITL8(0); MMA8(0, 1, At, B1); BAR8;
;     LDA8(At, 0, 1); STAGE8(SA8(0, 0), A, brow, t + 2);
;     BAR8; WAITL8(0); MMA8(1, 0, At, B0); BAR8; SCHED8;
.LBB0_907:
	v_or_b32_e32 v134, 0x10000, v133
	v_add_u32_e32 v136, 0x10800, v133
	v_add_u32_e32 v135, 0x10400, v133
	ds_read_b128 v[144:147], v134
	ds_read_b128 v[148:151], v135
	v_add_u32_e32 v137, 0x10c00, v133
	ds_read_b128 v[152:155], v136
	ds_read_b128 v[156:159], v137
	v_lshl_add_u64 v[188:189], s[10:11], 0, v[130:131]
	s_mov_b64 s[90:91], 0x40080
	v_lshl_add_u64 v[138:139], v[188:189], 0, s[90:91]
	s_add_i32 s91, s13, 0xc000
	s_mov_b32 m0, s91
	s_mov_b64 s[92:93], 0x60080
	s_add_i32 s90, s13, 0xe000
	ds_read_b128 v[160:163], v132
	ds_read_b128 v[164:167], v132 offset:1024
	ds_read_b128 v[168:171], v132 offset:2048
	ds_read_b128 v[172:175], v132 offset:3072
	ds_read_b128 v[176:179], v132 offset:4096
	ds_read_b128 v[180:183], v132 offset:5120
	ds_read_b128 v[184:187], v132 offset:6144
	ds_read_b128 v[204:207], v132 offset:7168
	global_load_lds_dwordx4 v[138:139], off
	v_lshl_add_u64 v[138:139], v[188:189], 0, s[92:93]
	s_mov_b32 m0, s90
	s_nop 0
	global_load_lds_dwordx4 v[138:139], off
	s_waitcnt lgkmcnt(8)
	s_barrier
	s_waitcnt lgkmcnt(0)
	s_setprio 1
	s_waitcnt lgkmcnt(0)
	v_mfma_f32_16x16x32_bf16 v[124:127], v[144:147], v[160:163], v[124:127]
	v_mfma_f32_16x16x32_bf16 v[120:123], v[152:155], v[160:163], v[120:123]
	v_mfma_f32_16x16x32_bf16 v[116:119], v[144:147], v[168:171], v[116:119]
	v_mfma_f32_16x16x32_bf16 v[112:115], v[152:155], v[168:171], v[112:115]
	v_mfma_f32_16x16x32_bf16 v[108:111], v[144:147], v[176:179], v[108:111]
	v_mfma_f32_16x16x32_bf16 v[104:107], v[152:155], v[176:179], v[104:107]
	v_mfma_f32_16x16x32_bf16 v[100:103], v[144:147], v[184:187], v[100:103]
	v_mfma_f32_16x16x32_bf16 v[96:99], v[152:155], v[184:187], v[96:99]
	v_mfma_f32_16x16x32_bf16 v[124:127], v[148:151], v[164:167], v[124:127]
	v_mfma_f32_16x16x32_bf16 v[120:123], v[156:159], v[164:167], v[120:123]
	v_mfma_f32_16x16x32_bf16 v[116:119], v[148:151], v[172:175], v[116:119]
	v_mfma_f32_16x16x32_bf16 v[112:115], v[156:159], v[172:175], v[112:115]
	v_mfma_f32_16x16x32_bf16 v[108:111], v[148:151], v[180:183], v[108:111]
	v_mfma_f32_16x16x32_bf16 v[104:107], v[156:159], v[180:183], v[104:107]
	v_mfma_f32_16x16x32_bf16 v[100:103], v[148:151], v[204:207], v[100:103]
	v_mfma_f32_16x16x32_bf16 v[96:99], v[156:159], v[204:207], v[96:99]
	s_setprio 0
	s_barrier
	v_lshl_add_u64 v[190:191], s[6:7], 0, v[130:131]
	s_mov_b32 m0, s14
	v_or_b32_e32 v138, 0x14000, v133
	v_add_u32_e32 v140, 0x14800, v133
	v_lshl_add_u64 v[224:225], v[190:191], 0, s[4:5]
	v_add_u32_e32 v139, 0x14400, v133
	ds_read_b128 v[208:211], v138
	ds_read_b128 v[212:215], v139
	v_add_u32_e32 v142, 0x14c00, v133
	ds_read_b128 v[216:219], v140
	ds_read_b128 v[220:223], v142
	global_load_lds_dwordx4 v[224:225], off
	v_lshl_add_u64 v[224:225], v[190:191], 0, s[60:61]
	s_mov_b32 m0, s15
	s_nop 0
	global_load_lds_dwordx4 v[224:225], off
	s_barrier
	s_waitcnt lgkmcnt(0)
	s_setprio 1
	s_waitcnt lgkmcnt(0)
	v_mfma_f32_16x16x32_bf16 v[92:95], v[208:211], v[160:163], v[92:95]
	v_mfma_f32_16x16x32_bf16 v[88:91], v[216:219], v[160:163], v[88:91]
	v_mfma_f32_16x16x32_bf16 v[84:87], v[208:211], v[168:171], v[84:87]
	v_mfma_f32_16x16x32_bf16 v[80:83], v[216:219], v[168:171], v[80:83]
	v_mfma_f32_16x16x32_bf16 v[76:79], v[208:211], v[176:179], v[76:79]
	v_mfma_f32_16x16x32_bf16 v[72:75], v[216:219], v[176:179], v[72:75]
	v_mfma_f32_16x16x32_bf16 v[68:71], v[208:211], v[184:187], v[68:71]
	v_mfma_f32_16x16x32_bf16 v[64:67], v[216:219], v[184:187], v[64:67]
	v_mfma_f32_16x16x32_bf16 v[92:95], v[212:215], v[164:167], v[92:95]
	v_mfma_f32_16x16x32_bf16 v[88:91], v[220:223], v[164:167], v[88:91]
	v_mfma_f32_16x16x32_bf16 v[84:87], v[212:215], v[172:175], v[84:87]
	v_mfma_f32_16x16x32_bf16 v[80:83], v[220:223], v[172:175], v[80:83]
	v_mfma_f32_16x16x32_bf16 v[76:79], v[212:215], v[180:183], v[76:79]
	v_mfma_f32_16x16x32_bf16 v[72:75], v[220:223], v[180:183], v[72:75]
	v_mfma_f32_16x16x32_bf16 v[68:71], v[212:215], v[204:207], v[68:71]
	v_mfma_f32_16x16x32_bf16 v[64:67], v[220:223], v[204:207], v[64:67]
	s_setprio 0
	s_mov_b32 m0, s13
	v_lshl_add_u64 v[224:225], v[188:189], 0, s[4:5]
	s_barrier
	ds_read_b128 v[160:163], v132 offset:16384
	ds_read_b128 v[164:167], v132 offset:17408
	ds_read_b128 v[168:171], v132 offset:18432
	ds_read_b128 v[172:175], v132 offset:19456
	ds_read_b128 v[176:179], v132 offset:20480
	ds_read_b128 v[180:183], v132 offset:21504
	ds_read_b128 v[184:187], v132 offset:22528
	ds_read_b128 v[204:207], v132 offset:23552
	global_load_lds_dwordx4 v[224:225], off
	v_lshl_add_u64 v[224:225], v[188:189], 0, s[60:61]
	s_mov_b32 m0, s16
	s_nop 0
	global_load_lds_dwordx4 v[224:225], off
	s_barrier
	s_waitcnt lgkmcnt(0)
	s_setprio 1
	s_waitcnt lgkmcnt(0)
	v_mfma_f32_16x16x32_bf16 v[60:63], v[144:147], v[160:163], v[60:63]
	v_mfma_f32_16x16x32_bf16 v[56:59], v[152:155], v[160:163], v[56:59]
	v_mfma_f32_16x16x32_bf16 v[52:55], v[144:147], v[168:171], v[52:55]
	v_mfma_f32_16x16x32_bf16 v[48:51], v[152:155], v[168:171], v[48:51]
	v_mfma_f32_16x16x32_bf16 v[44:47], v[144:147], v[176:179], v[44:47]
	v_mfma_f32_16x16x32_bf16 v[40:43], v[152:155], v[176:179], v[40:43]
	v_mfma_f32_16x16x32_bf16 v[36:39], v[144:147], v[184:187], v[36:39]
	v_mfma_f32_16x16x32_bf16 v[32:35], v[152:155], v[184:187], v[32:35]
	v_mfma_f32_16x16x32_bf16 v[60:63], v[148:151], v[164:167], v[60:63]
	v_mfma_f32_16x16x32_bf16 v[56:59], v[156:159], v[164:167], v[56:59]
	v_mfma_f32_16x16x32_bf16 v[52:55], v[148:151], v[172:175], v[52:55]
	v_mfma_f32_16x16x32_bf16 v[48:51], v[156:159], v[172:175], v[48:51]
	v_mfma_f32_16x16x32_bf16 v[44:47], v[148:151], v[180:183], v[44:47]
	v_mfma_f32_16x16x32_bf16 v[40:43], v[156:159], v[180:183], v[40:43]
	v_mfma_f32_16x16x32_bf16 v[36:39], v[148:151], v[204:207], v[36:39]
	v_mfma_f32_16x16x32_bf16 v[32:35], v[156:159], v[204:207], v[32:35]
	s_setprio 0
	s_barrier
; #define LDA8(dst, b, h)                                                                                               \
;   _Pragma("unroll") for (int m = 0; m < 4; ++m) _Pragma("unroll") for (int k = 0; k < 2; ++k)                         \
;     dst[m][k] = *(const bf16x8*)(SA8(b, h) + la + m * 2048 + k * 1024)
; #define LDB8(dst, b, h)                                                                                               \
;   _Pragma("unroll") for (int n = 0; n < 2; ++n) _Pragma("unroll") for (int k = 0; k < 2; ++k)                         \
;     dst[n][k] = *(const bf16x8*)(SB8(b, h) + lb + n * 2048 + k * 1024)
; #define WAITV8(n) asm volatile("s_waitcnt vmcnt(" #n ")" ::: "memory")
; #define WAITL8(n) asm volatile("s_waitcnt lgkmcnt(" #n ")" ::: "memory")
; #define BAR8 __builtin_amdgcn_s_barrier()
; #define SCHED8 __builtin_amdgcn_sched_barrier(0)
; template <class Epi>
; DEV void gemm_tile8(char* shm, const u16* __restrict__ A, const u16* __restrict__ Bt, int K, int brow, int bcol, Epi& epi) {
;     ...
;     STAGE8(SB8(0, 1), Bt, bcol + HALF, t + 2);
;     WAITV8(6); BAR8; MMA8(1, 1, At, B1); BAR8;
;     LDB8(B0, 1, 0); SCHED8; LDA8(At, 1, 0); STAGE8(SA8(0, 1), A, brow + HALF, t + 2);
;     WAITL8(8); BAR8; WAITL8(0); MMA8(0, 0, At, B0); BAR8; SCHED8;
;     LDB8(B1, 1, 1); STAGE8(SB8(1, 0), Bt, bcol, t + 3);
;     BAR8; WAITL8(0); MMA8(0, 1, At, B1); BAR8;
;     LDA8(At, 1, 1); STAGE8(SA8(1, 0), A, brow, t + 3);
	s_mov_b32 m0, s17
	v_lshl_add_u64 v[144:145], v[190:191], 0, s[76:77]
	global_load_lds_dwordx4 v[144:145], off
	v_lshl_add_u64 v[144:145], v[190:191], 0, s[46:47]
	s_mov_b32 m0, s23
	s_nop 0
	global_load_lds_dwordx4 v[144:145], off
	s_waitcnt vmcnt(6)
	s_barrier
	s_setprio 1
	v_mfma_f32_16x16x32_bf16 v[28:31], v[208:211], v[160:163], v[28:31]
	v_mfma_f32_16x16x32_bf16 v[24:27], v[216:219], v[160:163], v[24:27]
	v_mfma_f32_16x16x32_bf16 v[20:23], v[208:211], v[168:171], v[20:23]
	v_mfma_f32_16x16x32_bf16 v[16:19], v[216:219], v[168:171], v[16:19]
	v_mfma_f32_16x16x32_bf16 v[12:15], v[208:211], v[176:179], v[12:15]
	v_mfma_f32_16x16x32_bf16 v[8:11], v[216:219], v[176:179], v[8:11]
	v_mfma_f32_16x16x32_bf16 v[4:7], v[208:211], v[184:187], v[4:7]
	v_mfma_f32_16x16x32_bf16 v[0:3], v[216:219], v[184:187], v[0:3]
	v_mfma_f32_16x16x32_bf16 v[28:31], v[212:215], v[164:167], v[28:31]
	v_mfma_f32_16x16x32_bf16 v[24:27], v[220:223], v[164:167], v[24:27]
	v_mfma_f32_16x16x32_bf16 v[20:23], v[212:215], v[172:175], v[20:23]
	v_mfma_f32_16x16x32_bf16 v[16:19], v[220:223], v[172:175], v[16:19]
	v_mfma_f32_16x16x32_bf16 v[12:15], v[212:215], v[180:183], v[12:15]
	v_mfma_f32_16x16x32_bf16 v[8:11], v[220:223], v[180:183], v[8:11]
	v_mfma_f32_16x16x32_bf16 v[4:7], v[212:215], v[204:207], v[4:7]
	v_mfma_f32_16x16x32_bf16 v[0:3], v[220:223], v[204:207], v[0:3]
	s_setprio 0
	v_or_b32_e32 v143, 0x18000, v133
	v_add_u32_e32 v145, 0x18800, v133
	s_barrier
	v_add_u32_e32 v144, 0x18400, v133
	ds_read_b128 v[152:155], v143
	ds_read_b128 v[156:159], v144
	v_add_u32_e32 v146, 0x18c00, v133
	ds_read_b128 v[160:163], v145
	ds_read_b128 v[164:167], v146
	s_mov_b32 m0, s27
	v_lshl_add_u64 v[148:149], v[188:189], 0, s[76:77]
	ds_read_b128 v[168:171], v132 offset:32768
	ds_read_b128 v[172:175], v132 offset:33792
	ds_read_b128 v[176:179], v132 offset:34816
	ds_read_b128 v[180:183], v132 offset:35840
	ds_read_b128 v[184:187], v132 offset:36864
	ds_read_b128 v[204:207], v132 offset:37888
	ds_read_b128 v[208:211], v132 offset:38912
	ds_read_b128 v[212:215], v132 offset:39936
	global_load_lds_dwordx4 v[148:149], off
	v_lshl_add_u64 v[148:149], v[188:189], 0, s[46:47]
	s_mov_b32 m0, s44
	s_nop 0
	global_load_lds_dwordx4 v[148:149], off
	s_waitcnt lgkmcnt(8)
	s_barrier
	s_waitcnt lgkmcnt(0)
	s_setprio 1
	s_waitcnt lgkmcnt(0)
	v_mfma_f32_16x16x32_bf16 v[124:127], v[152:155], v[168:171], v[124:127]
	v_mfma_f32_16x16x32_bf16 v[120:123], v[160:163], v[168:171], v[120:123]
	v_mfma_f32_16x16x32_bf16 v[116:119], v[152:155], v[176:179], v[116:119]
	v_mfma_f32_16x16x32_bf16 v[112:115], v[160:163], v[176:179], v[112:115]
	v_mfma_f32_16x16x32_bf16 v[108:111], v[152:155], v[184:187], v[108:111]
	v_mfma_f32_16x16x32_bf16 v[104:107], v[160:163], v[184:187], v[104:107]
	v_mfma_f32_16x16x32_bf16 v[100:103], v[152:155], v[208:211], v[100:103]
	v_mfma_f32_16x16x32_bf16 v[96:99], v[160:163], v[208:211], v[96:99]
	v_mfma_f32_16x16x32_bf16 v[124:127], v[156:159], v[172:175], v[124:127]
	v_mfma_f32_16x16x32_bf16 v[120:123], v[164:167], v[172:175], v[120:123]
	v_mfma_f32_16x16x32_bf16 v[116:119], v[156:159], v[180:183], v[116:119]
	v_mfma_f32_16x16x32_bf16 v[112:115], v[164:167], v[180:183], v[112:115]
	v_mfma_f32_16x16x32_bf16 v[108:111], v[156:159], v[204:207], v[108:111]
	v_mfma_f32_16x16x32_bf16 v[104:107], v[164:167], v[204:207], v[104:107]
	v_mfma_f32_16x16x32_bf16 v[100:103], v[156:159], v[212:215], v[100:103]
	v_mfma_f32_16x16x32_bf16 v[96:99], v[164:167], v[212:215], v[96:99]
	s_setprio 0
	s_barrier
	s_mov_b32 m0, s45
	v_or_b32_e32 v147, 0x1c000, v133
	v_add_u32_e32 v149, 0x1c800, v133
	v_lshl_add_u64 v[232:233], v[190:191], 0, s[56:57]
	v_add_u32_e32 v148, 0x1c400, v133
	ds_read_b128 v[216:219], v147
	ds_read_b128 v[220:223], v148
	v_add_u32_e32 v150, 0x1cc00, v133
	ds_read_b128 v[224:227], v149
	ds_read_b128 v[228:231], v150
	global_load_lds_dwordx4 v[232:233], off
	v_lshl_add_u64 v[232:233], v[190:191], 0, s[68:69]
	s_mov_b32 m0, s54
	s_nop 0
	global_load_lds_dwordx4 v[232:233], off
	s_barrier
	s_waitcnt lgkmcnt(0)
	s_setprio 1
	s_waitcnt lgkmcnt(0)
	v_mfma_f32_16x16x32_bf16 v[92:95], v[216:219], v[168:171], v[92:95]
	v_mfma_f32_16x16x32_bf16 v[88:91], v[224:227], v[168:171], v[88:91]
	v_mfma_f32_16x16x32_bf16 v[84:87], v[216:219], v[176:179], v[84:87]
	v_mfma_f32_16x16x32_bf16 v[80:83], v[224:227], v[176:179], v[80:83]
	v_mfma_f32_16x16x32_bf16 v[76:79], v[216:219], v[184:187], v[76:79]
	v_mfma_f32_16x16x32_bf16 v[72:75], v[224:227], v[184:187], v[72:75]
	v_mfma_f32_16x16x32_bf16 v[68:71], v[216:219], v[208:211], v[68:71]
	v_mfma_f32_16x16x32_bf16 v[64:67], v[224:227], v[208:211], v[64:67]
	v_mfma_f32_16x16x32_bf16 v[92:95], v[220:223], v[172:175], v[92:95]
	v_mfma_f32_16x16x32_bf16 v[88:91], v[228:231], v[172:175], v[88:91]
	v_mfma_f32_16x16x32_bf16 v[84:87], v[220:223], v[180:183], v[84:87]
	v_mfma_f32_16x16x32_bf16 v[80:83], v[228:231], v[180:183], v[80:83]
	v_mfma_f32_16x16x32_bf16 v[76:79], v[220:223], v[204:207], v[76:79]
	v_mfma_f32_16x16x32_bf16 v[72:75], v[228:231], v[204:207], v[72:75]
	v_mfma_f32_16x16x32_bf16 v[68:71], v[220:223], v[212:215], v[68:71]
	v_mfma_f32_16x16x32_bf16 v[64:67], v[228:231], v[212:215], v[64:67]
	s_setprio 0
	s_mov_b32 m0, s55
	v_lshl_add_u64 v[232:233], v[188:189], 0, s[56:57]
	s_barrier
	ds_read_b128 v[168:171], v132 offset:49152
	ds_read_b128 v[172:175], v132 offset:50176
	ds_read_b128 v[176:179], v132 offset:51200
	ds_read_b128 v[180:183], v132 offset:52224
	ds_read_b128 v[184:187], v132 offset:53248
	ds_read_b128 v[204:207], v132 offset:54272
	ds_read_b128 v[208:211], v132 offset:55296
	ds_read_b128 v[212:215], v132 offset:56320
	global_load_lds_dwordx4 v[232:233], off
	v_lshl_add_u64 v[188:189], v[188:189], 0, s[68:69]
	s_mov_b32 m0, s70
	s_nop 0
	global_load_lds_dwordx4 v[188:189], off
	s_barrier
; #define LDA8(dst, b, h)                                                                                               \
;   _Pragma("unroll") for (int m = 0; m < 4; ++m) _Pragma("unroll") for (int k = 0; k < 2; ++k)                         \
;     dst[m][k] = *(const bf16x8*)(SA8(b, h) + la + m * 2048 + k * 1024)
; #define LDB8(dst, b, h)                                                                                               \
;   _Pragma("unroll") for (int n = 0; n < 2; ++n) _Pragma("unroll") for (int k = 0; k < 2; ++k)                         \
;     dst[n][k] = *(const bf16x8*)(SB8(b, h) + lb + n * 2048 + k * 1024)
; #define WAITV8(n) asm volatile("s_waitcnt vmcnt(" #n ")" ::: "memory")
; #define WAITL8(n) asm volatile("s_waitcnt lgkmcnt(" #n ")" ::: "memory")
; #define BAR8 __builtin_amdgcn_s_barrier()
; #define SCHED8 __builtin_amdgcn_sched_barrier(0)
; template <class Epi>
; DEV void gemm_tile8(char* shm, const u16* __restrict__ A, const u16* __restrict__ Bt, int K, int brow, int bcol, Epi& epi) {
;     ...
;     BAR8; WAITL8(0); MMA8(1, 0, At, B0); BAR8; SCHED8;
;     STAGE8(SB8(1, 1), Bt, bcol + HALF, t + 3);
;     WAITV8(6); BAR8; MMA8(1, 1, At, B1); BAR8;
;   }
;   { LDB8(B0, 0, 0); LDA8(At, 0, 0); STAGE8(SA8(1, 1), A, brow + HALF, nt - 1);
;     BAR8; WAITL8(0); MMA8(0, 0, At, B0); BAR8;
;     LDB8(B1, 0, 1); BAR8; WAITL8(0); MMA8(0, 1, At, B1); BAR8;
	s_waitcnt lgkmcnt(0)
	s_setprio 1
	s_waitcnt lgkmcnt(0)
	v_mfma_f32_16x16x32_bf16 v[60:63], v[152:155], v[168:171], v[60:63]
	v_mfma_f32_16x16x32_bf16 v[56:59], v[160:163], v[168:171], v[56:59]
	v_mfma_f32_16x16x32_bf16 v[52:55], v[152:155], v[176:179], v[52:55]
	v_mfma_f32_16x16x32_bf16 v[48:51], v[160:163], v[176:179], v[48:51]
	v_mfma_f32_16x16x32_bf16 v[44:47], v[152:155], v[184:187], v[44:47]
	v_mfma_f32_16x16x32_bf16 v[40:43], v[160:163], v[184:187], v[40:43]
	v_mfma_f32_16x16x32_bf16 v[36:39], v[152:155], v[208:211], v[36:39]
	v_mfma_f32_16x16x32_bf16 v[32:35], v[160:163], v[208:211], v[32:35]
	v_mfma_f32_16x16x32_bf16 v[60:63], v[156:159], v[172:175], v[60:63]
	v_mfma_f32_16x16x32_bf16 v[56:59], v[164:167], v[172:175], v[56:59]
	v_mfma_f32_16x16x32_bf16 v[52:55], v[156:159], v[180:183], v[52:55]
	v_mfma_f32_16x16x32_bf16 v[48:51], v[164:167], v[180:183], v[48:51]
	v_mfma_f32_16x16x32_bf16 v[44:47], v[156:159], v[204:207], v[44:47]
	v_mfma_f32_16x16x32_bf16 v[40:43], v[164:167], v[204:207], v[40:43]
	v_mfma_f32_16x16x32_bf16 v[36:39], v[156:159], v[212:215], v[36:39]
	v_mfma_f32_16x16x32_bf16 v[32:35], v[164:167], v[212:215], v[32:35]
	s_setprio 0
	s_barrier
	s_mov_b64 s[92:93], 0x40180
	s_mov_b32 m0, s71
	v_lshl_add_u64 v[152:153], v[190:191], 0, s[92:93]
	s_mov_b64 s[92:93], 0x60180
	global_load_lds_dwordx4 v[152:153], off
	v_lshl_add_u64 v[152:153], v[190:191], 0, s[92:93]
	s_mov_b32 m0, s72
	s_nop 0
	global_load_lds_dwordx4 v[152:153], off
	s_waitcnt vmcnt(6)
	s_barrier
	s_setprio 1
	v_mfma_f32_16x16x32_bf16 v[28:31], v[216:219], v[168:171], v[28:31]
	v_mfma_f32_16x16x32_bf16 v[24:27], v[224:227], v[168:171], v[24:27]
	v_mfma_f32_16x16x32_bf16 v[20:23], v[216:219], v[176:179], v[20:23]
	v_mfma_f32_16x16x32_bf16 v[16:19], v[224:227], v[176:179], v[16:19]
	v_mfma_f32_16x16x32_bf16 v[12:15], v[216:219], v[184:187], v[12:15]
	v_mfma_f32_16x16x32_bf16 v[8:11], v[224:227], v[184:187], v[8:11]
	v_mfma_f32_16x16x32_bf16 v[4:7], v[216:219], v[208:211], v[4:7]
	v_mfma_f32_16x16x32_bf16 v[0:3], v[224:227], v[208:211], v[0:3]
	v_mfma_f32_16x16x32_bf16 v[28:31], v[220:223], v[172:175], v[28:31]
	v_mfma_f32_16x16x32_bf16 v[24:27], v[228:231], v[172:175], v[24:27]
	v_mfma_f32_16x16x32_bf16 v[20:23], v[220:223], v[180:183], v[20:23]
	v_mfma_f32_16x16x32_bf16 v[16:19], v[228:231], v[180:183], v[16:19]
	v_mfma_f32_16x16x32_bf16 v[12:15], v[220:223], v[204:207], v[12:15]
	v_mfma_f32_16x16x32_bf16 v[8:11], v[228:231], v[204:207], v[8:11]
	v_mfma_f32_16x16x32_bf16 v[4:7], v[220:223], v[212:215], v[4:7]
	v_mfma_f32_16x16x32_bf16 v[0:3], v[228:231], v[212:215], v[0:3]
	s_setprio 0
	s_add_i32 s73, s73, 2
	s_add_u32 s10, s10, 0x100
	s_addc_u32 s11, s11, 0
	s_add_u32 s6, s6, 0x100
	s_addc_u32 s7, s7, 0
	s_cmp_lt_u32 s73, 12
	s_barrier
	s_cbranch_scc1 .LBB0_907
	s_mov_b64 s[6:7], 0x780
	s_mov_b32 m0, s91
	v_lshl_add_u64 v[130:131], v[128:129], 0, s[6:7]
	s_mov_b64 s[6:7], 0x20780
	s_waitcnt vmcnt(0)
	ds_read_b128 v[152:155], v134
	ds_read_b128 v[156:159], v135
	ds_read_b128 v[160:163], v136
	ds_read_b128 v[134:137], v137
	ds_read_b128 v[164:167], v132
	ds_read_b128 v[168:171], v132 offset:1024
	ds_read_b128 v[172:175], v132 offset:2048
	ds_read_b128 v[176:179], v132 offset:3072
	ds_read_b128 v[180:183], v132 offset:4096
	ds_read_b128 v[184:187], v132 offset:5120
	ds_read_b128 v[204:207], v132 offset:6144
	ds_read_b128 v[208:211], v132 offset:7168
	global_load_lds_dwordx4 v[130:131], off
	v_lshl_add_u64 v[128:129], v[128:129], 0, s[6:7]
	s_mov_b32 m0, s90
	s_nop 0
	global_load_lds_dwordx4 v[128:129], off
	s_barrier
	s_waitcnt lgkmcnt(0)
	s_setprio 1
	s_waitcnt lgkmcnt(0)
	v_mfma_f32_16x16x32_bf16 v[124:127], v[152:155], v[164:167], v[124:127]
	v_mfma_f32_16x16x32_bf16 v[120:123], v[160:163], v[164:167], v[120:123]
	v_mfma_f32_16x16x32_bf16 v[116:119], v[152:155], v[172:175], v[116:119]
	v_mfma_f32_16x16x32_bf16 v[112:115], v[160:163], v[172:175], v[112:115]
	v_mfma_f32_16x16x32_bf16 v[108:111], v[152:155], v[180:183], v[108:111]
	v_mfma_f32_16x16x32_bf16 v[104:107], v[160:163], v[180:183], v[104:107]
	v_mfma_f32_16x16x32_bf16 v[100:103], v[152:155], v[204:207], v[100:103]
	v_mfma_f32_16x16x32_bf16 v[96:99], v[160:163], v[204:207], v[96:99]
	v_mfma_f32_16x16x32_bf16 v[124:127], v[156:159], v[168:171], v[124:127]
	v_mfma_f32_16x16x32_bf16 v[120:123], v[134:137], v[168:171], v[120:123]
	v_mfma_f32_16x16x32_bf16 v[116:119], v[156:159], v[176:179], v[116:119]
	v_mfma_f32_16x16x32_bf16 v[112:115], v[134:137], v[176:179], v[112:115]
	v_mfma_f32_16x16x32_bf16 v[108:111], v[156:159], v[184:187], v[108:111]
	v_mfma_f32_16x16x32_bf16 v[104:107], v[134:137], v[184:187], v[104:107]
	v_mfma_f32_16x16x32_bf16 v[100:103], v[156:159], v[208:211], v[100:103]
	v_mfma_f32_16x16x32_bf16 v[96:99], v[134:137], v[208:211], v[96:99]
	s_setprio 0
	s_barrier
	s_waitcnt vmcnt(0)
	ds_read_b128 v[128:131], v138
	ds_read_b128 v[212:215], v139
	ds_read_b128 v[216:219], v140
	ds_read_b128 v[220:223], v142
	s_barrier
	s_waitcnt lgkmcnt(0)
	s_setprio 1
	s_waitcnt lgkmcnt(3)
	v_mfma_f32_16x16x32_bf16 v[92:95], v[128:131], v[164:167], v[92:95]
	s_waitcnt lgkmcnt(1)
	v_mfma_f32_16x16x32_bf16 v[88:91], v[216:219], v[164:167], v[88:91]
	v_mfma_f32_16x16x32_bf16 v[84:87], v[128:131], v[172:175], v[84:87]
	v_mfma_f32_16x16x32_bf16 v[80:83], v[216:219], v[172:175], v[80:83]
	v_mfma_f32_16x16x32_bf16 v[76:79], v[128:131], v[180:183], v[76:79]
	v_mfma_f32_16x16x32_bf16 v[72:75], v[216:219], v[180:183], v[72:75]
	v_mfma_f32_16x16x32_bf16 v[68:71], v[128:131], v[204:207], v[68:71]
	v_mfma_f32_16x16x32_bf16 v[64:67], v[216:219], v[204:207], v[64:67]
	v_mfma_f32_16x16x32_bf16 v[224:227], v[212:215], v[168:171], v[92:95]
	s_waitcnt lgkmcnt(0)
	v_mfma_f32_16x16x32_bf16 v[164:167], v[220:223], v[168:171], v[88:91]
	v_mfma_f32_16x16x32_bf16 v[168:171], v[212:215], v[176:179], v[84:87]
	v_mfma_f32_16x16x32_bf16 v[172:175], v[220:223], v[176:179], v[80:83]
	v_mfma_f32_16x16x32_bf16 v[176:179], v[212:215], v[184:187], v[76:79]
	v_mfma_f32_16x16x32_bf16 v[180:183], v[220:223], v[184:187], v[72:75]
	v_mfma_f32_16x16x32_bf16 v[184:187], v[212:215], v[208:211], v[68:71]
	v_mfma_f32_16x16x32_bf16 v[204:207], v[220:223], v[208:211], v[64:67]
	s_setprio 0
	s_barrier
; #define LDA8(dst, b, h)                                                                                               \
;   _Pragma("unroll") for (int m = 0; m < 4; ++m) _Pragma("unroll") for (int k = 0; k < 2; ++k)                         \
;     dst[m][k] = *(const bf16x8*)(SA8(b, h) + la + m * 2048 + k * 1024)
; #define LDB8(dst, b, h)                                                                                               \
;   _Pragma("unroll") for (int n = 0; n < 2; ++n) _Pragma("unroll") for (int k = 0; k < 2; ++k)                         \
;     dst[n][k] = *(const bf16x8*)(SB8(b, h) + lb + n * 2048 + k * 1024)
; #define WAITV8(n) asm volatile("s_waitcnt vmcnt(" #n ")" ::: "memory")
; #define WAITL8(n) asm volatile("s_waitcnt lgkmcnt(" #n ")" ::: "memory")
; #define BAR8 __builtin_amdgcn_s_barrier()
; template <class Epi>
; DEV void gemm_tile8(char* shm, const u16* __restrict__ A, const u16* __restrict__ Bt, int K, int brow, int bcol, Epi& epi) {
;     ...
;     LDA8(At, 0, 1); WAITV8(4); BAR8; WAITL8(0); MMA8(1, 0, At, B0); MMA8(1, 1, At, B1); BAR8; }
;   { LDB8(B0, 1, 0); LDA8(At, 1, 0); WAITV8(2); BAR8; WAITL8(0); MMA8(0, 0, At, B0); BAR8;
	s_nop 0
	ds_read_b128 v[64:67], v132 offset:16384
	ds_read_b128 v[68:71], v132 offset:17408
	ds_read_b128 v[72:75], v132 offset:18432
	ds_read_b128 v[76:79], v132 offset:19456
	ds_read_b128 v[80:83], v132 offset:20480
	ds_read_b128 v[84:87], v132 offset:21504
	ds_read_b128 v[88:91], v132 offset:22528
	ds_read_b128 v[92:95], v132 offset:23552
	s_waitcnt vmcnt(4)
	s_barrier
	s_waitcnt lgkmcnt(0)
	s_setprio 1
	s_waitcnt lgkmcnt(7)
	v_mfma_f32_16x16x32_bf16 v[60:63], v[152:155], v[64:67], v[60:63]
	v_mfma_f32_16x16x32_bf16 v[56:59], v[160:163], v[64:67], v[56:59]
	s_waitcnt lgkmcnt(5)
	v_mfma_f32_16x16x32_bf16 v[52:55], v[152:155], v[72:75], v[52:55]
	v_mfma_f32_16x16x32_bf16 v[48:51], v[160:163], v[72:75], v[48:51]
	s_waitcnt lgkmcnt(3)
	v_mfma_f32_16x16x32_bf16 v[44:47], v[152:155], v[80:83], v[44:47]
	v_mfma_f32_16x16x32_bf16 v[40:43], v[160:163], v[80:83], v[40:43]
	s_waitcnt lgkmcnt(1)
	v_mfma_f32_16x16x32_bf16 v[36:39], v[152:155], v[88:91], v[36:39]
	v_mfma_f32_16x16x32_bf16 v[32:35], v[160:163], v[88:91], v[32:35]
	v_mfma_f32_16x16x32_bf16 v[60:63], v[156:159], v[68:71], v[60:63]
	v_mfma_f32_16x16x32_bf16 v[56:59], v[134:137], v[68:71], v[56:59]
	v_mfma_f32_16x16x32_bf16 v[52:55], v[156:159], v[76:79], v[52:55]
	v_mfma_f32_16x16x32_bf16 v[48:51], v[134:137], v[76:79], v[48:51]
	v_mfma_f32_16x16x32_bf16 v[44:47], v[156:159], v[84:87], v[44:47]
	v_mfma_f32_16x16x32_bf16 v[40:43], v[134:137], v[84:87], v[40:43]
	s_waitcnt lgkmcnt(0)
	v_mfma_f32_16x16x32_bf16 v[36:39], v[156:159], v[92:95], v[36:39]
	v_mfma_f32_16x16x32_bf16 v[32:35], v[134:137], v[92:95], v[32:35]
	s_setprio 0
	s_setprio 1
	v_mfma_f32_16x16x32_bf16 v[28:31], v[128:131], v[64:67], v[28:31]
	v_mfma_f32_16x16x32_bf16 v[24:27], v[216:219], v[64:67], v[24:27]
	v_mfma_f32_16x16x32_bf16 v[20:23], v[128:131], v[72:75], v[20:23]
	v_mfma_f32_16x16x32_bf16 v[16:19], v[216:219], v[72:75], v[16:19]
	v_mfma_f32_16x16x32_bf16 v[12:15], v[128:131], v[80:83], v[12:15]
	v_mfma_f32_16x16x32_bf16 v[8:11], v[216:219], v[80:83], v[8:11]
	v_mfma_f32_16x16x32_bf16 v[4:7], v[128:131], v[88:91], v[4:7]
	v_mfma_f32_16x16x32_bf16 v[0:3], v[216:219], v[88:91], v[0:3]
	v_mfma_f32_16x16x32_bf16 v[134:137], v[212:215], v[68:71], v[28:31]
	v_mfma_f32_16x16x32_bf16 v[152:155], v[220:223], v[68:71], v[24:27]
	v_mfma_f32_16x16x32_bf16 v[156:159], v[212:215], v[76:79], v[20:23]
	v_mfma_f32_16x16x32_bf16 v[160:163], v[220:223], v[76:79], v[16:19]
	v_mfma_f32_16x16x32_bf16 v[208:211], v[212:215], v[84:87], v[12:15]
	v_mfma_f32_16x16x32_bf16 v[228:231], v[220:223], v[84:87], v[8:11]
	v_mfma_f32_16x16x32_bf16 v[128:131], v[212:215], v[92:95], v[4:7]
	v_mfma_f32_16x16x32_bf16 v[212:215], v[220:223], v[92:95], v[0:3]
	s_setprio 0
	s_barrier
	ds_read_b128 v[24:27], v143
	ds_read_b128 v[28:31], v144
	ds_read_b128 v[142:145], v145
	ds_read_b128 v[216:219], v146
	ds_read_b128 v[0:3], v132 offset:32768
	ds_read_b128 v[4:7], v132 offset:33792
	ds_read_b128 v[8:11], v132 offset:34816
	ds_read_b128 v[12:15], v132 offset:35840
	ds_read_b128 v[16:19], v132 offset:36864
	ds_read_b128 v[20:23], v132 offset:37888
	ds_read_b128 v[220:223], v132 offset:38912
	ds_read_b128 v[232:235], v132 offset:39936
	s_waitcnt vmcnt(2)
	s_barrier
	s_waitcnt lgkmcnt(0)
	s_setprio 1
	s_waitcnt lgkmcnt(7)
	v_mfma_f32_16x16x32_bf16 v[64:67], v[24:27], v[0:3], v[124:127]
	s_waitcnt lgkmcnt(6)
	v_mfma_f32_16x16x32_bf16 v[72:75], v[28:31], v[4:7], v[64:67]
	v_mfma_f32_16x16x32_bf16 v[64:67], v[142:145], v[0:3], v[120:123]
	s_waitcnt lgkmcnt(5)
	v_mfma_f32_16x16x32_bf16 v[68:71], v[24:27], v[8:11], v[116:119]
	v_mfma_f32_16x16x32_bf16 v[76:79], v[142:145], v[8:11], v[112:115]
	s_waitcnt lgkmcnt(3)
	v_mfma_f32_16x16x32_bf16 v[80:83], v[24:27], v[16:19], v[108:111]
	v_mfma_f32_16x16x32_bf16 v[84:87], v[142:145], v[16:19], v[104:107]
	s_waitcnt lgkmcnt(1)
	v_mfma_f32_16x16x32_bf16 v[88:91], v[24:27], v[220:223], v[100:103]
	v_mfma_f32_16x16x32_bf16 v[92:95], v[142:145], v[220:223], v[96:99]
	v_mfma_f32_16x16x32_bf16 v[64:67], v[216:219], v[4:7], v[64:67]
	v_mfma_f32_16x16x32_bf16 v[68:71], v[28:31], v[12:15], v[68:71]
	v_mfma_f32_16x16x32_bf16 v[76:79], v[216:219], v[12:15], v[76:79]
	v_mfma_f32_16x16x32_bf16 v[80:83], v[28:31], v[20:23], v[80:83]
	v_mfma_f32_16x16x32_bf16 v[84:87], v[216:219], v[20:23], v[84:87]
	s_waitcnt lgkmcnt(0)
	v_mfma_f32_16x16x32_bf16 v[88:91], v[28:31], v[232:235], v[88:91]
	v_mfma_f32_16x16x32_bf16 v[92:95], v[216:219], v[232:235], v[92:95]
	s_setprio 0
	s_barrier
; #define LDA8(dst, b, h)                                                                                               \
;   _Pragma("unroll") for (int m = 0; m < 4; ++m) _Pragma("unroll") for (int k = 0; k < 2; ++k)                         \
;     dst[m][k] = *(const bf16x8*)(SA8(b, h) + la + m * 2048 + k * 1024)
; #define LDB8(dst, b, h)                                                                                               \
;   _Pragma("unroll") for (int n = 0; n < 2; ++n) _Pragma("unroll") for (int k = 0; k < 2; ++k)                         \
;     dst[n][k] = *(const bf16x8*)(SB8(b, h) + lb + n * 2048 + k * 1024)
; #define WAITV8(n) asm volatile("s_waitcnt vmcnt(" #n ")" ::: "memory")
; #define WAITL8(n) asm volatile("s_waitcnt lgkmcnt(" #n ")" ::: "memory")
; #define BAR8 __builtin_amdgcn_s_barrier()
; template <class Epi>
; DEV void gemm_tile8(char* shm, const u16* __restrict__ A, const u16* __restrict__ Bt, int K, int brow, int bcol, Epi& epi) {
;     ...
;     LDB8(B1, 1, 1); WAITV8(0); BAR8; WAITL8(0); MMA8(0, 1, At, B1); BAR8;
;     LDA8(At, 1, 1); BAR8; WAITL8(0); MMA8(1, 0, At, B0); MMA8(1, 1, At, B1); BAR8; }
;   if (wrs == 0) BAR8;
	ds_read_b128 v[236:239], v147
	ds_read_b128 v[240:243], v148
	ds_read_b128 v[146:149], v149
	ds_read_b128 v[244:247], v150
	s_waitcnt vmcnt(0)
	s_barrier
	s_waitcnt lgkmcnt(0)
	s_setprio 1
	s_waitcnt lgkmcnt(3)
	v_mfma_f32_16x16x32_bf16 v[96:99], v[236:239], v[0:3], v[224:227]
	s_waitcnt lgkmcnt(1)
	v_mfma_f32_16x16x32_bf16 v[0:3], v[146:149], v[0:3], v[164:167]
	v_mfma_f32_16x16x32_bf16 v[104:107], v[240:243], v[4:7], v[96:99]
	s_waitcnt lgkmcnt(0)
	v_mfma_f32_16x16x32_bf16 v[96:99], v[244:247], v[4:7], v[0:3]
	v_mfma_f32_16x16x32_bf16 v[0:3], v[236:239], v[8:11], v[168:171]
	v_mfma_f32_16x16x32_bf16 v[100:103], v[240:243], v[12:15], v[0:3]
	v_mfma_f32_16x16x32_bf16 v[0:3], v[146:149], v[8:11], v[172:175]
	v_mfma_f32_16x16x32_bf16 v[108:111], v[244:247], v[12:15], v[0:3]
	v_mfma_f32_16x16x32_bf16 v[0:3], v[236:239], v[16:19], v[176:179]
	v_mfma_f32_16x16x32_bf16 v[112:115], v[240:243], v[20:23], v[0:3]
	v_mfma_f32_16x16x32_bf16 v[0:3], v[146:149], v[16:19], v[180:183]
	v_mfma_f32_16x16x32_bf16 v[116:119], v[244:247], v[20:23], v[0:3]
	v_mfma_f32_16x16x32_bf16 v[0:3], v[236:239], v[220:223], v[184:187]
	v_mfma_f32_16x16x32_bf16 v[120:123], v[240:243], v[232:235], v[0:3]
	v_mfma_f32_16x16x32_bf16 v[0:3], v[146:149], v[220:223], v[204:207]
	v_mfma_f32_16x16x32_bf16 v[124:127], v[244:247], v[232:235], v[0:3]
	s_setprio 0
	s_barrier
	ds_read_b128 v[164:167], v132 offset:49152
	ds_read_b128 v[168:171], v132 offset:50176
	ds_read_b128 v[172:175], v132 offset:51200
	ds_read_b128 v[176:179], v132 offset:52224
	ds_read_b128 v[180:183], v132 offset:53248
	ds_read_b128 v[184:187], v132 offset:54272
	ds_read_b128 v[204:207], v132 offset:55296
	ds_read_b128 v[220:223], v132 offset:56320
	s_barrier
	s_waitcnt lgkmcnt(0)
	s_setprio 1
	s_waitcnt lgkmcnt(7)
	v_mfma_f32_16x16x32_bf16 v[0:3], v[24:27], v[164:167], v[60:63]
	s_waitcnt lgkmcnt(5)
	v_mfma_f32_16x16x32_bf16 v[8:11], v[24:27], v[172:175], v[52:55]
	s_waitcnt lgkmcnt(3)
	v_mfma_f32_16x16x32_bf16 v[16:19], v[24:27], v[180:183], v[44:47]
	s_waitcnt lgkmcnt(1)
	v_mfma_f32_16x16x32_bf16 v[24:27], v[24:27], v[204:207], v[36:39]
	v_mfma_f32_16x16x32_bf16 v[0:3], v[28:31], v[168:171], v[0:3]
	v_mfma_f32_16x16x32_bf16 v[4:7], v[142:145], v[164:167], v[56:59]
	v_mfma_f32_16x16x32_bf16 v[8:11], v[28:31], v[176:179], v[8:11]
	v_mfma_f32_16x16x32_bf16 v[12:15], v[142:145], v[172:175], v[48:51]
	v_mfma_f32_16x16x32_bf16 v[16:19], v[28:31], v[184:187], v[16:19]
	v_mfma_f32_16x16x32_bf16 v[20:23], v[142:145], v[180:183], v[40:43]
	s_waitcnt lgkmcnt(0)
	v_mfma_f32_16x16x32_bf16 v[24:27], v[28:31], v[220:223], v[24:27]
	v_mfma_f32_16x16x32_bf16 v[28:31], v[142:145], v[204:207], v[32:35]
	v_mfma_f32_16x16x32_bf16 v[4:7], v[216:219], v[168:171], v[4:7]
	v_mfma_f32_16x16x32_bf16 v[12:15], v[216:219], v[176:179], v[12:15]
	v_mfma_f32_16x16x32_bf16 v[20:23], v[216:219], v[184:187], v[20:23]
	v_mfma_f32_16x16x32_bf16 v[28:31], v[216:219], v[220:223], v[28:31]
	s_setprio 0
	s_setprio 1
	v_mfma_f32_16x16x32_bf16 v[32:35], v[236:239], v[164:167], v[134:137]
	v_mfma_f32_16x16x32_bf16 v[36:39], v[146:149], v[164:167], v[152:155]
	v_mfma_f32_16x16x32_bf16 v[40:43], v[236:239], v[172:175], v[156:159]
	v_mfma_f32_16x16x32_bf16 v[44:47], v[146:149], v[172:175], v[160:163]
	v_mfma_f32_16x16x32_bf16 v[48:51], v[236:239], v[180:183], v[208:211]
	v_mfma_f32_16x16x32_bf16 v[52:55], v[146:149], v[180:183], v[228:231]
	v_mfma_f32_16x16x32_bf16 v[56:59], v[236:239], v[204:207], v[128:131]
	v_mfma_f32_16x16x32_bf16 v[60:63], v[146:149], v[204:207], v[212:215]
	v_mfma_f32_16x16x32_bf16 v[32:35], v[240:243], v[168:171], v[32:35]
	v_mfma_f32_16x16x32_bf16 v[36:39], v[244:247], v[168:171], v[36:39]
	v_mfma_f32_16x16x32_bf16 v[40:43], v[240:243], v[176:179], v[40:43]
	v_mfma_f32_16x16x32_bf16 v[44:47], v[244:247], v[176:179], v[44:47]
	v_mfma_f32_16x16x32_bf16 v[48:51], v[240:243], v[184:187], v[48:51]
	v_mfma_f32_16x16x32_bf16 v[52:55], v[244:247], v[184:187], v[52:55]
	v_mfma_f32_16x16x32_bf16 v[56:59], v[240:243], v[220:223], v[56:59]
	v_mfma_f32_16x16x32_bf16 v[60:63], v[244:247], v[220:223], v[60:63]
	s_setprio 0
	s_cmp_lg_u32 s12, 0
	s_barrier
	s_cbranch_scc1 .LBB0_910
	s_barrier
